# a+b plus: loader tail compacted (s_setprio 1 before one combined s_waitcnt vmcnt(8) lgkmcnt(0), then barrier); size-neutral
# speedup vs baseline: 1.0031x; 1.0031x over previous
; #define PG8_STAGE(bufoff, gbase, voff) do { const char* _gb = (const char*)(gbase); asm volatile("" : "+s"(_gb)); _Pragma("unroll") for (int _i = 0; _i < 2; ++_i) { asm volatile("" : "+v"((voff)[_i])); \
;         __builtin_amdgcn_global_load_lds((const unsigned*)(_gb + (voff)[_i]), (PG8_LAS unsigned*)(lds + (bufoff) + ldsw + _i * 8192), 16, 0, 0); } } while (0)
; #define PG8_LDA(dst, b, h) do { _Pragma("unroll") for (int m = 0; m < 4; ++m) _Pragma("unroll") for (int k = 0; k < 2; ++k) dst[m][k] = *(const PG8_LAS bf16x8*)(lds + PG8_SA(b, h) + aoff + m * 2048 + k * 1024); } while (0)
; #define PG8_LDB(dst, b, h) do { _Pragma("unroll") for (int n = 0; n < 2; ++n) _Pragma("unroll") for (int k = 0; k < 2; ++k) dst[n][k] = *(const PG8_LAS bf16x8*)(lds + PG8_SB(b, h) + boff + n * 2048 + k * 1024); } while (0)
; #define PG8_WAIT_V(n) asm volatile("s_waitcnt vmcnt(" #n ")" ::: "memory")
; #define PG8_WAIT_L(n) asm volatile("s_waitcnt lgkmcnt(" #n ")" ::: "memory")
; #define PG8_BAR __builtin_amdgcn_s_barrier()
; #define PG8_SCHED __builtin_amdgcn_sched_barrier(0)
; #define PG8_STAGE(bufoff, gbase, voff) do { const char* _gb = (const char*)(gbase); asm volatile("" : "+s"(_gb)); _Pragma("unroll") for (int _i = 0; _i < 2; ++_i) { asm volatile("" : "+v"((voff)[_i])); \
;         __builtin_amdgcn_global_load_lds((const unsigned*)(_gb + (voff)[_i]), (PG8_LAS unsigned*)(lds + (bufoff) + ldsw + _i * 8192), 16, 0, 0); } } while (0)
; #define PG8_LDA(dst, b, h) do { _Pragma("unroll") for (int m = 0; m < 4; ++m) _Pragma("unroll") for (int k = 0; k < 2; ++k) dst[m][k] = *(const PG8_LAS bf16x8*)(lds + PG8_SA(b, h) + aoff + m * 2048 + k * 1024); } while (0)
; #define PG8_WAIT_V(n) asm volatile("s_waitcnt vmcnt(" #n ")" ::: "memory")
; template <class Epi, class Sched, bool ALIGN_EPI = false, bool SP2 = false>
; __device__ __forceinline__ void gemm_phase(PG8_LAS unsigned char* lds, const Gemm g, const Sched& S, const Epi& E) {
;     ...
;             PG8_LDB(B0, 0, 0); PG8_LDB(B1, 0, 1); PG8_SCHED; PG8_LDA(At, 0, 0); PG8_STAGE(PG8_SA(1, 1), a1 + hstep, voffA);
;             PG8_WAIT_V(8); PG8_WAIT_L(0); PG8_BAR; PG8_MMA2(0); PG8_BAR; PG8_SCHED;
;             PG8_LDA(At, 0, 1); PG8_STAGE(PG8_SB(0, 0), b2, voffB); PG8_STAGE(PG8_SB(0, 1), b2 + hstep, voffB); PG8_STAGE(PG8_SA(0, 0), a2, voffA);
;             PG8_WAIT_V(8); PG8_WAIT_L(0); PG8_BAR; PG8_MMA2(1); PG8_BAR; PG8_SCHED;
.LBB0_313:
	ds_read_b128 v[136:139], v150
	ds_read_b128 v[140:143], v150 offset:1024
	ds_read_b128 v[154:157], v150 offset:2048
	ds_read_b128 v[158:161], v150 offset:3072
	ds_read_b128 v[162:165], v151
	ds_read_b128 v[166:169], v151 offset:1024
	ds_read_b128 v[170:173], v151 offset:2048
	ds_read_b128 v[174:177], v151 offset:3072
	s_add_u32 s14, s8, 0x100
	s_addc_u32 s15, s9, 0
	s_cmp_eq_u32 s43, 60
	s_cselect_b32 s24, s13, s14
	s_cselect_b32 s25, s11, s15
	s_cselect_b32 s16, s36, s37
	s_cselect_b32 s17, s33, s42
	s_add_u32 s2, s24, 0x80
	s_addc_u32 s3, s25, 0
	s_add_u32 s8, s8, 0x100080
	s_addc_u32 s9, s9, 0
	s_add_i32 m0, s63, 0xc000
	ds_read_b128 v[178:181], v152
	ds_read_b128 v[182:185], v152 offset:1024
	ds_read_b128 v[186:189], v152 offset:2048
	ds_read_b128 v[190:193], v152 offset:3072
	ds_read_b128 v[194:197], v152 offset:4096
	ds_read_b128 v[198:201], v152 offset:5120
	ds_read_b128 v[202:205], v152 offset:6144
	ds_read_b128 v[206:209], v152 offset:7168
	s_nop 0
	global_load_lds_dwordx4 v1, s[8:9]
	s_add_i32 m0, s63, 0xe000
	s_nop 0
	global_load_lds_dwordx4 v145, s[8:9]
	s_nop 0
	s_nop 0
	s_setprio 1
	s_waitcnt vmcnt(8) lgkmcnt(0)
	s_barrier
	v_mfma_f32_16x16x32_bf16 v[126:129], v[136:139], v[178:181], v[126:129]
	v_mfma_f32_16x16x32_bf16 v[122:125], v[154:157], v[178:181], v[122:125]
	v_mfma_f32_16x16x32_bf16 v[110:113], v[136:139], v[186:189], v[110:113]
	v_mfma_f32_16x16x32_bf16 v[106:109], v[154:157], v[186:189], v[106:109]
	v_mfma_f32_16x16x32_bf16 v[94:97], v[136:139], v[194:197], v[94:97]
	v_mfma_f32_16x16x32_bf16 v[90:93], v[154:157], v[194:197], v[90:93]
	v_mfma_f32_16x16x32_bf16 v[78:81], v[136:139], v[202:205], v[78:81]
	v_mfma_f32_16x16x32_bf16 v[74:77], v[154:157], v[202:205], v[74:77]
	v_mfma_f32_16x16x32_bf16 v[118:121], v[162:165], v[178:181], v[118:121]
	v_mfma_f32_16x16x32_bf16 v[114:117], v[170:173], v[178:181], v[114:117]
	v_mfma_f32_16x16x32_bf16 v[102:105], v[162:165], v[186:189], v[102:105]
	v_mfma_f32_16x16x32_bf16 v[98:101], v[170:173], v[186:189], v[98:101]
	v_mfma_f32_16x16x32_bf16 v[86:89], v[162:165], v[194:197], v[86:89]
	v_mfma_f32_16x16x32_bf16 v[82:85], v[170:173], v[194:197], v[82:85]
	v_mfma_f32_16x16x32_bf16 v[70:73], v[162:165], v[202:205], v[70:73]
	v_mfma_f32_16x16x32_bf16 v[66:69], v[170:173], v[202:205], v[66:69]
	v_mfma_f32_16x16x32_bf16 v[126:129], v[140:143], v[182:185], v[126:129]
	v_mfma_f32_16x16x32_bf16 v[122:125], v[158:161], v[182:185], v[122:125]
	v_mfma_f32_16x16x32_bf16 v[110:113], v[140:143], v[190:193], v[110:113]
	v_mfma_f32_16x16x32_bf16 v[106:109], v[158:161], v[190:193], v[106:109]
	v_mfma_f32_16x16x32_bf16 v[94:97], v[140:143], v[198:201], v[94:97]
	v_mfma_f32_16x16x32_bf16 v[90:93], v[158:161], v[198:201], v[90:93]
	v_mfma_f32_16x16x32_bf16 v[78:81], v[140:143], v[206:209], v[78:81]
	v_mfma_f32_16x16x32_bf16 v[74:77], v[158:161], v[206:209], v[74:77]
	v_mfma_f32_16x16x32_bf16 v[118:121], v[166:169], v[182:185], v[118:121]
	v_mfma_f32_16x16x32_bf16 v[114:117], v[174:177], v[182:185], v[114:117]
	v_mfma_f32_16x16x32_bf16 v[102:105], v[166:169], v[190:193], v[102:105]
	v_mfma_f32_16x16x32_bf16 v[98:101], v[174:177], v[190:193], v[98:101]
	v_mfma_f32_16x16x32_bf16 v[86:89], v[166:169], v[198:201], v[86:89]
	v_mfma_f32_16x16x32_bf16 v[82:85], v[174:177], v[198:201], v[82:85]
	v_mfma_f32_16x16x32_bf16 v[70:73], v[166:169], v[206:209], v[70:73]
	v_mfma_f32_16x16x32_bf16 v[66:69], v[174:177], v[206:209], v[66:69]
	s_setprio 0
	s_barrier
	s_add_i32 s44, s95, s61
	s_mov_b64 s[8:9], s[16:17]
	s_mov_b32 m0, s44
	ds_read_b128 v[178:181], v152 offset:16384
	ds_read_b128 v[182:185], v152 offset:17408
	ds_read_b128 v[186:189], v152 offset:18432
	ds_read_b128 v[190:193], v152 offset:19456
	ds_read_b128 v[194:197], v152 offset:20480
	ds_read_b128 v[198:201], v152 offset:21504
	ds_read_b128 v[202:205], v152 offset:22528
	ds_read_b128 v[206:209], v152 offset:23552
	s_nop 0
	global_load_lds_dwordx4 v144, s[8:9]
	s_add_i32 m0, s44, 0x2000
	s_nop 0
	global_load_lds_dwordx4 v146, s[8:9]
	s_add_u32 s8, s16, 0x100000
	s_addc_u32 s9, s17, 0
	s_add_i32 s44, s96, s61
	s_mov_b32 m0, s44
	s_nop 0
	global_load_lds_dwordx4 v144, s[8:9]
	s_add_i32 m0, s44, 0x2000
	s_nop 0
	global_load_lds_dwordx4 v146, s[8:9]
	s_mov_b64 s[8:9], s[24:25]
	s_mov_b32 m0, s63
	s_nop 0
	global_load_lds_dwordx4 v1, s[8:9]
	s_mov_b32 m0, s65
	s_nop 0
	global_load_lds_dwordx4 v145, s[8:9]
	s_nop 0
	s_nop 0
	s_setprio 1
	s_waitcnt vmcnt(8) lgkmcnt(0)
	s_barrier
	v_mfma_f32_16x16x32_bf16 v[62:65], v[136:139], v[178:181], v[62:65]
	v_mfma_f32_16x16x32_bf16 v[58:61], v[154:157], v[178:181], v[58:61]
	v_mfma_f32_16x16x32_bf16 v[46:49], v[136:139], v[186:189], v[46:49]
	v_mfma_f32_16x16x32_bf16 v[42:45], v[154:157], v[186:189], v[42:45]
	v_mfma_f32_16x16x32_bf16 v[30:33], v[136:139], v[194:197], v[30:33]
	v_mfma_f32_16x16x32_bf16 v[26:29], v[154:157], v[194:197], v[26:29]
	v_mfma_f32_16x16x32_bf16 v[14:17], v[136:139], v[202:205], v[14:17]
	v_mfma_f32_16x16x32_bf16 v[10:13], v[154:157], v[202:205], v[10:13]
	v_mfma_f32_16x16x32_bf16 v[54:57], v[162:165], v[178:181], v[54:57]
	v_mfma_f32_16x16x32_bf16 v[50:53], v[170:173], v[178:181], v[50:53]
	v_mfma_f32_16x16x32_bf16 v[38:41], v[162:165], v[186:189], v[38:41]
	v_mfma_f32_16x16x32_bf16 v[34:37], v[170:173], v[186:189], v[34:37]
	v_mfma_f32_16x16x32_bf16 v[22:25], v[162:165], v[194:197], v[22:25]
	v_mfma_f32_16x16x32_bf16 v[18:21], v[170:173], v[194:197], v[18:21]
	v_mfma_f32_16x16x32_bf16 v[6:9], v[162:165], v[202:205], v[6:9]
	v_mfma_f32_16x16x32_bf16 v[2:5], v[170:173], v[202:205], v[2:5]
	v_mfma_f32_16x16x32_bf16 v[62:65], v[140:143], v[182:185], v[62:65]
	v_mfma_f32_16x16x32_bf16 v[58:61], v[158:161], v[182:185], v[58:61]
	v_mfma_f32_16x16x32_bf16 v[46:49], v[140:143], v[190:193], v[46:49]
	v_mfma_f32_16x16x32_bf16 v[42:45], v[158:161], v[190:193], v[42:45]
	v_mfma_f32_16x16x32_bf16 v[30:33], v[140:143], v[198:201], v[30:33]
	v_mfma_f32_16x16x32_bf16 v[26:29], v[158:161], v[198:201], v[26:29]
	v_mfma_f32_16x16x32_bf16 v[14:17], v[140:143], v[206:209], v[14:17]
	v_mfma_f32_16x16x32_bf16 v[10:13], v[158:161], v[206:209], v[10:13]
	v_mfma_f32_16x16x32_bf16 v[54:57], v[166:169], v[182:185], v[54:57]
	v_mfma_f32_16x16x32_bf16 v[50:53], v[174:177], v[182:185], v[50:53]
	v_mfma_f32_16x16x32_bf16 v[38:41], v[166:169], v[190:193], v[38:41]
	v_mfma_f32_16x16x32_bf16 v[34:37], v[174:177], v[190:193], v[34:37]
	v_mfma_f32_16x16x32_bf16 v[22:25], v[166:169], v[198:201], v[22:25]
	v_mfma_f32_16x16x32_bf16 v[18:21], v[174:177], v[198:201], v[18:21]
	v_mfma_f32_16x16x32_bf16 v[6:9], v[166:169], v[206:209], v[6:9]
	v_mfma_f32_16x16x32_bf16 v[2:5], v[174:177], v[206:209], v[2:5]
	s_setprio 0
	s_barrier
; #define PG8_STAGE(bufoff, gbase, voff) do { const char* _gb = (const char*)(gbase); asm volatile("" : "+s"(_gb)); _Pragma("unroll") for (int _i = 0; _i < 2; ++_i) { asm volatile("" : "+v"((voff)[_i])); \
;         __builtin_amdgcn_global_load_lds((const unsigned*)(_gb + (voff)[_i]), (PG8_LAS unsigned*)(lds + (bufoff) + ldsw + _i * 8192), 16, 0, 0); } } while (0)
; #define PG8_LDA(dst, b, h) do { _Pragma("unroll") for (int m = 0; m < 4; ++m) _Pragma("unroll") for (int k = 0; k < 2; ++k) dst[m][k] = *(const PG8_LAS bf16x8*)(lds + PG8_SA(b, h) + aoff + m * 2048 + k * 1024); } while (0)
; #define PG8_LDB(dst, b, h) do { _Pragma("unroll") for (int n = 0; n < 2; ++n) _Pragma("unroll") for (int k = 0; k < 2; ++k) dst[n][k] = *(const PG8_LAS bf16x8*)(lds + PG8_SB(b, h) + boff + n * 2048 + k * 1024); } while (0)
; #define PG8_WAIT_V(n) asm volatile("s_waitcnt vmcnt(" #n ")" ::: "memory")
; #define PG8_WAIT_L(n) asm volatile("s_waitcnt lgkmcnt(" #n ")" ::: "memory")
; #define PG8_BAR __builtin_amdgcn_s_barrier()
; #define PG8_SCHED __builtin_amdgcn_sched_barrier(0)
; #define PG8_STAGE(bufoff, gbase, voff) do { const char* _gb = (const char*)(gbase); asm volatile("" : "+s"(_gb)); _Pragma("unroll") for (int _i = 0; _i < 2; ++_i) { asm volatile("" : "+v"((voff)[_i])); \
;         __builtin_amdgcn_global_load_lds((const unsigned*)(_gb + (voff)[_i]), (PG8_LAS unsigned*)(lds + (bufoff) + ldsw + _i * 8192), 16, 0, 0); } } while (0)
; #define PG8_LDA(dst, b, h) do { _Pragma("unroll") for (int m = 0; m < 4; ++m) _Pragma("unroll") for (int k = 0; k < 2; ++k) dst[m][k] = *(const PG8_LAS bf16x8*)(lds + PG8_SA(b, h) + aoff + m * 2048 + k * 1024); } while (0)
; #define PG8_WAIT_V(n) asm volatile("s_waitcnt vmcnt(" #n ")" ::: "memory")
; template <class Epi, class Sched, bool ALIGN_EPI = false, bool SP2 = false>
; __device__ __forceinline__ void gemm_phase(PG8_LAS unsigned char* lds, const Gemm g, const Sched& S, const Epi& E) {
;     ...
;             PG8_LDB(B0, 1, 0); PG8_LDB(B1, 1, 1); PG8_SCHED; PG8_LDA(At, 1, 0); PG8_STAGE(PG8_SA(0, 1), a2 + hstep, voffA);
;             PG8_WAIT_V(8); PG8_WAIT_L(0); PG8_BAR; PG8_MMA2(0); PG8_BAR; PG8_SCHED;
;             PG8_LDA(At, 1, 1); PG8_STAGE(PG8_SB(1, 0), b3, voffB); PG8_STAGE(PG8_SB(1, 1), b3 + hstep, voffB); PG8_STAGE(PG8_SA(1, 0), a3, voffA);
;             PG8_WAIT_V(8); PG8_WAIT_L(0); PG8_BAR; PG8_MMA2(1); PG8_BAR; PG8_SCHED;
	s_add_i32 s44, 0, 0x18000
	v_add_u32_e32 v135, s44, v148
	s_add_i32 s45, 0, 0x1c000
	ds_read_b128 v[136:139], v135
	ds_read_b128 v[140:143], v135 offset:1024
	ds_read_b128 v[154:157], v135 offset:2048
	ds_read_b128 v[158:161], v135 offset:3072
	v_add_u32_e32 v135, s45, v148
	ds_read_b128 v[162:165], v135
	ds_read_b128 v[166:169], v135 offset:1024
	ds_read_b128 v[170:173], v135 offset:2048
	ds_read_b128 v[174:177], v135 offset:3072
	s_add_u32 s8, s24, 0x100000
	s_addc_u32 s9, s25, 0
	s_mov_b32 m0, s88
	ds_read_b128 v[178:181], v152 offset:32768
	ds_read_b128 v[182:185], v152 offset:33792
	ds_read_b128 v[186:189], v152 offset:34816
	ds_read_b128 v[190:193], v152 offset:35840
	ds_read_b128 v[194:197], v152 offset:36864
	ds_read_b128 v[198:201], v152 offset:37888
	ds_read_b128 v[202:205], v152 offset:38912
	ds_read_b128 v[206:209], v152 offset:39936
	s_nop 0
	global_load_lds_dwordx4 v1, s[8:9]
	s_mov_b32 m0, s89
	s_nop 0
	global_load_lds_dwordx4 v145, s[8:9]
	s_nop 0
	s_nop 0
	s_setprio 1
	s_waitcnt vmcnt(8) lgkmcnt(0)
	s_barrier
	v_mfma_f32_16x16x32_bf16 v[126:129], v[136:139], v[178:181], v[126:129]
	v_mfma_f32_16x16x32_bf16 v[122:125], v[154:157], v[178:181], v[122:125]
	v_mfma_f32_16x16x32_bf16 v[110:113], v[136:139], v[186:189], v[110:113]
	v_mfma_f32_16x16x32_bf16 v[106:109], v[154:157], v[186:189], v[106:109]
	v_mfma_f32_16x16x32_bf16 v[94:97], v[136:139], v[194:197], v[94:97]
	v_mfma_f32_16x16x32_bf16 v[90:93], v[154:157], v[194:197], v[90:93]
	v_mfma_f32_16x16x32_bf16 v[78:81], v[136:139], v[202:205], v[78:81]
	v_mfma_f32_16x16x32_bf16 v[74:77], v[154:157], v[202:205], v[74:77]
	v_mfma_f32_16x16x32_bf16 v[118:121], v[162:165], v[178:181], v[118:121]
	v_mfma_f32_16x16x32_bf16 v[114:117], v[170:173], v[178:181], v[114:117]
	v_mfma_f32_16x16x32_bf16 v[102:105], v[162:165], v[186:189], v[102:105]
	v_mfma_f32_16x16x32_bf16 v[98:101], v[170:173], v[186:189], v[98:101]
	v_mfma_f32_16x16x32_bf16 v[86:89], v[162:165], v[194:197], v[86:89]
	v_mfma_f32_16x16x32_bf16 v[82:85], v[170:173], v[194:197], v[82:85]
	v_mfma_f32_16x16x32_bf16 v[70:73], v[162:165], v[202:205], v[70:73]
	v_mfma_f32_16x16x32_bf16 v[66:69], v[170:173], v[202:205], v[66:69]
	v_mfma_f32_16x16x32_bf16 v[126:129], v[140:143], v[182:185], v[126:129]
	v_mfma_f32_16x16x32_bf16 v[122:125], v[158:161], v[182:185], v[122:125]
	v_mfma_f32_16x16x32_bf16 v[110:113], v[140:143], v[190:193], v[110:113]
	v_mfma_f32_16x16x32_bf16 v[106:109], v[158:161], v[190:193], v[106:109]
	v_mfma_f32_16x16x32_bf16 v[94:97], v[140:143], v[198:201], v[94:97]
	v_mfma_f32_16x16x32_bf16 v[90:93], v[158:161], v[198:201], v[90:93]
	v_mfma_f32_16x16x32_bf16 v[78:81], v[140:143], v[206:209], v[78:81]
	v_mfma_f32_16x16x32_bf16 v[74:77], v[158:161], v[206:209], v[74:77]
	v_mfma_f32_16x16x32_bf16 v[118:121], v[166:169], v[182:185], v[118:121]
	v_mfma_f32_16x16x32_bf16 v[114:117], v[174:177], v[182:185], v[114:117]
	v_mfma_f32_16x16x32_bf16 v[102:105], v[166:169], v[190:193], v[102:105]
	v_mfma_f32_16x16x32_bf16 v[98:101], v[174:177], v[190:193], v[98:101]
	v_mfma_f32_16x16x32_bf16 v[86:89], v[166:169], v[198:201], v[86:89]
	v_mfma_f32_16x16x32_bf16 v[82:85], v[174:177], v[198:201], v[82:85]
	v_mfma_f32_16x16x32_bf16 v[70:73], v[166:169], v[206:209], v[70:73]
	v_mfma_f32_16x16x32_bf16 v[66:69], v[174:177], v[206:209], v[66:69]
	s_setprio 0
	s_barrier
	s_add_u32 s8, s16, 0x80
	s_addc_u32 s9, s17, 0
	s_add_i32 s24, s44, s61
	s_mov_b32 m0, s24
	ds_read_b128 v[178:181], v152 offset:49152
	ds_read_b128 v[182:185], v152 offset:50176
	ds_read_b128 v[186:189], v152 offset:51200
	ds_read_b128 v[190:193], v152 offset:52224
	ds_read_b128 v[194:197], v152 offset:53248
	ds_read_b128 v[198:201], v152 offset:54272
	ds_read_b128 v[202:205], v152 offset:55296
	ds_read_b128 v[206:209], v152 offset:56320
	s_nop 0
	global_load_lds_dwordx4 v144, s[8:9]
	s_add_i32 m0, s24, 0x2000
	s_nop 0
	global_load_lds_dwordx4 v146, s[8:9]
	s_add_u32 s8, s16, 0x100080
	s_addc_u32 s9, s17, 0
	s_add_i32 s16, s45, s61
	s_mov_b32 m0, s16
	s_nop 0
	global_load_lds_dwordx4 v144, s[8:9]
	s_add_i32 m0, s16, 0x2000
	s_nop 0
	global_load_lds_dwordx4 v146, s[8:9]
	s_mov_b32 m0, s91
	s_nop 0
	global_load_lds_dwordx4 v1, s[2:3]
	s_mov_b32 m0, s92
	s_nop 0
	global_load_lds_dwordx4 v145, s[2:3]
	s_nop 0
	s_nop 0
	s_setprio 1
	s_waitcnt vmcnt(8) lgkmcnt(0)
	s_barrier
	v_mfma_f32_16x16x32_bf16 v[62:65], v[136:139], v[178:181], v[62:65]
	v_mfma_f32_16x16x32_bf16 v[58:61], v[154:157], v[178:181], v[58:61]
	v_mfma_f32_16x16x32_bf16 v[46:49], v[136:139], v[186:189], v[46:49]
	v_mfma_f32_16x16x32_bf16 v[42:45], v[154:157], v[186:189], v[42:45]
	v_mfma_f32_16x16x32_bf16 v[30:33], v[136:139], v[194:197], v[30:33]
	v_mfma_f32_16x16x32_bf16 v[26:29], v[154:157], v[194:197], v[26:29]
	v_mfma_f32_16x16x32_bf16 v[14:17], v[136:139], v[202:205], v[14:17]
	v_mfma_f32_16x16x32_bf16 v[10:13], v[154:157], v[202:205], v[10:13]
	v_mfma_f32_16x16x32_bf16 v[54:57], v[162:165], v[178:181], v[54:57]
	v_mfma_f32_16x16x32_bf16 v[50:53], v[170:173], v[178:181], v[50:53]
	v_mfma_f32_16x16x32_bf16 v[38:41], v[162:165], v[186:189], v[38:41]
	v_mfma_f32_16x16x32_bf16 v[34:37], v[170:173], v[186:189], v[34:37]
	v_mfma_f32_16x16x32_bf16 v[22:25], v[162:165], v[194:197], v[22:25]
	v_mfma_f32_16x16x32_bf16 v[18:21], v[170:173], v[194:197], v[18:21]
	v_mfma_f32_16x16x32_bf16 v[6:9], v[162:165], v[202:205], v[6:9]
	v_mfma_f32_16x16x32_bf16 v[2:5], v[170:173], v[202:205], v[2:5]
	v_mfma_f32_16x16x32_bf16 v[62:65], v[140:143], v[182:185], v[62:65]
	v_mfma_f32_16x16x32_bf16 v[58:61], v[158:161], v[182:185], v[58:61]
	v_mfma_f32_16x16x32_bf16 v[46:49], v[140:143], v[190:193], v[46:49]
	v_mfma_f32_16x16x32_bf16 v[42:45], v[158:161], v[190:193], v[42:45]
	v_mfma_f32_16x16x32_bf16 v[30:33], v[140:143], v[198:201], v[30:33]
	v_mfma_f32_16x16x32_bf16 v[26:29], v[158:161], v[198:201], v[26:29]
	v_mfma_f32_16x16x32_bf16 v[14:17], v[140:143], v[206:209], v[14:17]
	v_mfma_f32_16x16x32_bf16 v[10:13], v[158:161], v[206:209], v[10:13]
	v_mfma_f32_16x16x32_bf16 v[54:57], v[166:169], v[182:185], v[54:57]
	v_mfma_f32_16x16x32_bf16 v[50:53], v[174:177], v[182:185], v[50:53]
	v_mfma_f32_16x16x32_bf16 v[38:41], v[166:169], v[190:193], v[38:41]
	v_mfma_f32_16x16x32_bf16 v[34:37], v[174:177], v[190:193], v[34:37]
	v_mfma_f32_16x16x32_bf16 v[22:25], v[166:169], v[198:201], v[22:25]
	v_mfma_f32_16x16x32_bf16 v[18:21], v[174:177], v[198:201], v[18:21]
	v_mfma_f32_16x16x32_bf16 v[6:9], v[166:169], v[206:209], v[6:9]
	v_mfma_f32_16x16x32_bf16 v[2:5], v[174:177], v[206:209], v[2:5]
	s_setprio 0
	s_barrier
	s_add_i32 s43, s43, 2
	s_add_u32 s37, s37, 0x100
	s_addc_u32 s42, s42, 0
	s_cmp_gt_u32 s43, 61
	s_mov_b64 s[8:9], s[14:15]
	s_cbranch_scc0 .LBB0_313
	s_and_b64 vcc, exec, s[58:59]
	s_cbranch_vccz .LBB0_333
	s_barrier
	s_cmp_lt_i32 s12, 24
	s_cbranch_scc0 .LBB0_334

.LBB0_746:
	ds_read_b128 v[118:121], v172
	ds_read_b128 v[134:137], v172 offset:1024
	ds_read_b128 v[138:141], v172 offset:2048
	ds_read_b128 v[142:145], v172 offset:3072
	ds_read_b128 v[146:149], v173
	ds_read_b128 v[150:153], v173 offset:1024
	ds_read_b128 v[154:157], v173 offset:2048
	ds_read_b128 v[176:179], v173 offset:3072
	s_add_u32 s16, s0, 0x100
	s_addc_u32 s17, s1, 0
	s_cmp_eq_u32 s33, 28
	s_cselect_b32 s26, s30, s16
	s_cselect_b32 s27, s31, s17
	s_cselect_b32 s24, s78, s5
	s_cselect_b32 s25, s79, s21
	s_add_u32 s2, s26, 0x80
	s_addc_u32 s3, s27, 0
	s_add_u32 s0, s0, 0x100080
	s_addc_u32 s1, s1, 0
	s_add_i32 s76, s46, 0xc000
	s_mov_b32 m0, s76
	s_add_i32 s77, s46, 0xe000
	ds_read_b128 v[180:183], v174
	ds_read_b128 v[184:187], v174 offset:1024
	ds_read_b128 v[188:191], v174 offset:2048
	ds_read_b128 v[192:195], v174 offset:3072
	ds_read_b128 v[196:199], v174 offset:4096
	ds_read_b128 v[200:203], v174 offset:5120
	ds_read_b128 v[204:207], v174 offset:6144
	ds_read_b128 v[208:211], v174 offset:7168
	s_nop 0
	global_load_lds_dwordx4 v1, s[0:1]
	s_mov_b32 m0, s77
	s_nop 0
	global_load_lds_dwordx4 v165, s[0:1]
	s_nop 0
	s_nop 0
	s_setprio 1
	s_waitcnt vmcnt(8) lgkmcnt(0)
	s_barrier
	v_mfma_f32_16x16x32_bf16 v[34:37], v[118:121], v[180:183], v[34:37]
	v_mfma_f32_16x16x32_bf16 v[30:33], v[138:141], v[180:183], v[30:33]
	v_mfma_f32_16x16x32_bf16 v[46:49], v[118:121], v[188:191], v[46:49]
	v_mfma_f32_16x16x32_bf16 v[62:65], v[138:141], v[188:191], v[62:65]
	v_mfma_f32_16x16x32_bf16 v[78:81], v[118:121], v[196:199], v[78:81]
	v_mfma_f32_16x16x32_bf16 v[90:93], v[138:141], v[196:199], v[90:93]
	v_mfma_f32_16x16x32_bf16 v[130:133], v[118:121], v[204:207], v[130:133]
	v_mfma_f32_16x16x32_bf16 v[114:117], v[138:141], v[204:207], v[114:117]
	v_mfma_f32_16x16x32_bf16 v[26:29], v[146:149], v[180:183], v[26:29]
	v_mfma_f32_16x16x32_bf16 v[50:53], v[154:157], v[180:183], v[50:53]
	v_mfma_f32_16x16x32_bf16 v[58:61], v[146:149], v[188:191], v[58:61]
	v_mfma_f32_16x16x32_bf16 v[82:85], v[154:157], v[188:191], v[82:85]
	v_mfma_f32_16x16x32_bf16 v[110:113], v[146:149], v[196:199], v[110:113]
	v_mfma_f32_16x16x32_bf16 v[106:109], v[154:157], v[196:199], v[106:109]
	v_mfma_f32_16x16x32_bf16 v[122:125], v[146:149], v[204:207], v[122:125]
	v_mfma_f32_16x16x32_bf16 v[126:129], v[154:157], v[204:207], v[126:129]
	v_mfma_f32_16x16x32_bf16 v[34:37], v[134:137], v[184:187], v[34:37]
	v_mfma_f32_16x16x32_bf16 v[30:33], v[142:145], v[184:187], v[30:33]
	v_mfma_f32_16x16x32_bf16 v[46:49], v[134:137], v[192:195], v[46:49]
	v_mfma_f32_16x16x32_bf16 v[62:65], v[142:145], v[192:195], v[62:65]
	v_mfma_f32_16x16x32_bf16 v[78:81], v[134:137], v[200:203], v[78:81]
	v_mfma_f32_16x16x32_bf16 v[90:93], v[142:145], v[200:203], v[90:93]
	v_mfma_f32_16x16x32_bf16 v[130:133], v[134:137], v[208:211], v[130:133]
	v_mfma_f32_16x16x32_bf16 v[114:117], v[142:145], v[208:211], v[114:117]
	v_mfma_f32_16x16x32_bf16 v[26:29], v[150:153], v[184:187], v[26:29]
	v_mfma_f32_16x16x32_bf16 v[50:53], v[176:179], v[184:187], v[50:53]
	v_mfma_f32_16x16x32_bf16 v[58:61], v[150:153], v[192:195], v[58:61]
	v_mfma_f32_16x16x32_bf16 v[82:85], v[176:179], v[192:195], v[82:85]
	v_mfma_f32_16x16x32_bf16 v[110:113], v[150:153], v[200:203], v[110:113]
	v_mfma_f32_16x16x32_bf16 v[106:109], v[176:179], v[200:203], v[106:109]
	v_mfma_f32_16x16x32_bf16 v[122:125], v[150:153], v[208:211], v[122:125]
	v_mfma_f32_16x16x32_bf16 v[126:129], v[176:179], v[208:211], v[126:129]
	s_setprio 0
	s_barrier
	s_add_i32 s80, s72, s45
	s_mov_b64 s[0:1], s[24:25]
	s_mov_b32 m0, s80
	s_add_i32 s81, s80, 0x2000
	ds_read_b128 v[180:183], v174 offset:16384
	ds_read_b128 v[184:187], v174 offset:17408
	ds_read_b128 v[188:191], v174 offset:18432
	ds_read_b128 v[192:195], v174 offset:19456
	ds_read_b128 v[196:199], v174 offset:20480
	ds_read_b128 v[200:203], v174 offset:21504
	ds_read_b128 v[204:207], v174 offset:22528
	ds_read_b128 v[208:211], v174 offset:23552
	s_nop 0
	global_load_lds_dwordx4 v164, s[0:1]
	s_mov_b32 m0, s81
	s_nop 0
	global_load_lds_dwordx4 v166, s[0:1]
	s_add_u32 s0, s24, 0x100000
	s_addc_u32 s1, s25, 0
	s_add_i32 s82, s73, s45
	s_mov_b32 m0, s82
	s_add_i32 s83, s82, 0x2000
	s_nop 0
	global_load_lds_dwordx4 v164, s[0:1]
	s_mov_b32 m0, s83
	s_nop 0
	global_load_lds_dwordx4 v166, s[0:1]
	s_mov_b64 s[0:1], s[26:27]
	s_mov_b32 m0, s46
	s_nop 0
	global_load_lds_dwordx4 v1, s[0:1]
	s_mov_b32 m0, s47
	s_nop 0
	global_load_lds_dwordx4 v165, s[0:1]
	s_nop 0
	s_nop 0
	s_setprio 1
	s_waitcnt vmcnt(8) lgkmcnt(0)
	s_barrier
	v_mfma_f32_16x16x32_bf16 v[102:105], v[118:121], v[180:183], v[102:105]
	v_mfma_f32_16x16x32_bf16 v[98:101], v[138:141], v[180:183], v[98:101]
	v_mfma_f32_16x16x32_bf16 v[74:77], v[118:121], v[188:191], v[74:77]
	v_mfma_f32_16x16x32_bf16 v[70:73], v[138:141], v[188:191], v[70:73]
	v_mfma_f32_16x16x32_bf16 v[42:45], v[118:121], v[196:199], v[42:45]
	v_mfma_f32_16x16x32_bf16 v[38:41], v[138:141], v[196:199], v[38:41]
	v_mfma_f32_16x16x32_bf16 v[18:21], v[118:121], v[204:207], v[18:21]
	v_mfma_f32_16x16x32_bf16 v[10:13], v[138:141], v[204:207], v[10:13]
	v_mfma_f32_16x16x32_bf16 v[94:97], v[146:149], v[180:183], v[94:97]
	v_mfma_f32_16x16x32_bf16 v[86:89], v[154:157], v[180:183], v[86:89]
	v_mfma_f32_16x16x32_bf16 v[66:69], v[146:149], v[188:191], v[66:69]
	v_mfma_f32_16x16x32_bf16 v[54:57], v[154:157], v[188:191], v[54:57]
	v_mfma_f32_16x16x32_bf16 v[22:25], v[146:149], v[196:199], v[22:25]
	v_mfma_f32_16x16x32_bf16 v[14:17], v[154:157], v[196:199], v[14:17]
	v_mfma_f32_16x16x32_bf16 v[6:9], v[146:149], v[204:207], v[6:9]
	v_mfma_f32_16x16x32_bf16 v[2:5], v[154:157], v[204:207], v[2:5]
	v_mfma_f32_16x16x32_bf16 v[102:105], v[134:137], v[184:187], v[102:105]
	v_mfma_f32_16x16x32_bf16 v[98:101], v[142:145], v[184:187], v[98:101]
	v_mfma_f32_16x16x32_bf16 v[74:77], v[134:137], v[192:195], v[74:77]
	v_mfma_f32_16x16x32_bf16 v[70:73], v[142:145], v[192:195], v[70:73]
	v_mfma_f32_16x16x32_bf16 v[42:45], v[134:137], v[200:203], v[42:45]
	v_mfma_f32_16x16x32_bf16 v[38:41], v[142:145], v[200:203], v[38:41]
	v_mfma_f32_16x16x32_bf16 v[18:21], v[134:137], v[208:211], v[18:21]
	v_mfma_f32_16x16x32_bf16 v[10:13], v[142:145], v[208:211], v[10:13]
	v_mfma_f32_16x16x32_bf16 v[94:97], v[150:153], v[184:187], v[94:97]
	v_mfma_f32_16x16x32_bf16 v[86:89], v[176:179], v[184:187], v[86:89]
	v_mfma_f32_16x16x32_bf16 v[66:69], v[150:153], v[192:195], v[66:69]
	v_mfma_f32_16x16x32_bf16 v[54:57], v[176:179], v[192:195], v[54:57]
	v_mfma_f32_16x16x32_bf16 v[22:25], v[150:153], v[200:203], v[22:25]
	v_mfma_f32_16x16x32_bf16 v[14:17], v[176:179], v[200:203], v[14:17]
	v_mfma_f32_16x16x32_bf16 v[6:9], v[150:153], v[208:211], v[6:9]
	v_mfma_f32_16x16x32_bf16 v[2:5], v[176:179], v[208:211], v[2:5]
	s_setprio 0
	s_barrier
	s_add_i32 s84, 0, 0x18000
	s_add_i32 s86, 0, 0x1c000
	v_add_u32_e32 v175, s84, v170
	v_add_u32_e32 v176, s86, v170
	ds_read_b128 v[118:121], v175
	ds_read_b128 v[134:137], v175 offset:1024
	ds_read_b128 v[138:141], v175 offset:2048
	ds_read_b128 v[142:145], v175 offset:3072
	ds_read_b128 v[146:149], v176
	ds_read_b128 v[150:153], v176 offset:1024
	ds_read_b128 v[154:157], v176 offset:2048
	ds_read_b128 v[178:181], v176 offset:3072
	s_add_u32 s0, s26, 0x100000
	s_addc_u32 s1, s27, 0
	s_mov_b32 m0, s48
	ds_read_b128 v[182:185], v174 offset:32768
	ds_read_b128 v[186:189], v174 offset:33792
	ds_read_b128 v[190:193], v174 offset:34816
	ds_read_b128 v[194:197], v174 offset:35840
	ds_read_b128 v[198:201], v174 offset:36864
	ds_read_b128 v[202:205], v174 offset:37888
	ds_read_b128 v[206:209], v174 offset:38912
	ds_read_b128 v[210:213], v174 offset:39936
	s_nop 0
	global_load_lds_dwordx4 v1, s[0:1]
	s_mov_b32 m0, s49
	s_nop 0
	global_load_lds_dwordx4 v165, s[0:1]
	s_nop 0
	s_nop 0
	s_setprio 1
	s_waitcnt vmcnt(8) lgkmcnt(0)
	s_barrier
	v_mfma_f32_16x16x32_bf16 v[34:37], v[118:121], v[182:185], v[34:37]
	v_mfma_f32_16x16x32_bf16 v[30:33], v[138:141], v[182:185], v[30:33]
	v_mfma_f32_16x16x32_bf16 v[46:49], v[118:121], v[190:193], v[46:49]
	v_mfma_f32_16x16x32_bf16 v[62:65], v[138:141], v[190:193], v[62:65]
	v_mfma_f32_16x16x32_bf16 v[78:81], v[118:121], v[198:201], v[78:81]
	v_mfma_f32_16x16x32_bf16 v[90:93], v[138:141], v[198:201], v[90:93]
	v_mfma_f32_16x16x32_bf16 v[130:133], v[118:121], v[206:209], v[130:133]
	v_mfma_f32_16x16x32_bf16 v[114:117], v[138:141], v[206:209], v[114:117]
	v_mfma_f32_16x16x32_bf16 v[26:29], v[146:149], v[182:185], v[26:29]
	v_mfma_f32_16x16x32_bf16 v[50:53], v[154:157], v[182:185], v[50:53]
	v_mfma_f32_16x16x32_bf16 v[58:61], v[146:149], v[190:193], v[58:61]
	v_mfma_f32_16x16x32_bf16 v[82:85], v[154:157], v[190:193], v[82:85]
	v_mfma_f32_16x16x32_bf16 v[110:113], v[146:149], v[198:201], v[110:113]
	v_mfma_f32_16x16x32_bf16 v[106:109], v[154:157], v[198:201], v[106:109]
	v_mfma_f32_16x16x32_bf16 v[122:125], v[146:149], v[206:209], v[122:125]
	v_mfma_f32_16x16x32_bf16 v[126:129], v[154:157], v[206:209], v[126:129]
	v_mfma_f32_16x16x32_bf16 v[34:37], v[134:137], v[186:189], v[34:37]
	v_mfma_f32_16x16x32_bf16 v[30:33], v[142:145], v[186:189], v[30:33]
	v_mfma_f32_16x16x32_bf16 v[46:49], v[134:137], v[194:197], v[46:49]
	v_mfma_f32_16x16x32_bf16 v[62:65], v[142:145], v[194:197], v[62:65]
	v_mfma_f32_16x16x32_bf16 v[78:81], v[134:137], v[202:205], v[78:81]
	v_mfma_f32_16x16x32_bf16 v[90:93], v[142:145], v[202:205], v[90:93]
	v_mfma_f32_16x16x32_bf16 v[130:133], v[134:137], v[210:213], v[130:133]
	v_mfma_f32_16x16x32_bf16 v[114:117], v[142:145], v[210:213], v[114:117]
	v_mfma_f32_16x16x32_bf16 v[26:29], v[150:153], v[186:189], v[26:29]
	v_mfma_f32_16x16x32_bf16 v[50:53], v[178:181], v[186:189], v[50:53]
	v_mfma_f32_16x16x32_bf16 v[58:61], v[150:153], v[194:197], v[58:61]
	v_mfma_f32_16x16x32_bf16 v[82:85], v[178:181], v[194:197], v[82:85]
	v_mfma_f32_16x16x32_bf16 v[110:113], v[150:153], v[202:205], v[110:113]
	v_mfma_f32_16x16x32_bf16 v[106:109], v[178:181], v[202:205], v[106:109]
	v_mfma_f32_16x16x32_bf16 v[122:125], v[150:153], v[210:213], v[122:125]
	v_mfma_f32_16x16x32_bf16 v[126:129], v[178:181], v[210:213], v[126:129]
	s_setprio 0
	s_barrier
	s_add_u32 s0, s24, 0x80
	s_addc_u32 s1, s25, 0
	s_add_i32 s84, s84, s45
	s_mov_b32 m0, s84
	s_add_i32 s85, s84, 0x2000
	ds_read_b128 v[182:185], v174 offset:49152
	ds_read_b128 v[186:189], v174 offset:50176
	ds_read_b128 v[190:193], v174 offset:51200
	ds_read_b128 v[194:197], v174 offset:52224
	ds_read_b128 v[198:201], v174 offset:53248
	ds_read_b128 v[202:205], v174 offset:54272
	ds_read_b128 v[206:209], v174 offset:55296
	ds_read_b128 v[210:213], v174 offset:56320
	s_nop 0
	global_load_lds_dwordx4 v164, s[0:1]
	s_mov_b32 m0, s85
	s_nop 0
	global_load_lds_dwordx4 v166, s[0:1]
	s_add_u32 s0, s24, 0x100080
	s_addc_u32 s1, s25, 0
	s_add_i32 s86, s86, s45
	s_mov_b32 m0, s86
	s_add_i32 s87, s86, 0x2000
	s_nop 0
	global_load_lds_dwordx4 v164, s[0:1]
	s_mov_b32 m0, s87
	s_nop 0
	global_load_lds_dwordx4 v166, s[0:1]
	s_mov_b32 m0, s57
	s_nop 0
	global_load_lds_dwordx4 v1, s[2:3]
	s_mov_b32 m0, s62
	s_nop 0
	global_load_lds_dwordx4 v165, s[2:3]
	s_nop 0
	s_nop 0
	s_setprio 1
	s_waitcnt vmcnt(8) lgkmcnt(0)
	s_barrier
	v_mfma_f32_16x16x32_bf16 v[102:105], v[118:121], v[182:185], v[102:105]
	v_mfma_f32_16x16x32_bf16 v[98:101], v[138:141], v[182:185], v[98:101]
	v_mfma_f32_16x16x32_bf16 v[74:77], v[118:121], v[190:193], v[74:77]
	v_mfma_f32_16x16x32_bf16 v[70:73], v[138:141], v[190:193], v[70:73]
	v_mfma_f32_16x16x32_bf16 v[42:45], v[118:121], v[198:201], v[42:45]
	v_mfma_f32_16x16x32_bf16 v[38:41], v[138:141], v[198:201], v[38:41]
	v_mfma_f32_16x16x32_bf16 v[18:21], v[118:121], v[206:209], v[18:21]
	v_mfma_f32_16x16x32_bf16 v[10:13], v[138:141], v[206:209], v[10:13]
	v_mfma_f32_16x16x32_bf16 v[94:97], v[146:149], v[182:185], v[94:97]
	v_mfma_f32_16x16x32_bf16 v[86:89], v[154:157], v[182:185], v[86:89]
	v_mfma_f32_16x16x32_bf16 v[66:69], v[146:149], v[190:193], v[66:69]
	v_mfma_f32_16x16x32_bf16 v[54:57], v[154:157], v[190:193], v[54:57]
	v_mfma_f32_16x16x32_bf16 v[22:25], v[146:149], v[198:201], v[22:25]
	v_mfma_f32_16x16x32_bf16 v[14:17], v[154:157], v[198:201], v[14:17]
	v_mfma_f32_16x16x32_bf16 v[6:9], v[146:149], v[206:209], v[6:9]
	v_mfma_f32_16x16x32_bf16 v[2:5], v[154:157], v[206:209], v[2:5]
	v_mfma_f32_16x16x32_bf16 v[102:105], v[134:137], v[186:189], v[102:105]
	v_mfma_f32_16x16x32_bf16 v[98:101], v[142:145], v[186:189], v[98:101]
	v_mfma_f32_16x16x32_bf16 v[74:77], v[134:137], v[194:197], v[74:77]
	v_mfma_f32_16x16x32_bf16 v[70:73], v[142:145], v[194:197], v[70:73]
	v_mfma_f32_16x16x32_bf16 v[42:45], v[134:137], v[202:205], v[42:45]
	v_mfma_f32_16x16x32_bf16 v[38:41], v[142:145], v[202:205], v[38:41]
	v_mfma_f32_16x16x32_bf16 v[18:21], v[134:137], v[210:213], v[18:21]
	v_mfma_f32_16x16x32_bf16 v[10:13], v[142:145], v[210:213], v[10:13]
	v_mfma_f32_16x16x32_bf16 v[94:97], v[150:153], v[186:189], v[94:97]
	v_mfma_f32_16x16x32_bf16 v[86:89], v[178:181], v[186:189], v[86:89]
	v_mfma_f32_16x16x32_bf16 v[66:69], v[150:153], v[194:197], v[66:69]
	v_mfma_f32_16x16x32_bf16 v[54:57], v[178:181], v[194:197], v[54:57]
	v_mfma_f32_16x16x32_bf16 v[22:25], v[150:153], v[202:205], v[22:25]
	v_mfma_f32_16x16x32_bf16 v[14:17], v[178:181], v[202:205], v[14:17]
	v_mfma_f32_16x16x32_bf16 v[6:9], v[150:153], v[210:213], v[6:9]
	v_mfma_f32_16x16x32_bf16 v[2:5], v[178:181], v[210:213], v[2:5]
	s_setprio 0
	s_barrier
; __device__ __forceinline__ float bf_lo(unsigned w) { return __uint_as_float(w << 16); }
; __device__ __forceinline__ float bf_hi(unsigned w) { return __uint_as_float(w & 0xffff0000u); }
;     __device__ __forceinline__ void mid(f32x4 (&acc)[2][2][4][2], const Unit& u, int wr, int wc, int fr, int fq) const {
;     ...
;             for (int m = 0; m < 4; ++m) { const size_t off = (size_t)(row0 + ai * HALF + m * 16) * 4096 + col0;
; #pragma unroll
;                 for (int bj = 0; bj < 2; ++bj) { const u32x4 ga = *(const u32x4*)(SGA + off + bj * HALF), gb = *(const u32x4*)(SGB + off + bj * HALF);
;                     const unsigned wa[4] = {ga.x, ga.y, ga.z, ga.w}, wb[4] = {gb.x, gb.y, gb.z, gb.w};
; #pragma unroll
;                     for (int p = 0; p < 4; ++p) { const float rl = bf_lo(wa[p]) * __builtin_amdgcn_rcpf(fmaxf(bf_lo(wb[p]), 1e-20f)), rh = bf_hi(wa[p]) * __builtin_amdgcn_rcpf(fmaxf(bf_hi(wb[p]), 1e-20f));
;                         acc[ai][bj][m][p >> 1][(p & 1) * 2] *= rl; acc[ai][bj][m][p >> 1][(p & 1) * 2 + 1] *= rh; } }
	s_add_i32 s33, s33, 2
	s_add_u32 s5, s5, 0x100
	s_addc_u32 s21, s21, 0
	s_cmp_gt_u32 s33, 29
	s_mov_b64 s[0:1], s[16:17]
	s_cbranch_scc0 .LBB0_746
	v_mov_b32_e32 v119, v167
	v_mov_b32_e32 v118, v168
	s_lshl_b32 s89, s20, 8
	s_lshl_b32 s88, s4, 8
	s_or_b32 s0, s89, s56
	v_lshl_add_u32 v118, v118, 3, s0
	s_add_i32 s0, s88, s55
	v_add_u32_e32 v120, s0, v119
	v_ashrrev_i32_e32 v121, 31, v120
	v_ashrrev_i32_e32 v119, 31, v118
	v_lshlrev_b64 v[120:121], 12, v[120:121]
	v_lshl_add_u64 v[118:119], v[120:121], 0, v[118:119]
	v_lshlrev_b64 v[162:163], 1, v[118:119]
	v_lshl_add_u64 v[138:139], s[12:13], 0, v[162:163]
	global_load_dwordx4 v[134:137], v[138:139], off
	v_lshl_add_u64 v[140:141], s[10:11], 0, v[162:163]
	global_load_dwordx4 v[118:121], v[140:141], off
	global_load_dwordx4 v[150:153], v[138:139], off offset:256
	global_load_dwordx4 v[146:149], v[140:141], off offset:256
	s_mov_b64 s[0:1], 0x20000
	v_lshl_add_u64 v[138:139], v[162:163], 0, s[0:1]
	v_lshl_add_u64 v[154:155], s[10:11], 0, v[138:139]
	v_lshl_add_u64 v[156:157], s[12:13], 0, v[138:139]
	global_load_dwordx4 v[138:141], v[154:155], off
	global_load_dwordx4 v[142:145], v[156:157], off
	s_mov_b64 s[0:1], 0x40000
	s_add_i32 s50, s50, 1
	v_readlane_b32 s2, v238, 45
	s_waitcnt vmcnt(0)
	v_lshlrev_b32_e32 v178, 16, v118
	v_and_b32_e32 v180, 0xffff0000, v134
	v_lshlrev_b32_e32 v181, 16, v135
	v_and_b32_e32 v182, 0xffff0000, v135
	v_lshlrev_b32_e32 v183, 16, v136
	v_and_b32_e32 v184, 0xffff0000, v136
	v_lshlrev_b32_e32 v185, 16, v137
	v_and_b32_e32 v186, 0xffff0000, v137
	v_lshlrev_b32_e32 v187, 16, v150
	v_and_b32_e32 v150, 0xffff0000, v150
	v_lshlrev_b32_e32 v188, 16, v151
	v_and_b32_e32 v151, 0xffff0000, v151
	v_max_f32_e32 v180, v180, v180
	v_max_f32_e32 v181, v181, v181
	v_max_f32_e32 v182, v182, v182
	v_max_f32_e32 v183, v183, v183
	v_max_f32_e32 v184, v184, v184
	v_max_f32_e32 v185, v185, v185
	v_max_f32_e32 v186, v186, v186
	v_max_f32_e32 v187, v187, v187
	v_max_f32_e32 v150, v150, v150
	v_max_f32_e32 v188, v188, v188
	v_max_f32_e32 v151, v151, v151
	v_max_f32_e32 v180, 0x1e3ce508, v180
	v_max_f32_e32 v181, 0x1e3ce508, v181
	v_max_f32_e32 v182, 0x1e3ce508, v182
	v_max_f32_e32 v183, 0x1e3ce508, v183
	v_max_f32_e32 v184, 0x1e3ce508, v184
	v_max_f32_e32 v185, 0x1e3ce508, v185
	v_max_f32_e32 v186, 0x1e3ce508, v186
	v_max_f32_e32 v187, 0x1e3ce508, v187
	v_max_f32_e32 v189, 0x1e3ce508, v150
	v_max_f32_e32 v188, 0x1e3ce508, v188
	v_max_f32_e32 v190, 0x1e3ce508, v151
	v_rcp_f32_e32 v151, v180
	v_rcp_f32_e32 v180, v181
	v_rcp_f32_e32 v181, v182
	v_rcp_f32_e32 v182, v183
	v_rcp_f32_e32 v183, v184
	v_rcp_f32_e32 v184, v185
	v_rcp_f32_e32 v185, v186
	v_rcp_f32_e32 v186, v187
	v_rcp_f32_e32 v187, v189
	v_rcp_f32_e32 v188, v188
	v_rcp_f32_e32 v189, v190
	v_and_b32_e32 v179, 0xffff0000, v118
	v_lshlrev_b32_e32 v118, 16, v119
	v_and_b32_e32 v119, 0xffff0000, v119
	v_lshlrev_b32_e32 v177, 16, v134
	v_lshlrev_b32_e32 v134, 16, v120
	v_and_b32_e32 v135, 0xffff0000, v120
	v_lshlrev_b32_e32 v120, 16, v121
	v_and_b32_e32 v121, 0xffff0000, v121
	v_lshlrev_b32_e32 v136, 16, v146
	v_and_b32_e32 v137, 0xffff0000, v146
	v_lshlrev_b32_e32 v146, 16, v147
	v_and_b32_e32 v147, 0xffff0000, v147
	v_pk_mul_f32 v[118:119], v[180:181], v[118:119]
	v_pk_mul_f32 v[134:135], v[182:183], v[134:135]
	v_pk_mul_f32 v[120:121], v[184:185], v[120:121]
	v_pk_mul_f32 v[36:37], v[36:37], v[118:119]
	v_pk_mul_f32 v[118:119], v[188:189], v[146:147]
	v_pk_mul_f32 v[30:31], v[30:31], v[134:135]
	v_pk_mul_f32 v[32:33], v[32:33], v[120:121]
	v_pk_mul_f32 v[28:29], v[28:29], v[118:119]
	global_load_dwordx4 v[118:121], v[156:157], off offset:256
	v_lshlrev_b32_e32 v134, 16, v152
	v_max_f32_e32 v134, v134, v134
	v_max_f32_e32 v134, 0x1e3ce508, v134
	v_rcp_f32_e32 v146, v134
	v_and_b32_e32 v134, 0xffff0000, v152
	v_max_f32_e32 v134, v134, v134
	v_pk_mul_f32 v[136:137], v[186:187], v[136:137]
	v_max_f32_e32 v134, 0x1e3ce508, v134
	v_pk_mul_f32 v[26:27], v[26:27], v[136:137]
	v_rcp_f32_e32 v147, v134
	global_load_dwordx4 v[134:137], v[154:155], off offset:256
	v_max_f32_e32 v177, v177, v177
	v_max_f32_e32 v177, 0x1e3ce508, v177
	v_rcp_f32_e32 v150, v177
	s_nop 0
	v_pk_mul_f32 v[150:151], v[150:151], v[178:179]
	s_nop 0
	v_pk_mul_f32 v[34:35], v[34:35], v[150:151]
	v_lshlrev_b32_e32 v150, 16, v148
	v_and_b32_e32 v151, 0xffff0000, v148
	v_lshlrev_b32_e32 v148, 16, v153
	v_max_f32_e32 v148, v148, v148
	v_max_f32_e32 v148, 0x1e3ce508, v148
	v_pk_mul_f32 v[146:147], v[146:147], v[150:151]
	v_rcp_f32_e32 v150, v148
	v_and_b32_e32 v148, 0xffff0000, v153
	v_max_f32_e32 v148, v148, v148
	v_max_f32_e32 v148, 0x1e3ce508, v148
	v_rcp_f32_e32 v151, v148
	v_pk_mul_f32 v[50:51], v[50:51], v[146:147]
	v_lshlrev_b32_e32 v146, 16, v149
	v_and_b32_e32 v147, 0xffff0000, v149
	v_pk_mul_f32 v[146:147], v[150:151], v[146:147]
	v_lshlrev_b32_e32 v148, 16, v142
	v_and_b32_e32 v142, 0xffff0000, v142
	v_pk_mul_f32 v[52:53], v[52:53], v[146:147]
	v_lshlrev_b32_e32 v146, 16, v138
	v_and_b32_e32 v147, 0xffff0000, v138
	v_lshlrev_b32_e32 v138, 16, v143
	v_max_f32_e32 v148, v148, v148
	v_max_f32_e32 v142, v142, v142
	v_max_f32_e32 v138, v138, v138
	v_max_f32_e32 v148, 0x1e3ce508, v148
	v_max_f32_e32 v142, 0x1e3ce508, v142
	v_max_f32_e32 v138, 0x1e3ce508, v138
	v_rcp_f32_e32 v148, v148
	v_rcp_f32_e32 v149, v142
	v_rcp_f32_e32 v142, v138
	v_and_b32_e32 v138, 0xffff0000, v143
	v_max_f32_e32 v138, v138, v138
	v_max_f32_e32 v138, 0x1e3ce508, v138
	v_rcp_f32_e32 v143, v138
	v_lshl_add_u64 v[150:151], v[162:163], 0, s[0:1]
	v_pk_mul_f32 v[146:147], v[148:149], v[146:147]
	v_lshl_add_u64 v[154:155], s[12:13], 0, v[150:151]
	v_pk_mul_f32 v[46:47], v[46:47], v[146:147]
	global_load_dwordx4 v[146:149], v[154:155], off
	v_lshlrev_b32_e32 v138, 16, v139
	v_and_b32_e32 v139, 0xffff0000, v139
	v_pk_mul_f32 v[138:139], v[142:143], v[138:139]
	v_lshlrev_b32_e32 v142, 16, v144
	v_max_f32_e32 v142, v142, v142
	v_max_f32_e32 v142, 0x1e3ce508, v142
	v_rcp_f32_e32 v156, v142
	v_lshl_add_u64 v[142:143], s[10:11], 0, v[150:151]
	global_load_dwordx4 v[150:153], v[142:143], off
	v_and_b32_e32 v144, 0xffff0000, v144
	v_pk_mul_f32 v[48:49], v[48:49], v[138:139]
	v_lshlrev_b32_e32 v138, 16, v140
	v_and_b32_e32 v139, 0xffff0000, v140
	v_lshlrev_b32_e32 v140, 16, v145
	v_max_f32_e32 v144, v144, v144
	v_max_f32_e32 v140, v140, v140
	v_max_f32_e32 v144, 0x1e3ce508, v144
	v_max_f32_e32 v140, 0x1e3ce508, v140
	v_rcp_f32_e32 v157, v144
	v_rcp_f32_e32 v144, v140
	v_and_b32_e32 v140, 0xffff0000, v145
	v_max_f32_e32 v140, v140, v140
	v_max_f32_e32 v140, 0x1e3ce508, v140
	v_rcp_f32_e32 v145, v140
	s_waitcnt vmcnt(3)
; __device__ __forceinline__ float bf_lo(unsigned w) { return __uint_as_float(w << 16); }
; __device__ __forceinline__ float bf_hi(unsigned w) { return __uint_as_float(w & 0xffff0000u); }
;     __device__ __forceinline__ void mid(f32x4 (&acc)[2][2][4][2], const Unit& u, int wr, int wc, int fr, int fq) const {
;     ...
;             for (int m = 0; m < 4; ++m) { const size_t off = (size_t)(row0 + ai * HALF + m * 16) * 4096 + col0;
; #pragma unroll
;                 for (int bj = 0; bj < 2; ++bj) { const u32x4 ga = *(const u32x4*)(SGA + off + bj * HALF), gb = *(const u32x4*)(SGB + off + bj * HALF);
;                     const unsigned wa[4] = {ga.x, ga.y, ga.z, ga.w}, wb[4] = {gb.x, gb.y, gb.z, gb.w};
; #pragma unroll
;                     for (int p = 0; p < 4; ++p) { const float rl = bf_lo(wa[p]) * __builtin_amdgcn_rcpf(fmaxf(bf_lo(wb[p]), 1e-20f)), rh = bf_hi(wa[p]) * __builtin_amdgcn_rcpf(fmaxf(bf_hi(wb[p]), 1e-20f));
;                         acc[ai][bj][m][p >> 1][(p & 1) * 2] *= rl; acc[ai][bj][m][p >> 1][(p & 1) * 2 + 1] *= rh; } }
	v_lshlrev_b32_e32 v140, 16, v118
	v_and_b32_e32 v118, 0xffff0000, v118
	v_max_f32_e32 v140, v140, v140
	v_max_f32_e32 v118, v118, v118
	v_pk_mul_f32 v[138:139], v[156:157], v[138:139]
	v_max_f32_e32 v140, 0x1e3ce508, v140
	v_max_f32_e32 v118, 0x1e3ce508, v118
	v_pk_mul_f32 v[62:63], v[62:63], v[138:139]
	v_lshlrev_b32_e32 v138, 16, v141
	v_and_b32_e32 v139, 0xffff0000, v141
	v_rcp_f32_e32 v140, v140
	v_rcp_f32_e32 v141, v118
	v_pk_mul_f32 v[138:139], v[144:145], v[138:139]
	global_load_dwordx4 v[142:145], v[142:143], off offset:256
	v_pk_mul_f32 v[64:65], v[64:65], v[138:139]
	s_waitcnt vmcnt(3)
	v_lshlrev_b32_e32 v138, 16, v134
	v_and_b32_e32 v139, 0xffff0000, v134
	v_pk_mul_f32 v[138:139], v[140:141], v[138:139]
	v_lshlrev_b32_e32 v118, 16, v119
	v_pk_mul_f32 v[58:59], v[58:59], v[138:139]
	global_load_dwordx4 v[138:141], v[154:155], off offset:256
	v_and_b32_e32 v119, 0xffff0000, v119
	v_max_f32_e32 v118, v118, v118
	v_max_f32_e32 v119, v119, v119
	v_max_f32_e32 v118, 0x1e3ce508, v118
	v_max_f32_e32 v119, 0x1e3ce508, v119
	v_rcp_f32_e32 v118, v118
	v_rcp_f32_e32 v119, v119
	v_lshlrev_b32_e32 v134, 16, v135
	v_and_b32_e32 v135, 0xffff0000, v135
	s_mov_b64 s[0:1], 0x60000
	v_pk_mul_f32 v[118:119], v[118:119], v[134:135]
	v_lshlrev_b32_e32 v134, 16, v136
	v_pk_mul_f32 v[60:61], v[60:61], v[118:119]
	v_lshlrev_b32_e32 v118, 16, v120
	v_and_b32_e32 v119, 0xffff0000, v120
	v_max_f32_e32 v118, v118, v118
	v_max_f32_e32 v119, v119, v119
	v_max_f32_e32 v118, 0x1e3ce508, v118
	v_max_f32_e32 v119, 0x1e3ce508, v119
	v_lshlrev_b32_e32 v120, 16, v121
	v_and_b32_e32 v121, 0xffff0000, v121
	v_rcp_f32_e32 v118, v118
	v_rcp_f32_e32 v119, v119
	v_max_f32_e32 v120, v120, v120
	v_max_f32_e32 v121, v121, v121
	v_max_f32_e32 v120, 0x1e3ce508, v120
	v_max_f32_e32 v121, 0x1e3ce508, v121
	v_rcp_f32_e32 v120, v120
	v_rcp_f32_e32 v121, v121
	v_and_b32_e32 v135, 0xffff0000, v136
	v_pk_mul_f32 v[118:119], v[118:119], v[134:135]
	s_nop 0
	v_pk_mul_f32 v[82:83], v[82:83], v[118:119]
	v_lshlrev_b32_e32 v118, 16, v137
	v_and_b32_e32 v119, 0xffff0000, v137
	v_pk_mul_f32 v[118:119], v[120:121], v[118:119]
	s_waitcnt vmcnt(3)
	v_lshlrev_b32_e32 v120, 16, v146
	v_and_b32_e32 v121, 0xffff0000, v146
	v_max_f32_e32 v120, v120, v120
	v_max_f32_e32 v121, v121, v121
	v_max_f32_e32 v120, 0x1e3ce508, v120
	v_max_f32_e32 v121, 0x1e3ce508, v121
	v_rcp_f32_e32 v120, v120
	v_rcp_f32_e32 v121, v121
	v_pk_mul_f32 v[84:85], v[84:85], v[118:119]
	s_waitcnt vmcnt(2)
	v_lshlrev_b32_e32 v118, 16, v150
	v_and_b32_e32 v119, 0xffff0000, v150
	v_pk_mul_f32 v[118:119], v[120:121], v[118:119]
	v_lshlrev_b32_e32 v150, 16, v151
	v_pk_mul_f32 v[78:79], v[78:79], v[118:119]
	v_lshlrev_b32_e32 v118, 16, v147
	v_and_b32_e32 v119, 0xffff0000, v147
	v_lshl_add_u64 v[146:147], v[162:163], 0, s[0:1]
	v_lshl_add_u64 v[120:121], s[12:13], 0, v[146:147]
	v_max_f32_e32 v118, v118, v118
	v_max_f32_e32 v119, v119, v119
	global_load_dwordx4 v[134:137], v[120:121], off
	v_max_f32_e32 v118, 0x1e3ce508, v118
	v_max_f32_e32 v119, 0x1e3ce508, v119
	v_rcp_f32_e32 v118, v118
	v_rcp_f32_e32 v119, v119
	v_and_b32_e32 v151, 0xffff0000, v151
	s_mov_b64 s[0:1], 0x120000
	v_pk_mul_f32 v[150:151], v[118:119], v[150:151]
	v_lshlrev_b32_e32 v118, 16, v148
	v_max_f32_e32 v118, v118, v118
	v_max_f32_e32 v118, 0x1e3ce508, v118
	v_rcp_f32_e32 v178, v118
	v_lshl_add_u64 v[118:119], s[10:11], 0, v[146:147]
	global_load_dwordx4 v[154:157], v[118:119], off
	v_and_b32_e32 v146, 0xffff0000, v148
	v_max_f32_e32 v146, v146, v146
	v_max_f32_e32 v146, 0x1e3ce508, v146
	v_lshlrev_b32_e32 v148, 16, v149
	v_and_b32_e32 v149, 0xffff0000, v149
	v_rcp_f32_e32 v179, v146
	v_max_f32_e32 v148, v148, v148
	v_max_f32_e32 v149, v149, v149
	v_max_f32_e32 v148, 0x1e3ce508, v148
	v_max_f32_e32 v149, 0x1e3ce508, v149
	v_rcp_f32_e32 v148, v148
	v_rcp_f32_e32 v149, v149
	v_lshlrev_b32_e32 v146, 16, v152
	v_and_b32_e32 v147, 0xffff0000, v152
	v_pk_mul_f32 v[146:147], v[178:179], v[146:147]
	v_pk_mul_f32 v[80:81], v[80:81], v[150:151]
	v_pk_mul_f32 v[90:91], v[90:91], v[146:147]
	v_lshlrev_b32_e32 v146, 16, v153
	v_and_b32_e32 v147, 0xffff0000, v153
	v_pk_mul_f32 v[146:147], v[148:149], v[146:147]
	s_waitcnt vmcnt(2)
	v_lshlrev_b32_e32 v148, 16, v138
	v_and_b32_e32 v138, 0xffff0000, v138
	v_max_f32_e32 v148, v148, v148
	v_max_f32_e32 v138, v138, v138
	v_max_f32_e32 v148, 0x1e3ce508, v148
	v_max_f32_e32 v138, 0x1e3ce508, v138
	global_load_dwordx4 v[150:153], v[120:121], off offset:256
	v_rcp_f32_e32 v148, v148
	v_rcp_f32_e32 v149, v138
	v_pk_mul_f32 v[92:93], v[92:93], v[146:147]
	v_lshlrev_b32_e32 v146, 16, v142
	v_and_b32_e32 v147, 0xffff0000, v142
	v_pk_mul_f32 v[146:147], v[148:149], v[146:147]
	v_lshlrev_b32_e32 v138, 16, v139
	v_pk_mul_f32 v[110:111], v[110:111], v[146:147]
	global_load_dwordx4 v[146:149], v[118:119], off offset:256
	v_and_b32_e32 v139, 0xffff0000, v139
	v_max_f32_e32 v138, v138, v138
	v_max_f32_e32 v139, v139, v139
	v_max_f32_e32 v138, 0x1e3ce508, v138
	v_max_f32_e32 v120, 0x1e3ce508, v139
	v_rcp_f32_e32 v138, v138
	v_rcp_f32_e32 v139, v120
	v_lshlrev_b32_e32 v120, 16, v143
	v_and_b32_e32 v121, 0xffff0000, v143
	v_and_b32_e32 v119, 0xffff0000, v140
	v_pk_mul_f32 v[120:121], v[138:139], v[120:121]
	v_lshlrev_b32_e32 v138, 16, v140
	v_max_f32_e32 v138, v138, v138
	v_max_f32_e32 v119, v119, v119
	v_max_f32_e32 v118, 0x1e3ce508, v138
	v_max_f32_e32 v119, 0x1e3ce508, v119
	v_rcp_f32_e32 v118, v118
	v_rcp_f32_e32 v119, v119
	v_pk_mul_f32 v[112:113], v[112:113], v[120:121]
	v_lshlrev_b32_e32 v120, 16, v144
	v_and_b32_e32 v121, 0xffff0000, v144
	v_pk_mul_f32 v[118:119], v[118:119], v[120:121]
	v_lshlrev_b32_e32 v120, 16, v141
	v_and_b32_e32 v121, 0xffff0000, v141
	v_max_f32_e32 v120, v120, v120
	v_max_f32_e32 v121, v121, v121
	v_max_f32_e32 v120, 0x1e3ce508, v120
	v_max_f32_e32 v121, 0x1e3ce508, v121
	v_rcp_f32_e32 v120, v120
	v_rcp_f32_e32 v121, v121
	v_pk_mul_f32 v[118:119], v[106:107], v[118:119]
	v_lshlrev_b32_e32 v106, 16, v145
	v_and_b32_e32 v107, 0xffff0000, v145
	v_pk_mul_f32 v[106:107], v[120:121], v[106:107]
	s_waitcnt vmcnt(3)
; __device__ __forceinline__ float bf_lo(unsigned w) { return __uint_as_float(w << 16); }
; __device__ __forceinline__ float bf_hi(unsigned w) { return __uint_as_float(w & 0xffff0000u); }
;     __device__ __forceinline__ void mid(f32x4 (&acc)[2][2][4][2], const Unit& u, int wr, int wc, int fr, int fq) const {
;     ...
;             for (int m = 0; m < 4; ++m) { const size_t off = (size_t)(row0 + ai * HALF + m * 16) * 4096 + col0;
; #pragma unroll
;                 for (int bj = 0; bj < 2; ++bj) { const u32x4 ga = *(const u32x4*)(SGA + off + bj * HALF), gb = *(const u32x4*)(SGB + off + bj * HALF);
;                     const unsigned wa[4] = {ga.x, ga.y, ga.z, ga.w}, wb[4] = {gb.x, gb.y, gb.z, gb.w};
; #pragma unroll
;                     for (int p = 0; p < 4; ++p) { const float rl = bf_lo(wa[p]) * __builtin_amdgcn_rcpf(fmaxf(bf_lo(wb[p]), 1e-20f)), rh = bf_hi(wa[p]) * __builtin_amdgcn_rcpf(fmaxf(bf_hi(wb[p]), 1e-20f));
;                         acc[ai][bj][m][p >> 1][(p & 1) * 2] *= rl; acc[ai][bj][m][p >> 1][(p & 1) * 2 + 1] *= rh; } }
	v_lshlrev_b32_e32 v120, 16, v134
	v_max_f32_e32 v120, v120, v120
	v_max_f32_e32 v120, 0x1e3ce508, v120
	v_rcp_f32_e32 v138, v120
	v_and_b32_e32 v120, 0xffff0000, v134
	v_max_f32_e32 v120, v120, v120
	v_max_f32_e32 v120, 0x1e3ce508, v120
	v_rcp_f32_e32 v139, v120
	v_pk_mul_f32 v[120:121], v[108:109], v[106:107]
	v_lshlrev_b32_e32 v108, 16, v135
	v_and_b32_e32 v109, 0xffff0000, v135
	v_max_f32_e32 v108, v108, v108
	v_max_f32_e32 v109, v109, v109
	v_max_f32_e32 v108, 0x1e3ce508, v108
	v_max_f32_e32 v109, 0x1e3ce508, v109
	v_rcp_f32_e32 v108, v108
	v_rcp_f32_e32 v109, v109
	s_waitcnt vmcnt(2)
	v_lshlrev_b32_e32 v106, 16, v154
	v_and_b32_e32 v107, 0xffff0000, v154
	v_pk_mul_f32 v[106:107], v[138:139], v[106:107]
	v_lshl_add_u64 v[140:141], v[162:163], 0, s[0:1]
	v_pk_mul_f32 v[106:107], v[130:131], v[106:107]
	v_lshlrev_b32_e32 v130, 16, v155
	v_and_b32_e32 v131, 0xffff0000, v155
	v_pk_mul_f32 v[108:109], v[108:109], v[130:131]
	v_lshlrev_b32_e32 v130, 16, v136
	v_and_b32_e32 v131, 0xffff0000, v136
	v_max_f32_e32 v130, v130, v130
	v_max_f32_e32 v131, v131, v131
	v_max_f32_e32 v130, 0x1e3ce508, v130
	v_max_f32_e32 v131, 0x1e3ce508, v131
	v_rcp_f32_e32 v130, v130
	v_rcp_f32_e32 v131, v131
	v_pk_mul_f32 v[108:109], v[132:133], v[108:109]
	v_lshlrev_b32_e32 v132, 16, v156
	v_and_b32_e32 v133, 0xffff0000, v156
	v_pk_mul_f32 v[130:131], v[130:131], v[132:133]
	v_lshlrev_b32_e32 v132, 16, v137
	v_and_b32_e32 v133, 0xffff0000, v137
	v_max_f32_e32 v132, v132, v132
	v_max_f32_e32 v133, v133, v133
	v_max_f32_e32 v132, 0x1e3ce508, v132
	v_max_f32_e32 v133, 0x1e3ce508, v133
	v_rcp_f32_e32 v132, v132
	v_rcp_f32_e32 v133, v133
	v_pk_mul_f32 v[114:115], v[114:115], v[130:131]
	v_lshlrev_b32_e32 v130, 16, v157
	v_and_b32_e32 v131, 0xffff0000, v157
	v_pk_mul_f32 v[130:131], v[132:133], v[130:131]
	s_waitcnt vmcnt(1)
	v_lshlrev_b32_e32 v132, 16, v150
	v_and_b32_e32 v133, 0xffff0000, v150
	v_max_f32_e32 v132, v132, v132
	v_max_f32_e32 v133, v133, v133
	v_max_f32_e32 v132, 0x1e3ce508, v132
	v_max_f32_e32 v133, 0x1e3ce508, v133
	v_rcp_f32_e32 v132, v132
	v_rcp_f32_e32 v133, v133
	v_pk_mul_f32 v[116:117], v[116:117], v[130:131]
	s_waitcnt vmcnt(0)
	v_lshlrev_b32_e32 v130, 16, v146
	v_and_b32_e32 v131, 0xffff0000, v146
	v_pk_mul_f32 v[130:131], v[132:133], v[130:131]
	v_lshlrev_b32_e32 v132, 16, v151
	v_and_b32_e32 v133, 0xffff0000, v151
	v_max_f32_e32 v132, v132, v132
	v_max_f32_e32 v133, v133, v133
	v_max_f32_e32 v132, 0x1e3ce508, v132
	v_max_f32_e32 v133, 0x1e3ce508, v133
	v_rcp_f32_e32 v132, v132
	v_rcp_f32_e32 v133, v133
	v_pk_mul_f32 v[122:123], v[122:123], v[130:131]
	v_lshlrev_b32_e32 v130, 16, v147
	v_and_b32_e32 v131, 0xffff0000, v147
	v_pk_mul_f32 v[130:131], v[132:133], v[130:131]
	v_lshlrev_b32_e32 v132, 16, v152
	v_and_b32_e32 v133, 0xffff0000, v152
	v_max_f32_e32 v132, v132, v132
	v_max_f32_e32 v133, v133, v133
	v_max_f32_e32 v132, 0x1e3ce508, v132
	v_max_f32_e32 v133, 0x1e3ce508, v133
	v_rcp_f32_e32 v132, v132
	v_rcp_f32_e32 v133, v133
	v_pk_mul_f32 v[124:125], v[124:125], v[130:131]
	v_lshlrev_b32_e32 v130, 16, v148
	v_and_b32_e32 v131, 0xffff0000, v148
	v_pk_mul_f32 v[130:131], v[132:133], v[130:131]
	v_lshlrev_b32_e32 v132, 16, v153
	v_and_b32_e32 v133, 0xffff0000, v153
	v_max_f32_e32 v132, v132, v132
	v_max_f32_e32 v133, v133, v133
	v_max_f32_e32 v132, 0x1e3ce508, v132
	v_max_f32_e32 v133, 0x1e3ce508, v133
	v_rcp_f32_e32 v132, v132
	v_rcp_f32_e32 v133, v133
	v_pk_mul_f32 v[126:127], v[126:127], v[130:131]
	v_lshlrev_b32_e32 v130, 16, v149
	v_and_b32_e32 v131, 0xffff0000, v149
	v_pk_mul_f32 v[130:131], v[132:133], v[130:131]
	v_lshl_add_u64 v[154:155], s[12:13], 0, v[140:141]
	v_pk_mul_f32 v[128:129], v[128:129], v[130:131]
	v_lshl_add_u64 v[130:131], v[162:163], 0, s[8:9]
	v_lshl_add_u64 v[132:133], s[12:13], 0, v[130:131]
	global_load_dwordx4 v[150:153], v[132:133], off
	v_lshl_add_u64 v[130:131], s[10:11], 0, v[130:131]
	global_load_dwordx4 v[146:149], v[130:131], off
	global_load_dwordx4 v[142:145], v[132:133], off offset:256
	global_load_dwordx4 v[134:137], v[130:131], off offset:256
	s_mov_b64 s[0:1], 0x140000
	s_waitcnt vmcnt(3)
	v_lshlrev_b32_e32 v130, 16, v150
	v_and_b32_e32 v131, 0xffff0000, v150
	v_max_f32_e32 v130, v130, v130
	v_max_f32_e32 v131, v131, v131
	v_max_f32_e32 v130, 0x1e3ce508, v130
	v_max_f32_e32 v131, 0x1e3ce508, v131
	v_rcp_f32_e32 v130, v130
	v_rcp_f32_e32 v131, v131
	s_waitcnt vmcnt(2)
	v_lshlrev_b32_e32 v132, 16, v146
	v_and_b32_e32 v133, 0xffff0000, v146
	v_lshlrev_b32_e32 v146, 16, v147
	v_pk_mul_f32 v[130:131], v[130:131], v[132:133]
	v_and_b32_e32 v147, 0xffff0000, v147
	v_pk_mul_f32 v[102:103], v[102:103], v[130:131]
	v_lshlrev_b32_e32 v130, 16, v151
	v_max_f32_e32 v130, v130, v130
	v_max_f32_e32 v130, 0x1e3ce508, v130
	v_rcp_f32_e32 v138, v130
	v_and_b32_e32 v130, 0xffff0000, v151
	v_max_f32_e32 v130, v130, v130
	v_max_f32_e32 v130, 0x1e3ce508, v130
	v_rcp_f32_e32 v139, v130
	global_load_dwordx4 v[130:133], v[154:155], off
	v_lshl_add_u64 v[150:151], s[10:11], 0, v[140:141]
	v_pk_mul_f32 v[146:147], v[138:139], v[146:147]
	v_lshlrev_b32_e32 v138, 16, v152
	v_max_f32_e32 v138, v138, v138
	v_max_f32_e32 v138, 0x1e3ce508, v138
	v_rcp_f32_e32 v156, v138
	global_load_dwordx4 v[138:141], v[150:151], off
	v_and_b32_e32 v152, 0xffff0000, v152
	v_pk_mul_f32 v[104:105], v[104:105], v[146:147]
	v_lshlrev_b32_e32 v146, 16, v148
	v_and_b32_e32 v147, 0xffff0000, v148
	v_lshlrev_b32_e32 v148, 16, v153
	v_max_f32_e32 v152, v152, v152
	v_max_f32_e32 v148, v148, v148
	v_max_f32_e32 v152, 0x1e3ce508, v152
	v_max_f32_e32 v148, 0x1e3ce508, v148
	v_rcp_f32_e32 v157, v152
	v_rcp_f32_e32 v152, v148
	v_and_b32_e32 v148, 0xffff0000, v153
	v_max_f32_e32 v148, v148, v148
	v_max_f32_e32 v148, 0x1e3ce508, v148
	v_rcp_f32_e32 v153, v148
	s_waitcnt vmcnt(3)
; __device__ __forceinline__ float bf_lo(unsigned w) { return __uint_as_float(w << 16); }
; __device__ __forceinline__ float bf_hi(unsigned w) { return __uint_as_float(w & 0xffff0000u); }
;     __device__ __forceinline__ void mid(f32x4 (&acc)[2][2][4][2], const Unit& u, int wr, int wc, int fr, int fq) const {
;     ...
;             for (int m = 0; m < 4; ++m) { const size_t off = (size_t)(row0 + ai * HALF + m * 16) * 4096 + col0;
; #pragma unroll
;                 for (int bj = 0; bj < 2; ++bj) { const u32x4 ga = *(const u32x4*)(SGA + off + bj * HALF), gb = *(const u32x4*)(SGB + off + bj * HALF);
;                     const unsigned wa[4] = {ga.x, ga.y, ga.z, ga.w}, wb[4] = {gb.x, gb.y, gb.z, gb.w};
; #pragma unroll
;                     for (int p = 0; p < 4; ++p) { const float rl = bf_lo(wa[p]) * __builtin_amdgcn_rcpf(fmaxf(bf_lo(wb[p]), 1e-20f)), rh = bf_hi(wa[p]) * __builtin_amdgcn_rcpf(fmaxf(bf_hi(wb[p]), 1e-20f));
;                         acc[ai][bj][m][p >> 1][(p & 1) * 2] *= rl; acc[ai][bj][m][p >> 1][(p & 1) * 2 + 1] *= rh; } }
	v_lshlrev_b32_e32 v148, 16, v142
	v_and_b32_e32 v142, 0xffff0000, v142
	v_max_f32_e32 v148, v148, v148
	v_max_f32_e32 v142, v142, v142
	v_pk_mul_f32 v[146:147], v[156:157], v[146:147]
	v_max_f32_e32 v148, 0x1e3ce508, v148
	v_max_f32_e32 v142, 0x1e3ce508, v142
	v_pk_mul_f32 v[98:99], v[98:99], v[146:147]
	v_lshlrev_b32_e32 v146, 16, v149
	v_and_b32_e32 v147, 0xffff0000, v149
	v_rcp_f32_e32 v148, v148
	v_rcp_f32_e32 v149, v142
	v_pk_mul_f32 v[146:147], v[152:153], v[146:147]
	global_load_dwordx4 v[150:153], v[150:151], off offset:256
	v_pk_mul_f32 v[100:101], v[100:101], v[146:147]
	s_waitcnt vmcnt(3)
	v_lshlrev_b32_e32 v146, 16, v134
	v_and_b32_e32 v147, 0xffff0000, v134
	v_pk_mul_f32 v[146:147], v[148:149], v[146:147]
	v_lshlrev_b32_e32 v134, 16, v143
	v_pk_mul_f32 v[94:95], v[94:95], v[146:147]
	global_load_dwordx4 v[146:149], v[154:155], off offset:256
	v_max_f32_e32 v134, v134, v134
	v_max_f32_e32 v134, 0x1e3ce508, v134
	v_rcp_f32_e32 v142, v134
	v_and_b32_e32 v134, 0xffff0000, v143
	v_max_f32_e32 v134, v134, v134
	v_max_f32_e32 v134, 0x1e3ce508, v134
	v_rcp_f32_e32 v143, v134
	v_lshlrev_b32_e32 v134, 16, v135
	v_and_b32_e32 v135, 0xffff0000, v135
	v_pk_mul_f32 v[134:135], v[142:143], v[134:135]
	s_nop 0
	v_pk_mul_f32 v[96:97], v[96:97], v[134:135]
	v_lshlrev_b32_e32 v134, 16, v144
	v_and_b32_e32 v135, 0xffff0000, v144
	v_max_f32_e32 v134, v134, v134
	v_max_f32_e32 v135, v135, v135
	v_max_f32_e32 v134, 0x1e3ce508, v134
	v_max_f32_e32 v135, 0x1e3ce508, v135
	v_rcp_f32_e32 v134, v134
	v_rcp_f32_e32 v135, v135
	v_lshlrev_b32_e32 v142, 16, v136
	v_and_b32_e32 v143, 0xffff0000, v136
	v_lshlrev_b32_e32 v136, 16, v145
	v_max_f32_e32 v136, v136, v136
	v_max_f32_e32 v136, 0x1e3ce508, v136
	v_pk_mul_f32 v[134:135], v[134:135], v[142:143]
	v_rcp_f32_e32 v142, v136
	v_and_b32_e32 v136, 0xffff0000, v145
	v_max_f32_e32 v136, v136, v136
	v_max_f32_e32 v136, 0x1e3ce508, v136
	v_rcp_f32_e32 v143, v136
	v_pk_mul_f32 v[86:87], v[86:87], v[134:135]
	v_lshlrev_b32_e32 v134, 16, v137
	v_and_b32_e32 v135, 0xffff0000, v137
	v_pk_mul_f32 v[134:135], v[142:143], v[134:135]
	s_waitcnt vmcnt(3)
	v_lshlrev_b32_e32 v136, 16, v130
	v_and_b32_e32 v130, 0xffff0000, v130
	v_max_f32_e32 v130, v130, v130
	v_max_f32_e32 v130, 0x1e3ce508, v130
	v_rcp_f32_e32 v137, v130
	v_lshlrev_b32_e32 v130, 16, v131
	v_max_f32_e32 v136, v136, v136
	v_max_f32_e32 v130, v130, v130
	v_max_f32_e32 v136, 0x1e3ce508, v136
	v_max_f32_e32 v130, 0x1e3ce508, v130
	v_rcp_f32_e32 v136, v136
	v_rcp_f32_e32 v142, v130
	v_and_b32_e32 v130, 0xffff0000, v131
	v_max_f32_e32 v130, v130, v130
	v_max_f32_e32 v130, 0x1e3ce508, v130
	v_pk_mul_f32 v[88:89], v[88:89], v[134:135]
	s_waitcnt vmcnt(2)
	v_lshlrev_b32_e32 v134, 16, v138
	v_and_b32_e32 v135, 0xffff0000, v138
	v_rcp_f32_e32 v143, v130
	v_lshl_add_u64 v[144:145], v[162:163], 0, s[0:1]
	v_pk_mul_f32 v[134:135], v[136:137], v[134:135]
	v_lshl_add_u64 v[130:131], s[12:13], 0, v[144:145]
	v_pk_mul_f32 v[74:75], v[74:75], v[134:135]
	global_load_dwordx4 v[134:137], v[130:131], off
	v_lshlrev_b32_e32 v138, 16, v139
	v_and_b32_e32 v139, 0xffff0000, v139
	v_pk_mul_f32 v[154:155], v[142:143], v[138:139]
	v_lshlrev_b32_e32 v138, 16, v132
	v_max_f32_e32 v138, v138, v138
	v_and_b32_e32 v132, 0xffff0000, v132
	v_max_f32_e32 v138, 0x1e3ce508, v138
	v_max_f32_e32 v132, v132, v132
	v_rcp_f32_e32 v156, v138
	v_lshl_add_u64 v[138:139], s[10:11], 0, v[144:145]
	v_max_f32_e32 v132, 0x1e3ce508, v132
	global_load_dwordx4 v[142:145], v[138:139], off
	v_rcp_f32_e32 v157, v132
	v_lshlrev_b32_e32 v132, 16, v133
	v_and_b32_e32 v133, 0xffff0000, v133
	v_max_f32_e32 v132, v132, v132
	v_max_f32_e32 v133, v133, v133
	v_max_f32_e32 v132, 0x1e3ce508, v132
	v_max_f32_e32 v133, 0x1e3ce508, v133
	v_rcp_f32_e32 v132, v132
	v_rcp_f32_e32 v133, v133
	v_pk_mul_f32 v[76:77], v[76:77], v[154:155]
	v_lshlrev_b32_e32 v154, 16, v140
	v_and_b32_e32 v155, 0xffff0000, v140
	v_lshlrev_b32_e32 v140, 16, v141
	v_and_b32_e32 v141, 0xffff0000, v141
	v_pk_mul_f32 v[132:133], v[132:133], v[140:141]
	s_waitcnt vmcnt(2)
	v_lshlrev_b32_e32 v140, 16, v146
	v_and_b32_e32 v141, 0xffff0000, v146
	v_max_f32_e32 v140, v140, v140
	v_max_f32_e32 v141, v141, v141
	v_max_f32_e32 v140, 0x1e3ce508, v140
	v_max_f32_e32 v141, 0x1e3ce508, v141
	v_rcp_f32_e32 v140, v140
	v_rcp_f32_e32 v141, v141
	v_pk_mul_f32 v[72:73], v[72:73], v[132:133]
	v_lshlrev_b32_e32 v132, 16, v150
	v_and_b32_e32 v133, 0xffff0000, v150
	v_pk_mul_f32 v[132:133], v[140:141], v[132:133]
	v_lshlrev_b32_e32 v140, 16, v147
	v_and_b32_e32 v141, 0xffff0000, v147
	v_max_f32_e32 v140, v140, v140
	v_max_f32_e32 v141, v141, v141
	v_max_f32_e32 v140, 0x1e3ce508, v140
	v_max_f32_e32 v141, 0x1e3ce508, v141
	v_rcp_f32_e32 v140, v140
	v_rcp_f32_e32 v141, v141
	v_pk_mul_f32 v[66:67], v[66:67], v[132:133]
	v_lshlrev_b32_e32 v132, 16, v151
	v_and_b32_e32 v133, 0xffff0000, v151
	v_pk_mul_f32 v[132:133], v[140:141], v[132:133]
	v_lshlrev_b32_e32 v140, 16, v148
	v_pk_mul_f32 v[68:69], v[68:69], v[132:133]
	global_load_dwordx4 v[130:133], v[130:131], off offset:256
	v_max_f32_e32 v140, v140, v140
	v_max_f32_e32 v140, 0x1e3ce508, v140
	v_rcp_f32_e32 v146, v140
	v_and_b32_e32 v140, 0xffff0000, v148
	v_max_f32_e32 v140, v140, v140
	v_max_f32_e32 v140, 0x1e3ce508, v140
	v_rcp_f32_e32 v147, v140
	global_load_dwordx4 v[138:141], v[138:139], off offset:256
	v_lshlrev_b32_e32 v148, 16, v149
	v_and_b32_e32 v149, 0xffff0000, v149
	v_max_f32_e32 v148, v148, v148
	v_max_f32_e32 v149, v149, v149
	v_max_f32_e32 v148, 0x1e3ce508, v148
	v_max_f32_e32 v149, 0x1e3ce508, v149
	v_rcp_f32_e32 v148, v148
	v_rcp_f32_e32 v149, v149
	v_lshlrev_b32_e32 v150, 16, v152
	v_and_b32_e32 v151, 0xffff0000, v152
	v_pk_mul_f32 v[146:147], v[146:147], v[150:151]
	s_mov_b64 s[0:1], 0x160000
	v_pk_mul_f32 v[54:55], v[54:55], v[146:147]
	v_lshlrev_b32_e32 v146, 16, v153
	v_and_b32_e32 v147, 0xffff0000, v153
	v_pk_mul_f32 v[146:147], v[148:149], v[146:147]
	v_pk_mul_f32 v[154:155], v[156:157], v[154:155]
	s_waitcnt vmcnt(3)
; __device__ __forceinline__ float bf_lo(unsigned w) { return __uint_as_float(w << 16); }
; __device__ __forceinline__ float bf_hi(unsigned w) { return __uint_as_float(w & 0xffff0000u); }
;     __device__ bool next(int i, Unit& u) const { if (i > 1) return false; const int xcd = c & 7, idx = c >> 3; u.pm = 16 * i + 4 * (xcd >> 1) + (idx & 3); u.pn = 8 * (xcd & 1) + (idx >> 2); return true; }
;     __host__ __device__ bool next(int i, Unit& u) const {
;         const long L = (long)i * G + c; if (L >= nwg) return false;
;         int wgid = (int)L; { const int q = nwg / NXCD, r = nwg % NXCD, xcd = wgid % NXCD, off = wgid / NXCD; wgid = (xcd < r ? xcd * (q + 1) : r * (q + 1) + (xcd - r) * q) + off; }
;         const int nig = WGM * nN, gid = wgid / nig, fm = gid * WGM, gsz = (nM - fm) < WGM ? (nM - fm) : WGM;
;         u.pm = fm + ((wgid % nig) % gsz); u.pn = (wgid % nig) / gsz; return true;
;     __device__ __forceinline__ void mid(f32x4 (&acc)[2][2][4][2], const Unit& u, int wr, int wc, int fr, int fq) const {
;     ...
;             for (int m = 0; m < 4; ++m) { const size_t off = (size_t)(row0 + ai * HALF + m * 16) * 4096 + col0;
; #pragma unroll
;                 for (int bj = 0; bj < 2; ++bj) { const u32x4 ga = *(const u32x4*)(SGA + off + bj * HALF), gb = *(const u32x4*)(SGB + off + bj * HALF);
;                     const unsigned wa[4] = {ga.x, ga.y, ga.z, ga.w}, wb[4] = {gb.x, gb.y, gb.z, gb.w};
; #pragma unroll
;                     for (int p = 0; p < 4; ++p) { const float rl = bf_lo(wa[p]) * __builtin_amdgcn_rcpf(fmaxf(bf_lo(wb[p]), 1e-20f)), rh = bf_hi(wa[p]) * __builtin_amdgcn_rcpf(fmaxf(bf_hi(wb[p]), 1e-20f));
;                         acc[ai][bj][m][p >> 1][(p & 1) * 2] *= rl; acc[ai][bj][m][p >> 1][(p & 1) * 2 + 1] *= rh; } }
	v_lshlrev_b32_e32 v148, 16, v134
	v_and_b32_e32 v134, 0xffff0000, v134
	v_max_f32_e32 v148, v148, v148
	v_max_f32_e32 v134, v134, v134
	v_max_f32_e32 v148, 0x1e3ce508, v148
	v_max_f32_e32 v134, 0x1e3ce508, v134
	v_rcp_f32_e32 v148, v148
	v_rcp_f32_e32 v149, v134
	v_pk_mul_f32 v[56:57], v[56:57], v[146:147]
	v_lshl_add_u64 v[150:151], v[162:163], 0, s[0:1]
	v_pk_mul_f32 v[70:71], v[70:71], v[154:155]
	v_lshlrev_b32_e32 v134, 16, v135
	s_waitcnt vmcnt(2)
	v_lshlrev_b32_e32 v146, 16, v142
	v_and_b32_e32 v147, 0xffff0000, v142
	v_pk_mul_f32 v[146:147], v[148:149], v[146:147]
	v_and_b32_e32 v135, 0xffff0000, v135
	v_lshl_add_u64 v[154:155], s[12:13], 0, v[150:151]
	v_pk_mul_f32 v[42:43], v[42:43], v[146:147]
	v_max_f32_e32 v134, v134, v134
	v_max_f32_e32 v135, v135, v135
	global_load_dwordx4 v[146:149], v[154:155], off
	v_max_f32_e32 v134, 0x1e3ce508, v134
	v_max_f32_e32 v135, 0x1e3ce508, v135
	v_rcp_f32_e32 v134, v134
	v_rcp_f32_e32 v135, v135
	v_lshlrev_b32_e32 v142, 16, v143
	v_and_b32_e32 v143, 0xffff0000, v143
	s_mul_i32 s0, s50, s63
	v_pk_mul_f32 v[142:143], v[134:135], v[142:143]
	v_lshlrev_b32_e32 v134, 16, v136
	v_max_f32_e32 v134, v134, v134
	v_max_f32_e32 v134, 0x1e3ce508, v134
	v_rcp_f32_e32 v156, v134
	v_lshl_add_u64 v[134:135], s[10:11], 0, v[150:151]
	global_load_dwordx4 v[150:153], v[134:135], off
	v_and_b32_e32 v136, 0xffff0000, v136
	v_max_f32_e32 v136, v136, v136
	v_max_f32_e32 v136, 0x1e3ce508, v136
	v_rcp_f32_e32 v157, v136
	v_lshlrev_b32_e32 v136, 16, v137
	v_and_b32_e32 v137, 0xffff0000, v137
	v_max_f32_e32 v136, v136, v136
	v_max_f32_e32 v137, v137, v137
	v_max_f32_e32 v136, 0x1e3ce508, v136
	v_max_f32_e32 v137, 0x1e3ce508, v137
	v_rcp_f32_e32 v136, v136
	v_rcp_f32_e32 v137, v137
	v_pk_mul_f32 v[44:45], v[44:45], v[142:143]
	v_lshlrev_b32_e32 v142, 16, v144
	v_and_b32_e32 v143, 0xffff0000, v144
	v_pk_mul_f32 v[142:143], v[156:157], v[142:143]
	s_mul_hi_u32 s1, s50, s2
	v_pk_mul_f32 v[38:39], v[38:39], v[142:143]
	v_lshlrev_b32_e32 v142, 16, v145
	v_and_b32_e32 v143, 0xffff0000, v145
	v_pk_mul_f32 v[136:137], v[136:137], v[142:143]
	s_waitcnt vmcnt(3)
	v_lshlrev_b32_e32 v142, 16, v130
	v_and_b32_e32 v130, 0xffff0000, v130
	v_max_f32_e32 v142, v142, v142
	v_max_f32_e32 v130, v130, v130
	v_max_f32_e32 v142, 0x1e3ce508, v142
	v_max_f32_e32 v130, 0x1e3ce508, v130
	v_rcp_f32_e32 v142, v142
	v_rcp_f32_e32 v143, v130
	v_lshlrev_b32_e32 v130, 16, v131
	v_and_b32_e32 v131, 0xffff0000, v131
	v_pk_mul_f32 v[40:41], v[40:41], v[136:137]
	s_waitcnt vmcnt(2)
	v_lshlrev_b32_e32 v136, 16, v138
	v_and_b32_e32 v137, 0xffff0000, v138
	v_max_f32_e32 v130, v130, v130
	v_max_f32_e32 v131, v131, v131
	v_pk_mul_f32 v[136:137], v[142:143], v[136:137]
	v_max_f32_e32 v130, 0x1e3ce508, v130
	global_load_dwordx4 v[142:145], v[154:155], off offset:256
	v_max_f32_e32 v131, 0x1e3ce508, v131
	v_rcp_f32_e32 v130, v130
	v_rcp_f32_e32 v131, v131
	v_pk_mul_f32 v[22:23], v[22:23], v[136:137]
	v_lshlrev_b32_e32 v136, 16, v139
	v_and_b32_e32 v137, 0xffff0000, v139
	v_pk_mul_f32 v[130:131], v[130:131], v[136:137]
	v_lshlrev_b32_e32 v136, 16, v132
	v_max_f32_e32 v138, v136, v136
	global_load_dwordx4 v[134:137], v[134:135], off offset:256
	v_and_b32_e32 v132, 0xffff0000, v132
	v_max_f32_e32 v132, v132, v132
	v_max_f32_e32 v132, 0x1e3ce508, v132
	v_max_f32_e32 v138, 0x1e3ce508, v138
	v_rcp_f32_e32 v139, v132
	v_lshlrev_b32_e32 v132, 16, v133
	v_and_b32_e32 v133, 0xffff0000, v133
	v_rcp_f32_e32 v138, v138
	v_max_f32_e32 v132, v132, v132
	v_max_f32_e32 v133, v133, v133
	v_max_f32_e32 v132, 0x1e3ce508, v132
	v_max_f32_e32 v133, 0x1e3ce508, v133
	v_rcp_f32_e32 v132, v132
	v_rcp_f32_e32 v133, v133
	v_pk_mul_f32 v[24:25], v[24:25], v[130:131]
	v_lshlrev_b32_e32 v130, 16, v140
	v_and_b32_e32 v131, 0xffff0000, v140
	v_pk_mul_f32 v[130:131], v[138:139], v[130:131]
	s_add_i32 s1, s1, s0
	v_pk_mul_f32 v[130:131], v[14:15], v[130:131]
	v_lshlrev_b32_e32 v14, 16, v141
	v_and_b32_e32 v15, 0xffff0000, v141
	v_pk_mul_f32 v[14:15], v[132:133], v[14:15]
	s_waitcnt vmcnt(3)
; __device__ __forceinline__ float bf_lo(unsigned w) { return __uint_as_float(w << 16); }
; __device__ __forceinline__ float bf_hi(unsigned w) { return __uint_as_float(w & 0xffff0000u); }
;     __host__ __device__ bool next(int i, Unit& u) const {
;         const long L = (long)i * G + c; if (L >= nwg) return false;
;         int wgid = (int)L; { const int q = nwg / NXCD, r = nwg % NXCD, xcd = wgid % NXCD, off = wgid / NXCD; wgid = (xcd < r ? xcd * (q + 1) : r * (q + 1) + (xcd - r) * q) + off; }
;         const int nig = WGM * nN, gid = wgid / nig, fm = gid * WGM, gsz = (nM - fm) < WGM ? (nM - fm) : WGM;
;         u.pm = fm + ((wgid % nig) % gsz); u.pn = (wgid % nig) / gsz; return true;
;     __device__ __forceinline__ void mid(f32x4 (&acc)[2][2][4][2], const Unit& u, int wr, int wc, int fr, int fq) const {
;     ...
;                 for (int bj = 0; bj < 2; ++bj) { const u32x4 ga = *(const u32x4*)(SGA + off + bj * HALF), gb = *(const u32x4*)(SGB + off + bj * HALF);
;                     const unsigned wa[4] = {ga.x, ga.y, ga.z, ga.w}, wb[4] = {gb.x, gb.y, gb.z, gb.w};
; #pragma unroll
;                     for (int p = 0; p < 4; ++p) { const float rl = bf_lo(wa[p]) * __builtin_amdgcn_rcpf(fmaxf(bf_lo(wb[p]), 1e-20f)), rh = bf_hi(wa[p]) * __builtin_amdgcn_rcpf(fmaxf(bf_hi(wb[p]), 1e-20f));
;                         acc[ai][bj][m][p >> 1][(p & 1) * 2] *= rl; acc[ai][bj][m][p >> 1][(p & 1) * 2 + 1] *= rh; } }
	v_lshlrev_b32_e32 v132, 16, v146
	v_max_f32_e32 v132, v132, v132
	v_max_f32_e32 v132, 0x1e3ce508, v132
	v_rcp_f32_e32 v138, v132
	v_and_b32_e32 v132, 0xffff0000, v146
	v_max_f32_e32 v132, v132, v132
	v_max_f32_e32 v132, 0x1e3ce508, v132
	v_rcp_f32_e32 v139, v132
	v_pk_mul_f32 v[132:133], v[16:17], v[14:15]
	v_lshlrev_b32_e32 v16, 16, v147
	v_and_b32_e32 v17, 0xffff0000, v147
	v_max_f32_e32 v16, v16, v16
	v_max_f32_e32 v17, v17, v17
	v_max_f32_e32 v16, 0x1e3ce508, v16
	v_max_f32_e32 v17, 0x1e3ce508, v17
	v_rcp_f32_e32 v16, v16
	v_rcp_f32_e32 v17, v17
	s_waitcnt vmcnt(2)
	v_lshlrev_b32_e32 v14, 16, v150
	v_and_b32_e32 v15, 0xffff0000, v150
	v_pk_mul_f32 v[14:15], v[138:139], v[14:15]
	s_mul_i32 s0, s50, s2
	v_pk_mul_f32 v[14:15], v[18:19], v[14:15]
	v_lshlrev_b32_e32 v18, 16, v151
	v_and_b32_e32 v19, 0xffff0000, v151
	v_pk_mul_f32 v[16:17], v[16:17], v[18:19]
	v_lshlrev_b32_e32 v18, 16, v148
	v_and_b32_e32 v19, 0xffff0000, v148
	v_max_f32_e32 v18, v18, v18
	v_max_f32_e32 v19, v19, v19
	v_max_f32_e32 v18, 0x1e3ce508, v18
	v_max_f32_e32 v19, 0x1e3ce508, v19
	v_rcp_f32_e32 v18, v18
	v_rcp_f32_e32 v19, v19
	v_pk_mul_f32 v[16:17], v[20:21], v[16:17]
	v_lshlrev_b32_e32 v20, 16, v152
	v_and_b32_e32 v21, 0xffff0000, v152
	v_pk_mul_f32 v[18:19], v[18:19], v[20:21]
	v_lshlrev_b32_e32 v20, 16, v149
	v_and_b32_e32 v21, 0xffff0000, v149
	v_max_f32_e32 v20, v20, v20
	v_max_f32_e32 v21, v21, v21
	v_max_f32_e32 v20, 0x1e3ce508, v20
	v_max_f32_e32 v21, 0x1e3ce508, v21
	v_rcp_f32_e32 v20, v20
	v_rcp_f32_e32 v21, v21
	v_pk_mul_f32 v[10:11], v[10:11], v[18:19]
	v_lshlrev_b32_e32 v18, 16, v153
	v_and_b32_e32 v19, 0xffff0000, v153
	v_pk_mul_f32 v[18:19], v[20:21], v[18:19]
	s_waitcnt vmcnt(1)
	v_lshlrev_b32_e32 v20, 16, v142
	v_and_b32_e32 v21, 0xffff0000, v142
	v_max_f32_e32 v20, v20, v20
	v_max_f32_e32 v21, v21, v21
	v_max_f32_e32 v20, 0x1e3ce508, v20
	v_max_f32_e32 v21, 0x1e3ce508, v21
	v_rcp_f32_e32 v20, v20
	v_rcp_f32_e32 v21, v21
	v_pk_mul_f32 v[12:13], v[12:13], v[18:19]
	s_waitcnt vmcnt(0)
	v_lshlrev_b32_e32 v18, 16, v134
	v_and_b32_e32 v19, 0xffff0000, v134
	v_pk_mul_f32 v[18:19], v[20:21], v[18:19]
	v_lshlrev_b32_e32 v20, 16, v143
	v_and_b32_e32 v21, 0xffff0000, v143
	v_max_f32_e32 v20, v20, v20
	v_max_f32_e32 v21, v21, v21
	v_max_f32_e32 v20, 0x1e3ce508, v20
	v_max_f32_e32 v21, 0x1e3ce508, v21
	v_rcp_f32_e32 v20, v20
	v_rcp_f32_e32 v21, v21
	v_pk_mul_f32 v[6:7], v[6:7], v[18:19]
	v_lshlrev_b32_e32 v18, 16, v135
	v_and_b32_e32 v19, 0xffff0000, v135
	v_pk_mul_f32 v[18:19], v[20:21], v[18:19]
	v_lshlrev_b32_e32 v20, 16, v144
	v_and_b32_e32 v21, 0xffff0000, v144
	v_max_f32_e32 v20, v20, v20
	v_max_f32_e32 v21, v21, v21
	v_max_f32_e32 v20, 0x1e3ce508, v20
	v_max_f32_e32 v21, 0x1e3ce508, v21
	v_rcp_f32_e32 v20, v20
	v_rcp_f32_e32 v21, v21
	v_pk_mul_f32 v[8:9], v[8:9], v[18:19]
	v_lshlrev_b32_e32 v18, 16, v136
	v_and_b32_e32 v19, 0xffff0000, v136
	v_pk_mul_f32 v[18:19], v[20:21], v[18:19]
	v_lshlrev_b32_e32 v20, 16, v145
	v_and_b32_e32 v21, 0xffff0000, v145
	v_max_f32_e32 v20, v20, v20
	v_max_f32_e32 v21, v21, v21
	v_max_f32_e32 v20, 0x1e3ce508, v20
	v_max_f32_e32 v21, 0x1e3ce508, v21
	v_rcp_f32_e32 v20, v20
	v_rcp_f32_e32 v21, v21
	v_pk_mul_f32 v[2:3], v[2:3], v[18:19]
	v_lshlrev_b32_e32 v18, 16, v137
	v_and_b32_e32 v19, 0xffff0000, v137
	v_pk_mul_f32 v[18:19], v[20:21], v[18:19]
	v_readlane_b32 s2, v238, 44
	v_pk_mul_f32 v[4:5], v[4:5], v[18:19]
	s_add_u32 s2, s0, s2
	s_addc_u32 s3, s1, s28
	v_cmp_gt_i64_e32 vcc, s[2:3], v[160:161]
	v_cmp_lt_i64_e64 s[0:1], s[2:3], v[158:159]
	s_cbranch_vccnz .LBB0_753
	s_ashr_i32 s3, s2, 31
	s_lshr_b32 s3, s3, 29
	s_add_i32 s4, s2, s3
	s_and_b32 s3, s4, -8
	s_sub_i32 s5, s2, s3
	s_cmp_gt_i32 s5, -1
	s_mov_b64 s[2:3], -1
	s_cbranch_scc0 .LBB0_750
	s_lshl_b32 s16, s5, 6
	s_mov_b64 s[2:3], 0

.LBB0_754:
	ds_read_b128 v[18:21], v172
	ds_read_b128 v[134:137], v172 offset:1024
	ds_read_b128 v[138:141], v172 offset:2048
	ds_read_b128 v[142:145], v172 offset:3072
	ds_read_b128 v[146:149], v173
	ds_read_b128 v[150:153], v173 offset:1024
	ds_read_b128 v[154:157], v173 offset:2048
	ds_read_b128 v[178:181], v173 offset:3072
	s_add_u32 s2, s30, 0x100
	s_addc_u32 s3, s31, 0
	s_cmp_eq_u32 s37, 60
	s_cselect_b32 s26, s33, s2
	s_cselect_b32 s27, s5, s3
	s_cselect_b32 s24, s36, s34
	s_cselect_b32 s25, s21, s35
	s_add_u32 s16, s26, 0x80
	s_addc_u32 s17, s27, 0
	s_add_u32 s30, s30, 0x100080
	s_addc_u32 s31, s31, 0
	s_mov_b32 m0, s76
	ds_read_b128 v[182:185], v174
	ds_read_b128 v[186:189], v174 offset:1024
	ds_read_b128 v[190:193], v174 offset:2048
	ds_read_b128 v[194:197], v174 offset:3072
	ds_read_b128 v[198:201], v174 offset:4096
	ds_read_b128 v[202:205], v174 offset:5120
	ds_read_b128 v[206:209], v174 offset:6144
	ds_read_b128 v[210:213], v174 offset:7168
	s_nop 0
	global_load_lds_dwordx4 v1, s[30:31]
	s_mov_b32 m0, s77
	s_nop 0
	global_load_lds_dwordx4 v165, s[30:31]
	s_nop 0
	s_nop 0
	s_setprio 1
	s_waitcnt vmcnt(8) lgkmcnt(0)
	s_barrier
	v_mfma_f32_16x16x32_bf16 v[34:37], v[18:21], v[182:185], v[34:37]
	v_mfma_f32_16x16x32_bf16 v[30:33], v[138:141], v[182:185], v[30:33]
	v_mfma_f32_16x16x32_bf16 v[46:49], v[18:21], v[190:193], v[46:49]
	v_mfma_f32_16x16x32_bf16 v[62:65], v[138:141], v[190:193], v[62:65]
	v_mfma_f32_16x16x32_bf16 v[78:81], v[18:21], v[198:201], v[78:81]
	v_mfma_f32_16x16x32_bf16 v[90:93], v[138:141], v[198:201], v[90:93]
	v_mfma_f32_16x16x32_bf16 v[106:109], v[18:21], v[206:209], v[106:109]
	v_mfma_f32_16x16x32_bf16 v[114:117], v[138:141], v[206:209], v[114:117]
	v_mfma_f32_16x16x32_bf16 v[26:29], v[146:149], v[182:185], v[26:29]
	v_mfma_f32_16x16x32_bf16 v[50:53], v[154:157], v[182:185], v[50:53]
	v_mfma_f32_16x16x32_bf16 v[58:61], v[146:149], v[190:193], v[58:61]
	v_mfma_f32_16x16x32_bf16 v[82:85], v[154:157], v[190:193], v[82:85]
	v_mfma_f32_16x16x32_bf16 v[110:113], v[146:149], v[198:201], v[110:113]
	v_mfma_f32_16x16x32_bf16 v[118:121], v[154:157], v[198:201], v[118:121]
	v_mfma_f32_16x16x32_bf16 v[122:125], v[146:149], v[206:209], v[122:125]
	v_mfma_f32_16x16x32_bf16 v[126:129], v[154:157], v[206:209], v[126:129]
	v_mfma_f32_16x16x32_bf16 v[34:37], v[134:137], v[186:189], v[34:37]
	v_mfma_f32_16x16x32_bf16 v[30:33], v[142:145], v[186:189], v[30:33]
	v_mfma_f32_16x16x32_bf16 v[46:49], v[134:137], v[194:197], v[46:49]
	v_mfma_f32_16x16x32_bf16 v[62:65], v[142:145], v[194:197], v[62:65]
	v_mfma_f32_16x16x32_bf16 v[78:81], v[134:137], v[202:205], v[78:81]
	v_mfma_f32_16x16x32_bf16 v[90:93], v[142:145], v[202:205], v[90:93]
	v_mfma_f32_16x16x32_bf16 v[106:109], v[134:137], v[210:213], v[106:109]
	v_mfma_f32_16x16x32_bf16 v[114:117], v[142:145], v[210:213], v[114:117]
	v_mfma_f32_16x16x32_bf16 v[26:29], v[150:153], v[186:189], v[26:29]
	v_mfma_f32_16x16x32_bf16 v[50:53], v[178:181], v[186:189], v[50:53]
	v_mfma_f32_16x16x32_bf16 v[58:61], v[150:153], v[194:197], v[58:61]
	v_mfma_f32_16x16x32_bf16 v[82:85], v[178:181], v[194:197], v[82:85]
	v_mfma_f32_16x16x32_bf16 v[110:113], v[150:153], v[202:205], v[110:113]
	v_mfma_f32_16x16x32_bf16 v[118:121], v[178:181], v[202:205], v[118:121]
	v_mfma_f32_16x16x32_bf16 v[122:125], v[150:153], v[210:213], v[122:125]
	v_mfma_f32_16x16x32_bf16 v[126:129], v[178:181], v[210:213], v[126:129]
	s_setprio 0
	s_barrier
	s_mov_b32 m0, s80
	s_mov_b64 s[30:31], s[24:25]
	ds_read_b128 v[182:185], v174 offset:16384
	ds_read_b128 v[186:189], v174 offset:17408
	ds_read_b128 v[190:193], v174 offset:18432
	ds_read_b128 v[194:197], v174 offset:19456
	ds_read_b128 v[198:201], v174 offset:20480
	ds_read_b128 v[202:205], v174 offset:21504
	ds_read_b128 v[206:209], v174 offset:22528
	ds_read_b128 v[210:213], v174 offset:23552
	s_nop 0
	global_load_lds_dwordx4 v164, s[30:31]
	s_mov_b32 m0, s81
	s_nop 0
	global_load_lds_dwordx4 v166, s[30:31]
	s_add_u32 s30, s24, 0x100000
	s_addc_u32 s31, s25, 0
	s_mov_b32 m0, s82
	s_nop 0
	global_load_lds_dwordx4 v164, s[30:31]
	s_mov_b32 m0, s83
	s_nop 0
	global_load_lds_dwordx4 v166, s[30:31]
	s_mov_b64 s[30:31], s[26:27]
	s_mov_b32 m0, s46
	s_nop 0
	global_load_lds_dwordx4 v1, s[30:31]
	s_mov_b32 m0, s47
	s_nop 0
	global_load_lds_dwordx4 v165, s[30:31]
	s_nop 0
	s_nop 0
	s_setprio 1
	s_waitcnt vmcnt(8) lgkmcnt(0)
	s_barrier
	v_mfma_f32_16x16x32_bf16 v[102:105], v[18:21], v[182:185], v[102:105]
	v_mfma_f32_16x16x32_bf16 v[98:101], v[138:141], v[182:185], v[98:101]
	v_mfma_f32_16x16x32_bf16 v[74:77], v[18:21], v[190:193], v[74:77]
	v_mfma_f32_16x16x32_bf16 v[70:73], v[138:141], v[190:193], v[70:73]
	v_mfma_f32_16x16x32_bf16 v[42:45], v[18:21], v[198:201], v[42:45]
	v_mfma_f32_16x16x32_bf16 v[38:41], v[138:141], v[198:201], v[38:41]
	v_mfma_f32_16x16x32_bf16 v[14:17], v[18:21], v[206:209], v[14:17]
	v_mfma_f32_16x16x32_bf16 v[10:13], v[138:141], v[206:209], v[10:13]
	v_mfma_f32_16x16x32_bf16 v[18:21], v[146:149], v[182:185], v[94:97]
	v_mfma_f32_16x16x32_bf16 v[86:89], v[154:157], v[182:185], v[86:89]
	v_mfma_f32_16x16x32_bf16 v[66:69], v[146:149], v[190:193], v[66:69]
	v_mfma_f32_16x16x32_bf16 v[54:57], v[154:157], v[190:193], v[54:57]
	v_mfma_f32_16x16x32_bf16 v[22:25], v[146:149], v[198:201], v[22:25]
	v_mfma_f32_16x16x32_bf16 v[94:97], v[154:157], v[198:201], v[130:133]
	v_mfma_f32_16x16x32_bf16 v[6:9], v[146:149], v[206:209], v[6:9]
	v_mfma_f32_16x16x32_bf16 v[2:5], v[154:157], v[206:209], v[2:5]
	v_mfma_f32_16x16x32_bf16 v[102:105], v[134:137], v[186:189], v[102:105]
	v_mfma_f32_16x16x32_bf16 v[98:101], v[142:145], v[186:189], v[98:101]
	v_mfma_f32_16x16x32_bf16 v[74:77], v[134:137], v[194:197], v[74:77]
	v_mfma_f32_16x16x32_bf16 v[70:73], v[142:145], v[194:197], v[70:73]
	v_mfma_f32_16x16x32_bf16 v[42:45], v[134:137], v[202:205], v[42:45]
	v_mfma_f32_16x16x32_bf16 v[38:41], v[142:145], v[202:205], v[38:41]
	v_mfma_f32_16x16x32_bf16 v[14:17], v[134:137], v[210:213], v[14:17]
	v_mfma_f32_16x16x32_bf16 v[10:13], v[142:145], v[210:213], v[10:13]
	v_mfma_f32_16x16x32_bf16 v[86:89], v[178:181], v[186:189], v[86:89]
	v_mfma_f32_16x16x32_bf16 v[66:69], v[150:153], v[194:197], v[66:69]
	v_mfma_f32_16x16x32_bf16 v[54:57], v[178:181], v[194:197], v[54:57]
	v_mfma_f32_16x16x32_bf16 v[22:25], v[150:153], v[202:205], v[22:25]
	v_mfma_f32_16x16x32_bf16 v[130:133], v[178:181], v[202:205], v[94:97]
	v_mfma_f32_16x16x32_bf16 v[6:9], v[150:153], v[210:213], v[6:9]
	v_mfma_f32_16x16x32_bf16 v[2:5], v[178:181], v[210:213], v[2:5]
	v_mfma_f32_16x16x32_bf16 v[18:21], v[150:153], v[186:189], v[18:21]
	s_setprio 0
	s_barrier
; #define PG8_BAR __builtin_amdgcn_s_barrier()
; #define PG8_BAR __builtin_amdgcn_s_barrier()
; template <class Epi, class Sched>
; __device__ __forceinline__ void gemm_phase_dual(PG8_LAS unsigned char* lds, const Gemm g  , const bf16_t* A0, const bf16_t* Bt0, int K0, const Sched& S, const Epi& E) {
;     ...
;         if (wr == 0) PG8_BAR;
	ds_read_b128 v[94:97], v175
	ds_read_b128 v[134:137], v175 offset:1024
	ds_read_b128 v[138:141], v175 offset:2048
	ds_read_b128 v[142:145], v175 offset:3072
	ds_read_b128 v[146:149], v176
	ds_read_b128 v[150:153], v176 offset:1024
	ds_read_b128 v[154:157], v176 offset:2048
	ds_read_b128 v[178:181], v176 offset:3072
	s_add_u32 s26, s26, 0x100000
	s_addc_u32 s27, s27, 0
	s_mov_b32 m0, s48
	ds_read_b128 v[182:185], v174 offset:32768
	ds_read_b128 v[186:189], v174 offset:33792
	ds_read_b128 v[190:193], v174 offset:34816
	ds_read_b128 v[194:197], v174 offset:35840
	ds_read_b128 v[198:201], v174 offset:36864
	ds_read_b128 v[202:205], v174 offset:37888
	ds_read_b128 v[206:209], v174 offset:38912
	ds_read_b128 v[210:213], v174 offset:39936
	s_nop 0
	global_load_lds_dwordx4 v1, s[26:27]
	s_mov_b32 m0, s49
	s_nop 0
	global_load_lds_dwordx4 v165, s[26:27]
	s_nop 0
	s_nop 0
	s_setprio 1
	s_waitcnt vmcnt(8) lgkmcnt(0)
	s_barrier
	v_mfma_f32_16x16x32_bf16 v[34:37], v[94:97], v[182:185], v[34:37]
	v_mfma_f32_16x16x32_bf16 v[30:33], v[138:141], v[182:185], v[30:33]
	v_mfma_f32_16x16x32_bf16 v[46:49], v[94:97], v[190:193], v[46:49]
	v_mfma_f32_16x16x32_bf16 v[62:65], v[138:141], v[190:193], v[62:65]
	v_mfma_f32_16x16x32_bf16 v[78:81], v[94:97], v[198:201], v[78:81]
	v_mfma_f32_16x16x32_bf16 v[90:93], v[138:141], v[198:201], v[90:93]
	v_mfma_f32_16x16x32_bf16 v[106:109], v[94:97], v[206:209], v[106:109]
	v_mfma_f32_16x16x32_bf16 v[114:117], v[138:141], v[206:209], v[114:117]
	v_mfma_f32_16x16x32_bf16 v[26:29], v[146:149], v[182:185], v[26:29]
	v_mfma_f32_16x16x32_bf16 v[50:53], v[154:157], v[182:185], v[50:53]
	v_mfma_f32_16x16x32_bf16 v[58:61], v[146:149], v[190:193], v[58:61]
	v_mfma_f32_16x16x32_bf16 v[82:85], v[154:157], v[190:193], v[82:85]
	v_mfma_f32_16x16x32_bf16 v[110:113], v[146:149], v[198:201], v[110:113]
	v_mfma_f32_16x16x32_bf16 v[118:121], v[154:157], v[198:201], v[118:121]
	v_mfma_f32_16x16x32_bf16 v[122:125], v[146:149], v[206:209], v[122:125]
	v_mfma_f32_16x16x32_bf16 v[126:129], v[154:157], v[206:209], v[126:129]
	v_mfma_f32_16x16x32_bf16 v[34:37], v[134:137], v[186:189], v[34:37]
	v_mfma_f32_16x16x32_bf16 v[30:33], v[142:145], v[186:189], v[30:33]
	v_mfma_f32_16x16x32_bf16 v[46:49], v[134:137], v[194:197], v[46:49]
	v_mfma_f32_16x16x32_bf16 v[62:65], v[142:145], v[194:197], v[62:65]
	v_mfma_f32_16x16x32_bf16 v[78:81], v[134:137], v[202:205], v[78:81]
	v_mfma_f32_16x16x32_bf16 v[90:93], v[142:145], v[202:205], v[90:93]
	v_mfma_f32_16x16x32_bf16 v[106:109], v[134:137], v[210:213], v[106:109]
	v_mfma_f32_16x16x32_bf16 v[114:117], v[142:145], v[210:213], v[114:117]
	v_mfma_f32_16x16x32_bf16 v[26:29], v[150:153], v[186:189], v[26:29]
	v_mfma_f32_16x16x32_bf16 v[50:53], v[178:181], v[186:189], v[50:53]
	v_mfma_f32_16x16x32_bf16 v[58:61], v[150:153], v[194:197], v[58:61]
	v_mfma_f32_16x16x32_bf16 v[82:85], v[178:181], v[194:197], v[82:85]
	v_mfma_f32_16x16x32_bf16 v[110:113], v[150:153], v[202:205], v[110:113]
	v_mfma_f32_16x16x32_bf16 v[118:121], v[178:181], v[202:205], v[118:121]
	v_mfma_f32_16x16x32_bf16 v[122:125], v[150:153], v[210:213], v[122:125]
	v_mfma_f32_16x16x32_bf16 v[126:129], v[178:181], v[210:213], v[126:129]
	s_setprio 0
	s_barrier
	s_add_u32 s26, s24, 0x80
	s_mov_b32 m0, s84
	s_addc_u32 s27, s25, 0
	ds_read_b128 v[182:185], v174 offset:49152
	ds_read_b128 v[186:189], v174 offset:50176
	ds_read_b128 v[190:193], v174 offset:51200
	ds_read_b128 v[194:197], v174 offset:52224
	ds_read_b128 v[198:201], v174 offset:53248
	ds_read_b128 v[202:205], v174 offset:54272
	ds_read_b128 v[206:209], v174 offset:55296
	ds_read_b128 v[210:213], v174 offset:56320
	s_add_u32 s24, s24, 0x100080
	global_load_lds_dwordx4 v164, s[26:27]
	s_mov_b32 m0, s85
	s_addc_u32 s25, s25, 0
	global_load_lds_dwordx4 v166, s[26:27]
	s_mov_b32 m0, s86
	s_nop 0
	global_load_lds_dwordx4 v164, s[24:25]
	s_mov_b32 m0, s87
	s_nop 0
	global_load_lds_dwordx4 v166, s[24:25]
	s_mov_b32 m0, s57
	s_nop 0
	global_load_lds_dwordx4 v1, s[16:17]
	s_mov_b32 m0, s62
	s_nop 0
	global_load_lds_dwordx4 v165, s[16:17]
	s_nop 0
	s_nop 0
	s_setprio 1
	s_waitcnt vmcnt(8) lgkmcnt(0)
	s_barrier
	v_mfma_f32_16x16x32_bf16 v[18:21], v[146:149], v[182:185], v[18:21]
	v_mfma_f32_16x16x32_bf16 v[102:105], v[94:97], v[182:185], v[102:105]
	v_mfma_f32_16x16x32_bf16 v[74:77], v[94:97], v[190:193], v[74:77]
	v_mfma_f32_16x16x32_bf16 v[42:45], v[94:97], v[198:201], v[42:45]
	v_mfma_f32_16x16x32_bf16 v[14:17], v[94:97], v[206:209], v[14:17]
	v_mfma_f32_16x16x32_bf16 v[94:97], v[150:153], v[186:189], v[18:21]
	v_mfma_f32_16x16x32_bf16 v[18:21], v[154:157], v[182:185], v[86:89]
	v_mfma_f32_16x16x32_bf16 v[86:89], v[178:181], v[186:189], v[18:21]
	v_mfma_f32_16x16x32_bf16 v[18:21], v[146:149], v[190:193], v[66:69]
	v_mfma_f32_16x16x32_bf16 v[66:69], v[150:153], v[194:197], v[18:21]
	v_mfma_f32_16x16x32_bf16 v[18:21], v[154:157], v[190:193], v[54:57]
	v_mfma_f32_16x16x32_bf16 v[54:57], v[178:181], v[194:197], v[18:21]
	v_mfma_f32_16x16x32_bf16 v[18:21], v[146:149], v[198:201], v[22:25]
	v_mfma_f32_16x16x32_bf16 v[98:101], v[138:141], v[182:185], v[98:101]
	v_mfma_f32_16x16x32_bf16 v[70:73], v[138:141], v[190:193], v[70:73]
	v_mfma_f32_16x16x32_bf16 v[38:41], v[138:141], v[198:201], v[38:41]
	v_mfma_f32_16x16x32_bf16 v[10:13], v[138:141], v[206:209], v[10:13]
	v_mfma_f32_16x16x32_bf16 v[22:25], v[150:153], v[202:205], v[18:21]
	v_mfma_f32_16x16x32_bf16 v[18:21], v[154:157], v[198:201], v[130:133]
	v_mfma_f32_16x16x32_bf16 v[6:9], v[146:149], v[206:209], v[6:9]
	v_mfma_f32_16x16x32_bf16 v[2:5], v[154:157], v[206:209], v[2:5]
	v_mfma_f32_16x16x32_bf16 v[102:105], v[134:137], v[186:189], v[102:105]
	v_mfma_f32_16x16x32_bf16 v[98:101], v[142:145], v[186:189], v[98:101]
	v_mfma_f32_16x16x32_bf16 v[74:77], v[134:137], v[194:197], v[74:77]
	v_mfma_f32_16x16x32_bf16 v[70:73], v[142:145], v[194:197], v[70:73]
	v_mfma_f32_16x16x32_bf16 v[42:45], v[134:137], v[202:205], v[42:45]
	v_mfma_f32_16x16x32_bf16 v[38:41], v[142:145], v[202:205], v[38:41]
	v_mfma_f32_16x16x32_bf16 v[14:17], v[134:137], v[210:213], v[14:17]
	v_mfma_f32_16x16x32_bf16 v[10:13], v[142:145], v[210:213], v[10:13]
	v_mfma_f32_16x16x32_bf16 v[130:133], v[178:181], v[202:205], v[18:21]
	v_mfma_f32_16x16x32_bf16 v[6:9], v[150:153], v[210:213], v[6:9]
	v_mfma_f32_16x16x32_bf16 v[2:5], v[178:181], v[210:213], v[2:5]
	s_setprio 0
	s_barrier
	s_add_i32 s37, s37, 2
	s_add_u32 s34, s34, 0x100
	s_addc_u32 s35, s35, 0
	s_cmp_gt_u32 s37, 61
	s_mov_b64 s[30:31], s[2:3]
	s_cbranch_scc0 .LBB0_754
	s_and_b64 vcc, exec, s[18:19]
	s_cbranch_vccz .LBB0_757
	s_barrier

; #define PG8_STAGE(bufoff, gbase, voff) do { const char* _gb = (const char*)(gbase); asm volatile("" : "+s"(_gb)); _Pragma("unroll") for (int _i = 0; _i < 2; ++_i) { asm volatile("" : "+v"((voff)[_i])); \
;         __builtin_amdgcn_global_load_lds((const unsigned*)(_gb + (voff)[_i]), (PG8_LAS unsigned*)(lds + (bufoff) + ldsw + _i * 8192), 16, 0, 0); } } while (0)
; #define PG8_LDA(dst, b, h) do { _Pragma("unroll") for (int m = 0; m < 4; ++m) _Pragma("unroll") for (int k = 0; k < 2; ++k) dst[m][k] = *(const PG8_LAS bf16x8*)(lds + PG8_SA(b, h) + aoff + m * 2048 + k * 1024); } while (0)
; #define PG8_LDB(dst, b, h) do { _Pragma("unroll") for (int n = 0; n < 2; ++n) _Pragma("unroll") for (int k = 0; k < 2; ++k) dst[n][k] = *(const PG8_LAS bf16x8*)(lds + PG8_SB(b, h) + boff + n * 2048 + k * 1024); } while (0)
; #define PG8_WAIT_V(n) asm volatile("s_waitcnt vmcnt(" #n ")" ::: "memory")
; #define PG8_WAIT_L(n) asm volatile("s_waitcnt lgkmcnt(" #n ")" ::: "memory")
; #define PG8_BAR __builtin_amdgcn_s_barrier()
; #define PG8_SCHED __builtin_amdgcn_sched_barrier(0)
; #define PG8_STAGE(bufoff, gbase, voff) do { const char* _gb = (const char*)(gbase); asm volatile("" : "+s"(_gb)); _Pragma("unroll") for (int _i = 0; _i < 2; ++_i) { asm volatile("" : "+v"((voff)[_i])); \
;         __builtin_amdgcn_global_load_lds((const unsigned*)(_gb + (voff)[_i]), (PG8_LAS unsigned*)(lds + (bufoff) + ldsw + _i * 8192), 16, 0, 0); } } while (0)
; #define PG8_LDA(dst, b, h) do { _Pragma("unroll") for (int m = 0; m < 4; ++m) _Pragma("unroll") for (int k = 0; k < 2; ++k) dst[m][k] = *(const PG8_LAS bf16x8*)(lds + PG8_SA(b, h) + aoff + m * 2048 + k * 1024); } while (0)
; #define PG8_WAIT_V(n) asm volatile("s_waitcnt vmcnt(" #n ")" ::: "memory")
; template <class Epi, class Sched, bool ALIGN_EPI = false, bool SP2 = false>
; __device__ __forceinline__ void gemm_phase(PG8_LAS unsigned char* lds, const Gemm g, const Sched& S, const Epi& E) {
;     ...
;             PG8_LDB(B0, 0, 0); PG8_LDB(B1, 0, 1); PG8_SCHED; PG8_LDA(At, 0, 0); PG8_STAGE(PG8_SA(1, 1), a1 + hstep, voffA);
;             PG8_WAIT_V(8); PG8_WAIT_L(0); PG8_BAR; PG8_MMA2(0); PG8_BAR; PG8_SCHED;
;             PG8_LDA(At, 0, 1); PG8_STAGE(PG8_SB(0, 0), b2, voffB); PG8_STAGE(PG8_SB(0, 1), b2 + hstep, voffB); PG8_STAGE(PG8_SA(0, 0), a2, voffA);
;             PG8_WAIT_V(8); PG8_WAIT_L(0); PG8_BAR; PG8_MMA2(1); PG8_BAR; PG8_SCHED;
.LBB0_833:
	ds_read_b128 v[130:133], v180
	ds_read_b128 v[134:137], v180 offset:1024
	ds_read_b128 v[138:141], v180 offset:2048
	ds_read_b128 v[142:145], v180 offset:3072
	ds_read_b128 v[146:149], v181
	ds_read_b128 v[150:153], v181 offset:1024
	ds_read_b128 v[154:157], v181 offset:2048
	ds_read_b128 v[158:161], v181 offset:3072
	s_add_u32 s24, s16, 0x100
	s_addc_u32 s25, s17, 0
	s_cmp_eq_u32 s87, 60
	s_cselect_b32 s28, s83, s24
	s_cselect_b32 s29, s55, s25
	s_cselect_b32 s26, s84, s85
	s_cselect_b32 s27, s53, s86
	s_add_u32 s2, s28, 0x80
	s_addc_u32 s3, s29, 0
	s_add_u32 s16, s16, 0x100080
	s_addc_u32 s17, s17, 0
	s_add_i32 m0, s69, 0xc000
	ds_read_b128 v[166:169], v182
	ds_read_b128 v[170:173], v182 offset:1024
	ds_read_b128 v[184:187], v182 offset:2048
	ds_read_b128 v[188:191], v182 offset:3072
	ds_read_b128 v[192:195], v182 offset:4096
	ds_read_b128 v[196:199], v182 offset:5120
	ds_read_b128 v[200:203], v182 offset:6144
	ds_read_b128 v[204:207], v182 offset:7168
	s_nop 0
	global_load_lds_dwordx4 v1, s[16:17]
	s_add_i32 m0, s69, 0xe000
	s_nop 0
	global_load_lds_dwordx4 v175, s[16:17]
	s_nop 0
	s_nop 0
	s_setprio 1
	s_waitcnt vmcnt(8) lgkmcnt(0)
	s_barrier
	v_mfma_f32_16x16x32_bf16 v[126:129], v[130:133], v[166:169], v[126:129]
	v_mfma_f32_16x16x32_bf16 v[122:125], v[138:141], v[166:169], v[122:125]
	v_mfma_f32_16x16x32_bf16 v[110:113], v[130:133], v[184:187], v[110:113]
	v_mfma_f32_16x16x32_bf16 v[106:109], v[138:141], v[184:187], v[106:109]
	v_mfma_f32_16x16x32_bf16 v[94:97], v[130:133], v[192:195], v[94:97]
	v_mfma_f32_16x16x32_bf16 v[90:93], v[138:141], v[192:195], v[90:93]
	v_mfma_f32_16x16x32_bf16 v[78:81], v[130:133], v[200:203], v[78:81]
	v_mfma_f32_16x16x32_bf16 v[74:77], v[138:141], v[200:203], v[74:77]
	v_mfma_f32_16x16x32_bf16 v[118:121], v[146:149], v[166:169], v[118:121]
	v_mfma_f32_16x16x32_bf16 v[114:117], v[154:157], v[166:169], v[114:117]
	v_mfma_f32_16x16x32_bf16 v[102:105], v[146:149], v[184:187], v[102:105]
	v_mfma_f32_16x16x32_bf16 v[98:101], v[154:157], v[184:187], v[98:101]
	v_mfma_f32_16x16x32_bf16 v[86:89], v[146:149], v[192:195], v[86:89]
	v_mfma_f32_16x16x32_bf16 v[82:85], v[154:157], v[192:195], v[82:85]
	v_mfma_f32_16x16x32_bf16 v[70:73], v[146:149], v[200:203], v[70:73]
	v_mfma_f32_16x16x32_bf16 v[66:69], v[154:157], v[200:203], v[66:69]
	v_mfma_f32_16x16x32_bf16 v[126:129], v[134:137], v[170:173], v[126:129]
	v_mfma_f32_16x16x32_bf16 v[122:125], v[142:145], v[170:173], v[122:125]
	v_mfma_f32_16x16x32_bf16 v[110:113], v[134:137], v[188:191], v[110:113]
	v_mfma_f32_16x16x32_bf16 v[106:109], v[142:145], v[188:191], v[106:109]
	v_mfma_f32_16x16x32_bf16 v[94:97], v[134:137], v[196:199], v[94:97]
	v_mfma_f32_16x16x32_bf16 v[90:93], v[142:145], v[196:199], v[90:93]
	v_mfma_f32_16x16x32_bf16 v[78:81], v[134:137], v[204:207], v[78:81]
	v_mfma_f32_16x16x32_bf16 v[74:77], v[142:145], v[204:207], v[74:77]
	v_mfma_f32_16x16x32_bf16 v[118:121], v[150:153], v[170:173], v[118:121]
	v_mfma_f32_16x16x32_bf16 v[114:117], v[158:161], v[170:173], v[114:117]
	v_mfma_f32_16x16x32_bf16 v[102:105], v[150:153], v[188:191], v[102:105]
	v_mfma_f32_16x16x32_bf16 v[98:101], v[158:161], v[188:191], v[98:101]
	v_mfma_f32_16x16x32_bf16 v[86:89], v[150:153], v[196:199], v[86:89]
	v_mfma_f32_16x16x32_bf16 v[82:85], v[158:161], v[196:199], v[82:85]
	v_mfma_f32_16x16x32_bf16 v[70:73], v[150:153], v[204:207], v[70:73]
	v_mfma_f32_16x16x32_bf16 v[66:69], v[158:161], v[204:207], v[66:69]
	s_setprio 0
	s_barrier
	s_add_i32 s88, s81, s73
	s_mov_b64 s[16:17], s[26:27]
	s_mov_b32 m0, s88
	ds_read_b128 v[166:169], v182 offset:16384
	ds_read_b128 v[170:173], v182 offset:17408
	ds_read_b128 v[184:187], v182 offset:18432
	ds_read_b128 v[188:191], v182 offset:19456
	ds_read_b128 v[192:195], v182 offset:20480
	ds_read_b128 v[196:199], v182 offset:21504
	ds_read_b128 v[200:203], v182 offset:22528
	ds_read_b128 v[204:207], v182 offset:23552
	s_nop 0
	global_load_lds_dwordx4 v174, s[16:17]
	s_add_i32 m0, s88, 0x2000
	s_nop 0
	global_load_lds_dwordx4 v176, s[16:17]
	s_add_u32 s16, s26, 0x100000
	s_addc_u32 s17, s27, 0
	s_add_i32 s88, s82, s73
	s_mov_b32 m0, s88
	s_nop 0
	global_load_lds_dwordx4 v174, s[16:17]
	s_add_i32 m0, s88, 0x2000
	s_nop 0
	global_load_lds_dwordx4 v176, s[16:17]
	s_mov_b64 s[16:17], s[28:29]
	s_mov_b32 m0, s69
	s_nop 0
	global_load_lds_dwordx4 v1, s[16:17]
	s_mov_b32 m0, s71
	s_nop 0
	global_load_lds_dwordx4 v175, s[16:17]
	s_nop 0
	s_nop 0
	s_setprio 1
	s_waitcnt vmcnt(8) lgkmcnt(0)
	s_barrier
	v_mfma_f32_16x16x32_bf16 v[62:65], v[130:133], v[166:169], v[62:65]
	v_mfma_f32_16x16x32_bf16 v[58:61], v[138:141], v[166:169], v[58:61]
	v_mfma_f32_16x16x32_bf16 v[46:49], v[130:133], v[184:187], v[46:49]
	v_mfma_f32_16x16x32_bf16 v[42:45], v[138:141], v[184:187], v[42:45]
	v_mfma_f32_16x16x32_bf16 v[30:33], v[130:133], v[192:195], v[30:33]
	v_mfma_f32_16x16x32_bf16 v[26:29], v[138:141], v[192:195], v[26:29]
	v_mfma_f32_16x16x32_bf16 v[14:17], v[130:133], v[200:203], v[14:17]
	v_mfma_f32_16x16x32_bf16 v[10:13], v[138:141], v[200:203], v[10:13]
	v_mfma_f32_16x16x32_bf16 v[54:57], v[146:149], v[166:169], v[54:57]
	v_mfma_f32_16x16x32_bf16 v[50:53], v[154:157], v[166:169], v[50:53]
	v_mfma_f32_16x16x32_bf16 v[38:41], v[146:149], v[184:187], v[38:41]
	v_mfma_f32_16x16x32_bf16 v[34:37], v[154:157], v[184:187], v[34:37]
	v_mfma_f32_16x16x32_bf16 v[22:25], v[146:149], v[192:195], v[22:25]
	v_mfma_f32_16x16x32_bf16 v[18:21], v[154:157], v[192:195], v[18:21]
	v_mfma_f32_16x16x32_bf16 v[6:9], v[146:149], v[200:203], v[6:9]
	v_mfma_f32_16x16x32_bf16 v[2:5], v[154:157], v[200:203], v[2:5]
	v_mfma_f32_16x16x32_bf16 v[62:65], v[134:137], v[170:173], v[62:65]
	v_mfma_f32_16x16x32_bf16 v[58:61], v[142:145], v[170:173], v[58:61]
	v_mfma_f32_16x16x32_bf16 v[46:49], v[134:137], v[188:191], v[46:49]
	v_mfma_f32_16x16x32_bf16 v[42:45], v[142:145], v[188:191], v[42:45]
	v_mfma_f32_16x16x32_bf16 v[30:33], v[134:137], v[196:199], v[30:33]
	v_mfma_f32_16x16x32_bf16 v[26:29], v[142:145], v[196:199], v[26:29]
	v_mfma_f32_16x16x32_bf16 v[14:17], v[134:137], v[204:207], v[14:17]
	v_mfma_f32_16x16x32_bf16 v[10:13], v[142:145], v[204:207], v[10:13]
	v_mfma_f32_16x16x32_bf16 v[54:57], v[150:153], v[170:173], v[54:57]
	v_mfma_f32_16x16x32_bf16 v[50:53], v[158:161], v[170:173], v[50:53]
	v_mfma_f32_16x16x32_bf16 v[38:41], v[150:153], v[188:191], v[38:41]
	v_mfma_f32_16x16x32_bf16 v[34:37], v[158:161], v[188:191], v[34:37]
	v_mfma_f32_16x16x32_bf16 v[22:25], v[150:153], v[196:199], v[22:25]
	v_mfma_f32_16x16x32_bf16 v[18:21], v[158:161], v[196:199], v[18:21]
	v_mfma_f32_16x16x32_bf16 v[6:9], v[150:153], v[204:207], v[6:9]
	v_mfma_f32_16x16x32_bf16 v[2:5], v[158:161], v[204:207], v[2:5]
	s_setprio 0
	s_barrier
; #define PG8_STAGE(bufoff, gbase, voff) do { const char* _gb = (const char*)(gbase); asm volatile("" : "+s"(_gb)); _Pragma("unroll") for (int _i = 0; _i < 2; ++_i) { asm volatile("" : "+v"((voff)[_i])); \
;         __builtin_amdgcn_global_load_lds((const unsigned*)(_gb + (voff)[_i]), (PG8_LAS unsigned*)(lds + (bufoff) + ldsw + _i * 8192), 16, 0, 0); } } while (0)
; #define PG8_LDA(dst, b, h) do { _Pragma("unroll") for (int m = 0; m < 4; ++m) _Pragma("unroll") for (int k = 0; k < 2; ++k) dst[m][k] = *(const PG8_LAS bf16x8*)(lds + PG8_SA(b, h) + aoff + m * 2048 + k * 1024); } while (0)
; #define PG8_LDB(dst, b, h) do { _Pragma("unroll") for (int n = 0; n < 2; ++n) _Pragma("unroll") for (int k = 0; k < 2; ++k) dst[n][k] = *(const PG8_LAS bf16x8*)(lds + PG8_SB(b, h) + boff + n * 2048 + k * 1024); } while (0)
; #define PG8_WAIT_V(n) asm volatile("s_waitcnt vmcnt(" #n ")" ::: "memory")
; #define PG8_WAIT_L(n) asm volatile("s_waitcnt lgkmcnt(" #n ")" ::: "memory")
; #define PG8_BAR __builtin_amdgcn_s_barrier()
; #define PG8_SCHED __builtin_amdgcn_sched_barrier(0)
; #define PG8_STAGE(bufoff, gbase, voff) do { const char* _gb = (const char*)(gbase); asm volatile("" : "+s"(_gb)); _Pragma("unroll") for (int _i = 0; _i < 2; ++_i) { asm volatile("" : "+v"((voff)[_i])); \
;         __builtin_amdgcn_global_load_lds((const unsigned*)(_gb + (voff)[_i]), (PG8_LAS unsigned*)(lds + (bufoff) + ldsw + _i * 8192), 16, 0, 0); } } while (0)
; #define PG8_LDA(dst, b, h) do { _Pragma("unroll") for (int m = 0; m < 4; ++m) _Pragma("unroll") for (int k = 0; k < 2; ++k) dst[m][k] = *(const PG8_LAS bf16x8*)(lds + PG8_SA(b, h) + aoff + m * 2048 + k * 1024); } while (0)
; template <class Epi, class Sched, bool ALIGN_EPI = false, bool SP2 = false>
; __device__ __forceinline__ void gemm_phase(PG8_LAS unsigned char* lds, const Gemm g, const Sched& S, const Epi& E) {
;     ...
;             PG8_LDB(B0, 1, 0); PG8_LDB(B1, 1, 1); PG8_SCHED; PG8_LDA(At, 1, 0); PG8_STAGE(PG8_SA(0, 1), a2 + hstep, voffA);
;             PG8_WAIT_V(8); PG8_WAIT_L(0); PG8_BAR; PG8_MMA2(0); PG8_BAR; PG8_SCHED;
;             PG8_LDA(At, 1, 1); PG8_STAGE(PG8_SB(1, 0), b3, voffB); PG8_STAGE(PG8_SB(1, 1), b3 + hstep, voffB); PG8_STAGE(PG8_SA(1, 0), a3, voffA);
;             PG8_WAIT_V(8); PG8_WAIT_L(0); PG8_BAR; PG8_MMA2(1); PG8_BAR; PG8_SCHED;
;     ...
;         if constexpr (ALIGN_EPI) { if (wr == 0) PG8_BAR; }
	s_add_i32 s88, 0, 0x18000
	s_add_i32 s89, 0, 0x1c000
	v_add_u32_e32 v142, s88, v178
	v_add_u32_e32 v158, s89, v178
	ds_read_b128 v[130:133], v142
	ds_read_b128 v[134:137], v142 offset:1024
	ds_read_b128 v[138:141], v142 offset:2048
	ds_read_b128 v[142:145], v142 offset:3072
	ds_read_b128 v[146:149], v158
	ds_read_b128 v[150:153], v158 offset:1024
	ds_read_b128 v[154:157], v158 offset:2048
	ds_read_b128 v[158:161], v158 offset:3072
	s_add_u32 s16, s28, 0x100000
	s_addc_u32 s17, s29, 0
	s_mov_b32 m0, s74
	ds_read_b128 v[166:169], v182 offset:32768
	ds_read_b128 v[170:173], v182 offset:33792
	ds_read_b128 v[184:187], v182 offset:34816
	ds_read_b128 v[188:191], v182 offset:35840
	ds_read_b128 v[192:195], v182 offset:36864
	ds_read_b128 v[196:199], v182 offset:37888
	ds_read_b128 v[200:203], v182 offset:38912
	ds_read_b128 v[204:207], v182 offset:39936
	s_nop 0
	global_load_lds_dwordx4 v1, s[16:17]
	s_mov_b32 m0, s75
	s_nop 0
	global_load_lds_dwordx4 v175, s[16:17]
	s_nop 0
	s_nop 0
	s_setprio 1
	s_waitcnt vmcnt(8) lgkmcnt(0)
	s_barrier
	v_mfma_f32_16x16x32_bf16 v[126:129], v[130:133], v[166:169], v[126:129]
	v_mfma_f32_16x16x32_bf16 v[122:125], v[138:141], v[166:169], v[122:125]
	v_mfma_f32_16x16x32_bf16 v[110:113], v[130:133], v[184:187], v[110:113]
	v_mfma_f32_16x16x32_bf16 v[106:109], v[138:141], v[184:187], v[106:109]
	v_mfma_f32_16x16x32_bf16 v[94:97], v[130:133], v[192:195], v[94:97]
	v_mfma_f32_16x16x32_bf16 v[90:93], v[138:141], v[192:195], v[90:93]
	v_mfma_f32_16x16x32_bf16 v[78:81], v[130:133], v[200:203], v[78:81]
	v_mfma_f32_16x16x32_bf16 v[74:77], v[138:141], v[200:203], v[74:77]
	v_mfma_f32_16x16x32_bf16 v[118:121], v[146:149], v[166:169], v[118:121]
	v_mfma_f32_16x16x32_bf16 v[114:117], v[154:157], v[166:169], v[114:117]
	v_mfma_f32_16x16x32_bf16 v[102:105], v[146:149], v[184:187], v[102:105]
	v_mfma_f32_16x16x32_bf16 v[98:101], v[154:157], v[184:187], v[98:101]
	v_mfma_f32_16x16x32_bf16 v[86:89], v[146:149], v[192:195], v[86:89]
	v_mfma_f32_16x16x32_bf16 v[82:85], v[154:157], v[192:195], v[82:85]
	v_mfma_f32_16x16x32_bf16 v[70:73], v[146:149], v[200:203], v[70:73]
	v_mfma_f32_16x16x32_bf16 v[66:69], v[154:157], v[200:203], v[66:69]
	v_mfma_f32_16x16x32_bf16 v[126:129], v[134:137], v[170:173], v[126:129]
	v_mfma_f32_16x16x32_bf16 v[122:125], v[142:145], v[170:173], v[122:125]
	v_mfma_f32_16x16x32_bf16 v[110:113], v[134:137], v[188:191], v[110:113]
	v_mfma_f32_16x16x32_bf16 v[106:109], v[142:145], v[188:191], v[106:109]
	v_mfma_f32_16x16x32_bf16 v[94:97], v[134:137], v[196:199], v[94:97]
	v_mfma_f32_16x16x32_bf16 v[90:93], v[142:145], v[196:199], v[90:93]
	v_mfma_f32_16x16x32_bf16 v[78:81], v[134:137], v[204:207], v[78:81]
	v_mfma_f32_16x16x32_bf16 v[74:77], v[142:145], v[204:207], v[74:77]
	v_mfma_f32_16x16x32_bf16 v[118:121], v[150:153], v[170:173], v[118:121]
	v_mfma_f32_16x16x32_bf16 v[114:117], v[158:161], v[170:173], v[114:117]
	v_mfma_f32_16x16x32_bf16 v[102:105], v[150:153], v[188:191], v[102:105]
	v_mfma_f32_16x16x32_bf16 v[98:101], v[158:161], v[188:191], v[98:101]
	v_mfma_f32_16x16x32_bf16 v[86:89], v[150:153], v[196:199], v[86:89]
	v_mfma_f32_16x16x32_bf16 v[82:85], v[158:161], v[196:199], v[82:85]
	v_mfma_f32_16x16x32_bf16 v[70:73], v[150:153], v[204:207], v[70:73]
	v_mfma_f32_16x16x32_bf16 v[66:69], v[158:161], v[204:207], v[66:69]
	s_setprio 0
	s_barrier
	s_add_u32 s16, s26, 0x80
	s_addc_u32 s17, s27, 0
	s_add_i32 s28, s88, s73
	s_mov_b32 m0, s28
	ds_read_b128 v[166:169], v182 offset:49152
	ds_read_b128 v[170:173], v182 offset:50176
	ds_read_b128 v[184:187], v182 offset:51200
	ds_read_b128 v[188:191], v182 offset:52224
	ds_read_b128 v[192:195], v182 offset:53248
	ds_read_b128 v[196:199], v182 offset:54272
	ds_read_b128 v[200:203], v182 offset:55296
	ds_read_b128 v[204:207], v182 offset:56320
	s_nop 0
	global_load_lds_dwordx4 v174, s[16:17]
	s_add_i32 m0, s28, 0x2000
	s_nop 0
	global_load_lds_dwordx4 v176, s[16:17]
	s_add_u32 s16, s26, 0x100080
	s_addc_u32 s17, s27, 0
	s_add_i32 s26, s89, s73
	s_mov_b32 m0, s26
	s_nop 0
	global_load_lds_dwordx4 v174, s[16:17]
	s_add_i32 m0, s26, 0x2000
	s_nop 0
	global_load_lds_dwordx4 v176, s[16:17]
	s_mov_b32 m0, s77
	s_nop 0
	global_load_lds_dwordx4 v1, s[2:3]
	s_mov_b32 m0, s78
	s_nop 0
	global_load_lds_dwordx4 v175, s[2:3]
	s_nop 0
	s_nop 0
	s_setprio 1
	s_waitcnt vmcnt(8) lgkmcnt(0)
	s_barrier
	v_mfma_f32_16x16x32_bf16 v[62:65], v[130:133], v[166:169], v[62:65]
	v_mfma_f32_16x16x32_bf16 v[58:61], v[138:141], v[166:169], v[58:61]
	v_mfma_f32_16x16x32_bf16 v[46:49], v[130:133], v[184:187], v[46:49]
	v_mfma_f32_16x16x32_bf16 v[42:45], v[138:141], v[184:187], v[42:45]
	v_mfma_f32_16x16x32_bf16 v[30:33], v[130:133], v[192:195], v[30:33]
	v_mfma_f32_16x16x32_bf16 v[26:29], v[138:141], v[192:195], v[26:29]
	v_mfma_f32_16x16x32_bf16 v[14:17], v[130:133], v[200:203], v[14:17]
	v_mfma_f32_16x16x32_bf16 v[10:13], v[138:141], v[200:203], v[10:13]
	v_mfma_f32_16x16x32_bf16 v[54:57], v[146:149], v[166:169], v[54:57]
	v_mfma_f32_16x16x32_bf16 v[50:53], v[154:157], v[166:169], v[50:53]
	v_mfma_f32_16x16x32_bf16 v[38:41], v[146:149], v[184:187], v[38:41]
	v_mfma_f32_16x16x32_bf16 v[34:37], v[154:157], v[184:187], v[34:37]
	v_mfma_f32_16x16x32_bf16 v[22:25], v[146:149], v[192:195], v[22:25]
	v_mfma_f32_16x16x32_bf16 v[18:21], v[154:157], v[192:195], v[18:21]
	v_mfma_f32_16x16x32_bf16 v[6:9], v[146:149], v[200:203], v[6:9]
	v_mfma_f32_16x16x32_bf16 v[2:5], v[154:157], v[200:203], v[2:5]
	v_mfma_f32_16x16x32_bf16 v[62:65], v[134:137], v[170:173], v[62:65]
	v_mfma_f32_16x16x32_bf16 v[58:61], v[142:145], v[170:173], v[58:61]
	v_mfma_f32_16x16x32_bf16 v[46:49], v[134:137], v[188:191], v[46:49]
	v_mfma_f32_16x16x32_bf16 v[42:45], v[142:145], v[188:191], v[42:45]
	v_mfma_f32_16x16x32_bf16 v[30:33], v[134:137], v[196:199], v[30:33]
	v_mfma_f32_16x16x32_bf16 v[26:29], v[142:145], v[196:199], v[26:29]
	v_mfma_f32_16x16x32_bf16 v[14:17], v[134:137], v[204:207], v[14:17]
	v_mfma_f32_16x16x32_bf16 v[10:13], v[142:145], v[204:207], v[10:13]
	v_mfma_f32_16x16x32_bf16 v[54:57], v[150:153], v[170:173], v[54:57]
	v_mfma_f32_16x16x32_bf16 v[50:53], v[158:161], v[170:173], v[50:53]
	v_mfma_f32_16x16x32_bf16 v[38:41], v[150:153], v[188:191], v[38:41]
	v_mfma_f32_16x16x32_bf16 v[34:37], v[158:161], v[188:191], v[34:37]
	v_mfma_f32_16x16x32_bf16 v[22:25], v[150:153], v[196:199], v[22:25]
	v_mfma_f32_16x16x32_bf16 v[18:21], v[158:161], v[196:199], v[18:21]
	v_mfma_f32_16x16x32_bf16 v[6:9], v[150:153], v[204:207], v[6:9]
	v_mfma_f32_16x16x32_bf16 v[2:5], v[158:161], v[204:207], v[2:5]
	s_setprio 0
	s_barrier
	s_add_i32 s87, s87, 2
	s_add_u32 s85, s85, 0x100
	s_addc_u32 s86, s86, 0
	s_cmp_gt_u32 s87, 61
	s_mov_b64 s[16:17], s[24:25]
	s_cbranch_scc0 .LBB0_833
	s_and_b64 vcc, exec, s[12:13]
	s_cbranch_vccz .LBB0_836
	s_barrier

; #define PG8_STAGE(bufoff, gbase, voff) do { const char* _gb = (const char*)(gbase); asm volatile("" : "+s"(_gb)); _Pragma("unroll") for (int _i = 0; _i < 2; ++_i) { asm volatile("" : "+v"((voff)[_i])); \
;         __builtin_amdgcn_global_load_lds((const unsigned*)(_gb + (voff)[_i]), (PG8_LAS unsigned*)(lds + (bufoff) + ldsw + _i * 8192), 16, 0, 0); } } while (0)
; #define PG8_LDA(dst, b, h) do { _Pragma("unroll") for (int m = 0; m < 4; ++m) _Pragma("unroll") for (int k = 0; k < 2; ++k) dst[m][k] = *(const PG8_LAS bf16x8*)(lds + PG8_SA(b, h) + aoff + m * 2048 + k * 1024); } while (0)
; #define PG8_LDB(dst, b, h) do { _Pragma("unroll") for (int n = 0; n < 2; ++n) _Pragma("unroll") for (int k = 0; k < 2; ++k) dst[n][k] = *(const PG8_LAS bf16x8*)(lds + PG8_SB(b, h) + boff + n * 2048 + k * 1024); } while (0)
; #define PG8_WAIT_V(n) asm volatile("s_waitcnt vmcnt(" #n ")" ::: "memory")
; #define PG8_WAIT_L(n) asm volatile("s_waitcnt lgkmcnt(" #n ")" ::: "memory")
; #define PG8_BAR __builtin_amdgcn_s_barrier()
; #define PG8_SCHED __builtin_amdgcn_sched_barrier(0)
; #define PG8_STAGE(bufoff, gbase, voff) do { const char* _gb = (const char*)(gbase); asm volatile("" : "+s"(_gb)); _Pragma("unroll") for (int _i = 0; _i < 2; ++_i) { asm volatile("" : "+v"((voff)[_i])); \
;         __builtin_amdgcn_global_load_lds((const unsigned*)(_gb + (voff)[_i]), (PG8_LAS unsigned*)(lds + (bufoff) + ldsw + _i * 8192), 16, 0, 0); } } while (0)
; #define PG8_LDA(dst, b, h) do { _Pragma("unroll") for (int m = 0; m < 4; ++m) _Pragma("unroll") for (int k = 0; k < 2; ++k) dst[m][k] = *(const PG8_LAS bf16x8*)(lds + PG8_SA(b, h) + aoff + m * 2048 + k * 1024); } while (0)
; #define PG8_WAIT_V(n) asm volatile("s_waitcnt vmcnt(" #n ")" ::: "memory")
; template <class Epi, class Sched, bool ALIGN_EPI = false, bool SP2 = false>
; __device__ __forceinline__ void gemm_phase(PG8_LAS unsigned char* lds, const Gemm g, const Sched& S, const Epi& E) {
;     ...
;             PG8_LDB(B0, 0, 0); PG8_LDB(B1, 0, 1); PG8_SCHED; PG8_LDA(At, 0, 0); PG8_STAGE(PG8_SA(1, 1), a1 + hstep, voffA);
;             PG8_WAIT_V(8); PG8_WAIT_L(0); PG8_BAR; PG8_MMA2(0); PG8_BAR; PG8_SCHED;
;             PG8_LDA(At, 0, 1); PG8_STAGE(PG8_SB(0, 0), b2, voffB); PG8_STAGE(PG8_SB(0, 1), b2 + hstep, voffB); PG8_STAGE(PG8_SA(0, 0), a2, voffA);
;             PG8_WAIT_V(8); PG8_WAIT_L(0); PG8_BAR; PG8_MMA2(1); PG8_BAR; PG8_SCHED;
.LBB0_933:
	v_add_u32_e32 v142, s78, v201
	v_add_u32_e32 v147, s79, v201
	s_nop 0
	ds_read_b128 v[6:9], v142
	ds_read_b128 v[62:65], v142 offset:1024
	ds_read_b128 v[138:141], v142 offset:2048
	ds_read_b128 v[142:145], v142 offset:3072
	ds_read_b128 v[164:167], v147
	ds_read_b128 v[168:171], v147 offset:1024
	ds_read_b128 v[172:175], v147 offset:2048
	ds_read_b128 v[176:179], v147 offset:3072
	s_add_u32 s14, s12, 0x100
	s_addc_u32 s15, s13, 0
	s_cmp_eq_u32 s83, 60
	s_cselect_b32 s18, s21, s14
	s_cselect_b32 s19, s20, s15
	s_cselect_b32 s16, s51, s62
	s_cselect_b32 s17, s49, s63
	s_add_u32 s2, s18, 0x80
	s_addc_u32 s3, s19, 0
	s_add_u32 s12, s12, 0x100080
	s_addc_u32 s13, s13, 0
	s_add_i32 m0, s33, 0xc000
	ds_read_b128 v[180:183], v219
	ds_read_b128 v[184:187], v219 offset:1024
	ds_read_b128 v[188:191], v219 offset:2048
	ds_read_b128 v[192:195], v219 offset:3072
	ds_read_b128 v[222:225], v219 offset:4096
	ds_read_b128 v[226:229], v219 offset:5120
	ds_read_b128 v[230:233], v219 offset:6144
	ds_read_b128 v[234:237], v219 offset:7168
	s_nop 0
	global_load_lds_dwordx4 v1, s[12:13]
	s_add_i32 m0, s33, 0xe000
	s_nop 0
	global_load_lds_dwordx4 v199, s[12:13]
	s_nop 0
	s_nop 0
	s_setprio 1
	s_waitcnt vmcnt(8) lgkmcnt(0)
	s_barrier
	v_mfma_f32_16x16x32_bf16 v[118:121], v[6:9], v[180:183], v[118:121]
	v_mfma_f32_16x16x32_bf16 v[114:117], v[138:141], v[180:183], v[114:117]
	v_mfma_f32_16x16x32_bf16 v[106:109], v[6:9], v[188:191], v[106:109]
	v_mfma_f32_16x16x32_bf16 v[86:89], v[138:141], v[188:191], v[86:89]
	v_mfma_f32_16x16x32_bf16 v[134:137], v[6:9], v[222:225], v[134:137]
	v_mfma_f32_16x16x32_bf16 v[90:93], v[138:141], v[222:225], v[90:93]
	v_mfma_f32_16x16x32_bf16 v[130:133], v[6:9], v[230:233], v[130:133]
	v_mfma_f32_16x16x32_bf16 v[110:113], v[138:141], v[230:233], v[110:113]
	v_mfma_f32_16x16x32_bf16 v[94:97], v[164:167], v[180:183], v[94:97]
	v_mfma_f32_16x16x32_bf16 v[82:85], v[172:175], v[180:183], v[82:85]
	v_mfma_f32_16x16x32_bf16 v[78:81], v[164:167], v[188:191], v[78:81]
	v_mfma_f32_16x16x32_bf16 v[74:77], v[172:175], v[188:191], v[74:77]
	v_mfma_f32_16x16x32_bf16 v[126:129], v[164:167], v[222:225], v[126:129]
	v_mfma_f32_16x16x32_bf16 v[98:101], v[172:175], v[222:225], v[98:101]
	v_mfma_f32_16x16x32_bf16 v[122:125], v[164:167], v[230:233], v[122:125]
	v_mfma_f32_16x16x32_bf16 v[102:105], v[172:175], v[230:233], v[102:105]
	v_mfma_f32_16x16x32_bf16 v[118:121], v[62:65], v[184:187], v[118:121]
	v_mfma_f32_16x16x32_bf16 v[114:117], v[142:145], v[184:187], v[114:117]
	v_mfma_f32_16x16x32_bf16 v[106:109], v[62:65], v[192:195], v[106:109]
	v_mfma_f32_16x16x32_bf16 v[86:89], v[142:145], v[192:195], v[86:89]
	v_mfma_f32_16x16x32_bf16 v[134:137], v[62:65], v[226:229], v[134:137]
	v_mfma_f32_16x16x32_bf16 v[90:93], v[142:145], v[226:229], v[90:93]
	v_mfma_f32_16x16x32_bf16 v[130:133], v[62:65], v[234:237], v[130:133]
	v_mfma_f32_16x16x32_bf16 v[110:113], v[142:145], v[234:237], v[110:113]
	v_mfma_f32_16x16x32_bf16 v[94:97], v[168:171], v[184:187], v[94:97]
	v_mfma_f32_16x16x32_bf16 v[82:85], v[176:179], v[184:187], v[82:85]
	v_mfma_f32_16x16x32_bf16 v[78:81], v[168:171], v[192:195], v[78:81]
	v_mfma_f32_16x16x32_bf16 v[74:77], v[176:179], v[192:195], v[74:77]
	v_mfma_f32_16x16x32_bf16 v[126:129], v[168:171], v[226:229], v[126:129]
	v_mfma_f32_16x16x32_bf16 v[98:101], v[176:179], v[226:229], v[98:101]
	v_mfma_f32_16x16x32_bf16 v[122:125], v[168:171], v[234:237], v[122:125]
	v_mfma_f32_16x16x32_bf16 v[102:105], v[176:179], v[234:237], v[102:105]
	s_setprio 0
	s_barrier
	s_add_i32 s84, s78, s25
	s_mov_b64 s[12:13], s[16:17]
	s_mov_b32 m0, s84
	ds_read_b128 v[180:183], v219 offset:16384
	ds_read_b128 v[184:187], v219 offset:17408
	ds_read_b128 v[188:191], v219 offset:18432
	ds_read_b128 v[192:195], v219 offset:19456
	ds_read_b128 v[222:225], v219 offset:20480
	ds_read_b128 v[226:229], v219 offset:21504
	ds_read_b128 v[230:233], v219 offset:22528
	ds_read_b128 v[234:237], v219 offset:23552
	s_nop 0
	global_load_lds_dwordx4 v198, s[12:13]
	s_add_i32 m0, s84, 0x2000
	s_nop 0
	global_load_lds_dwordx4 v200, s[12:13]
	s_add_u32 s12, s16, 0x100000
	s_addc_u32 s13, s17, 0
	s_add_i32 s84, s79, s25
	s_mov_b32 m0, s84
	s_nop 0
	global_load_lds_dwordx4 v198, s[12:13]
	s_add_i32 m0, s84, 0x2000
	s_nop 0
	global_load_lds_dwordx4 v200, s[12:13]
	s_mov_b64 s[12:13], s[18:19]
	s_mov_b32 m0, s33
	s_nop 0
	global_load_lds_dwordx4 v1, s[12:13]
	s_mov_b32 m0, s45
	s_nop 0
	global_load_lds_dwordx4 v199, s[12:13]
	s_nop 0
	s_nop 0
	s_setprio 1
	s_waitcnt vmcnt(8) lgkmcnt(0)
	s_barrier
	v_mfma_f32_16x16x32_bf16 v[34:37], v[6:9], v[180:183], v[34:37]
	v_mfma_f32_16x16x32_bf16 v[30:33], v[138:141], v[180:183], v[30:33]
	v_mfma_f32_16x16x32_bf16 v[26:29], v[6:9], v[188:191], v[26:29]
	v_mfma_f32_16x16x32_bf16 v[22:25], v[138:141], v[188:191], v[22:25]
	v_mfma_f32_16x16x32_bf16 v[70:73], v[6:9], v[222:225], v[70:73]
	v_mfma_f32_16x16x32_bf16 v[66:69], v[138:141], v[222:225], v[66:69]
	v_mfma_f32_16x16x32_bf16 v[50:53], v[138:141], v[230:233], v[50:53]
	v_mfma_f32_16x16x32_bf16 v[18:21], v[164:167], v[180:183], v[18:21]
	v_mfma_f32_16x16x32_bf16 v[14:17], v[172:175], v[180:183], v[14:17]
	v_mfma_f32_16x16x32_bf16 v[10:13], v[164:167], v[188:191], v[10:13]
	v_mfma_f32_16x16x32_bf16 v[2:5], v[172:175], v[188:191], v[2:5]
	v_mfma_f32_16x16x32_bf16 v[54:57], v[164:167], v[222:225], v[54:57]
	v_mfma_f32_16x16x32_bf16 v[46:49], v[172:175], v[222:225], v[46:49]
	v_mfma_f32_16x16x32_bf16 v[42:45], v[164:167], v[230:233], v[42:45]
	v_mfma_f32_16x16x32_bf16 v[38:41], v[172:175], v[230:233], v[38:41]
	v_mfma_f32_16x16x32_bf16 v[34:37], v[62:65], v[184:187], v[34:37]
	v_mfma_f32_16x16x32_bf16 v[30:33], v[142:145], v[184:187], v[30:33]
	v_mfma_f32_16x16x32_bf16 v[26:29], v[62:65], v[192:195], v[26:29]
	v_mfma_f32_16x16x32_bf16 v[22:25], v[142:145], v[192:195], v[22:25]
	v_mfma_f32_16x16x32_bf16 v[70:73], v[62:65], v[226:229], v[70:73]
	v_mfma_f32_16x16x32_bf16 v[66:69], v[142:145], v[226:229], v[66:69]
	v_mfma_f32_16x16x32_bf16 v[6:9], v[6:9], v[230:233], v[58:61]
	v_mfma_f32_16x16x32_bf16 v[50:53], v[142:145], v[234:237], v[50:53]
	v_mfma_f32_16x16x32_bf16 v[18:21], v[168:171], v[184:187], v[18:21]
	v_mfma_f32_16x16x32_bf16 v[14:17], v[176:179], v[184:187], v[14:17]
	v_mfma_f32_16x16x32_bf16 v[10:13], v[168:171], v[192:195], v[10:13]
	v_mfma_f32_16x16x32_bf16 v[2:5], v[176:179], v[192:195], v[2:5]
	v_mfma_f32_16x16x32_bf16 v[54:57], v[168:171], v[226:229], v[54:57]
	v_mfma_f32_16x16x32_bf16 v[46:49], v[176:179], v[226:229], v[46:49]
	v_mfma_f32_16x16x32_bf16 v[42:45], v[168:171], v[234:237], v[42:45]
	v_mfma_f32_16x16x32_bf16 v[38:41], v[176:179], v[234:237], v[38:41]
	v_mfma_f32_16x16x32_bf16 v[6:9], v[62:65], v[234:237], v[6:9]
	s_setprio 0
	s_barrier
; #define PG8_STAGE(bufoff, gbase, voff) do { const char* _gb = (const char*)(gbase); asm volatile("" : "+s"(_gb)); _Pragma("unroll") for (int _i = 0; _i < 2; ++_i) { asm volatile("" : "+v"((voff)[_i])); \
;         __builtin_amdgcn_global_load_lds((const unsigned*)(_gb + (voff)[_i]), (PG8_LAS unsigned*)(lds + (bufoff) + ldsw + _i * 8192), 16, 0, 0); } } while (0)
; #define PG8_LDA(dst, b, h) do { _Pragma("unroll") for (int m = 0; m < 4; ++m) _Pragma("unroll") for (int k = 0; k < 2; ++k) dst[m][k] = *(const PG8_LAS bf16x8*)(lds + PG8_SA(b, h) + aoff + m * 2048 + k * 1024); } while (0)
; #define PG8_LDB(dst, b, h) do { _Pragma("unroll") for (int n = 0; n < 2; ++n) _Pragma("unroll") for (int k = 0; k < 2; ++k) dst[n][k] = *(const PG8_LAS bf16x8*)(lds + PG8_SB(b, h) + boff + n * 2048 + k * 1024); } while (0)
; #define PG8_WAIT_V(n) asm volatile("s_waitcnt vmcnt(" #n ")" ::: "memory")
; #define PG8_WAIT_L(n) asm volatile("s_waitcnt lgkmcnt(" #n ")" ::: "memory")
; #define PG8_BAR __builtin_amdgcn_s_barrier()
; #define PG8_SCHED __builtin_amdgcn_sched_barrier(0)
; #define PG8_STAGE(bufoff, gbase, voff) do { const char* _gb = (const char*)(gbase); asm volatile("" : "+s"(_gb)); _Pragma("unroll") for (int _i = 0; _i < 2; ++_i) { asm volatile("" : "+v"((voff)[_i])); \
;         __builtin_amdgcn_global_load_lds((const unsigned*)(_gb + (voff)[_i]), (PG8_LAS unsigned*)(lds + (bufoff) + ldsw + _i * 8192), 16, 0, 0); } } while (0)
; #define PG8_LDA(dst, b, h) do { _Pragma("unroll") for (int m = 0; m < 4; ++m) _Pragma("unroll") for (int k = 0; k < 2; ++k) dst[m][k] = *(const PG8_LAS bf16x8*)(lds + PG8_SA(b, h) + aoff + m * 2048 + k * 1024); } while (0)
; template <class Epi, class Sched, bool ALIGN_EPI = false, bool SP2 = false>
; __device__ __forceinline__ void gemm_phase(PG8_LAS unsigned char* lds, const Gemm g, const Sched& S, const Epi& E) {
;     ...
;             PG8_LDB(B0, 1, 0); PG8_LDB(B1, 1, 1); PG8_SCHED; PG8_LDA(At, 1, 0); PG8_STAGE(PG8_SA(0, 1), a2 + hstep, voffA);
;             PG8_WAIT_V(8); PG8_WAIT_L(0); PG8_BAR; PG8_MMA2(0); PG8_BAR; PG8_SCHED;
;             PG8_LDA(At, 1, 1); PG8_STAGE(PG8_SB(1, 0), b3, voffB); PG8_STAGE(PG8_SB(1, 1), b3 + hstep, voffB); PG8_STAGE(PG8_SA(1, 0), a3, voffA);
;             PG8_WAIT_V(8); PG8_WAIT_L(0); PG8_BAR; PG8_MMA2(1); PG8_BAR; PG8_SCHED;
;     ...
;         if constexpr (ALIGN_EPI) { if (wr == 0) PG8_BAR; }
	s_add_i32 s84, 0, 0x18000
	s_add_i32 s85, 0, 0x1c000
	v_add_u32_e32 v142, s84, v201
	v_add_u32_e32 v147, s85, v201
	ds_read_b128 v[58:61], v142
	ds_read_b128 v[62:65], v142 offset:1024
	ds_read_b128 v[138:141], v142 offset:2048
	ds_read_b128 v[142:145], v142 offset:3072
	ds_read_b128 v[164:167], v147
	ds_read_b128 v[168:171], v147 offset:1024
	ds_read_b128 v[172:175], v147 offset:2048
	ds_read_b128 v[176:179], v147 offset:3072
	s_add_u32 s12, s18, 0x100000
	s_addc_u32 s13, s19, 0
	s_mov_b32 m0, s47
	ds_read_b128 v[180:183], v219 offset:32768
	ds_read_b128 v[184:187], v219 offset:33792
	ds_read_b128 v[188:191], v219 offset:34816
	ds_read_b128 v[192:195], v219 offset:35840
	ds_read_b128 v[222:225], v219 offset:36864
	ds_read_b128 v[226:229], v219 offset:37888
	ds_read_b128 v[230:233], v219 offset:38912
	ds_read_b128 v[234:237], v219 offset:39936
	s_nop 0
	global_load_lds_dwordx4 v1, s[12:13]
	s_mov_b32 m0, s87
	s_nop 0
	global_load_lds_dwordx4 v199, s[12:13]
	s_nop 0
	s_nop 0
	s_setprio 1
	s_waitcnt vmcnt(8) lgkmcnt(0)
	s_barrier
	v_mfma_f32_16x16x32_bf16 v[118:121], v[58:61], v[180:183], v[118:121]
	v_mfma_f32_16x16x32_bf16 v[114:117], v[138:141], v[180:183], v[114:117]
	v_mfma_f32_16x16x32_bf16 v[106:109], v[58:61], v[188:191], v[106:109]
	v_mfma_f32_16x16x32_bf16 v[86:89], v[138:141], v[188:191], v[86:89]
	v_mfma_f32_16x16x32_bf16 v[134:137], v[58:61], v[222:225], v[134:137]
	v_mfma_f32_16x16x32_bf16 v[90:93], v[138:141], v[222:225], v[90:93]
	v_mfma_f32_16x16x32_bf16 v[130:133], v[58:61], v[230:233], v[130:133]
	v_mfma_f32_16x16x32_bf16 v[110:113], v[138:141], v[230:233], v[110:113]
	v_mfma_f32_16x16x32_bf16 v[94:97], v[164:167], v[180:183], v[94:97]
	v_mfma_f32_16x16x32_bf16 v[82:85], v[172:175], v[180:183], v[82:85]
	v_mfma_f32_16x16x32_bf16 v[78:81], v[164:167], v[188:191], v[78:81]
	v_mfma_f32_16x16x32_bf16 v[74:77], v[172:175], v[188:191], v[74:77]
	v_mfma_f32_16x16x32_bf16 v[126:129], v[164:167], v[222:225], v[126:129]
	v_mfma_f32_16x16x32_bf16 v[98:101], v[172:175], v[222:225], v[98:101]
	v_mfma_f32_16x16x32_bf16 v[122:125], v[164:167], v[230:233], v[122:125]
	v_mfma_f32_16x16x32_bf16 v[102:105], v[172:175], v[230:233], v[102:105]
	v_mfma_f32_16x16x32_bf16 v[118:121], v[62:65], v[184:187], v[118:121]
	v_mfma_f32_16x16x32_bf16 v[114:117], v[142:145], v[184:187], v[114:117]
	v_mfma_f32_16x16x32_bf16 v[106:109], v[62:65], v[192:195], v[106:109]
	v_mfma_f32_16x16x32_bf16 v[86:89], v[142:145], v[192:195], v[86:89]
	v_mfma_f32_16x16x32_bf16 v[134:137], v[62:65], v[226:229], v[134:137]
	v_mfma_f32_16x16x32_bf16 v[90:93], v[142:145], v[226:229], v[90:93]
	v_mfma_f32_16x16x32_bf16 v[130:133], v[62:65], v[234:237], v[130:133]
	v_mfma_f32_16x16x32_bf16 v[110:113], v[142:145], v[234:237], v[110:113]
	v_mfma_f32_16x16x32_bf16 v[94:97], v[168:171], v[184:187], v[94:97]
	v_mfma_f32_16x16x32_bf16 v[82:85], v[176:179], v[184:187], v[82:85]
	v_mfma_f32_16x16x32_bf16 v[78:81], v[168:171], v[192:195], v[78:81]
	v_mfma_f32_16x16x32_bf16 v[74:77], v[176:179], v[192:195], v[74:77]
	v_mfma_f32_16x16x32_bf16 v[126:129], v[168:171], v[226:229], v[126:129]
	v_mfma_f32_16x16x32_bf16 v[98:101], v[176:179], v[226:229], v[98:101]
	v_mfma_f32_16x16x32_bf16 v[122:125], v[168:171], v[234:237], v[122:125]
	v_mfma_f32_16x16x32_bf16 v[102:105], v[176:179], v[234:237], v[102:105]
	s_setprio 0
	s_barrier
	s_add_u32 s12, s16, 0x80
	s_addc_u32 s13, s17, 0
	s_add_i32 s18, s84, s25
	s_mov_b32 m0, s18
	ds_read_b128 v[180:183], v219 offset:49152
	ds_read_b128 v[184:187], v219 offset:50176
	ds_read_b128 v[188:191], v219 offset:51200
	ds_read_b128 v[192:195], v219 offset:52224
	ds_read_b128 v[222:225], v219 offset:53248
	ds_read_b128 v[226:229], v219 offset:54272
	ds_read_b128 v[230:233], v219 offset:55296
	ds_read_b128 v[234:237], v219 offset:56320
	s_nop 0
	global_load_lds_dwordx4 v198, s[12:13]
	s_add_i32 m0, s18, 0x2000
	s_nop 0
	global_load_lds_dwordx4 v200, s[12:13]
	s_add_u32 s12, s16, 0x100080
	s_addc_u32 s13, s17, 0
	s_add_i32 s16, s85, s25
	s_mov_b32 m0, s16
	s_nop 0
	global_load_lds_dwordx4 v198, s[12:13]
	s_add_i32 m0, s16, 0x2000
	s_nop 0
	global_load_lds_dwordx4 v200, s[12:13]
	s_mov_b32 m0, s71
	s_nop 0
	global_load_lds_dwordx4 v1, s[2:3]
	s_mov_b32 m0, s72
	s_nop 0
	global_load_lds_dwordx4 v199, s[2:3]
	s_nop 0
	s_nop 0
	s_setprio 1
	s_waitcnt vmcnt(8) lgkmcnt(0)
	s_barrier
	v_mfma_f32_16x16x32_bf16 v[6:9], v[58:61], v[230:233], v[6:9]
	v_mfma_f32_16x16x32_bf16 v[34:37], v[58:61], v[180:183], v[34:37]
	v_mfma_f32_16x16x32_bf16 v[26:29], v[58:61], v[188:191], v[26:29]
	v_mfma_f32_16x16x32_bf16 v[70:73], v[58:61], v[222:225], v[70:73]
	v_mfma_f32_16x16x32_bf16 v[58:61], v[62:65], v[234:237], v[6:9]
	v_mfma_f32_16x16x32_bf16 v[6:9], v[138:141], v[230:233], v[50:53]
	v_mfma_f32_16x16x32_bf16 v[50:53], v[142:145], v[234:237], v[6:9]
	v_mfma_f32_16x16x32_bf16 v[6:9], v[164:167], v[180:183], v[18:21]
	v_mfma_f32_16x16x32_bf16 v[18:21], v[168:171], v[184:187], v[6:9]
	v_mfma_f32_16x16x32_bf16 v[6:9], v[172:175], v[180:183], v[14:17]
	v_mfma_f32_16x16x32_bf16 v[14:17], v[176:179], v[184:187], v[6:9]
	v_mfma_f32_16x16x32_bf16 v[6:9], v[164:167], v[188:191], v[10:13]
	v_mfma_f32_16x16x32_bf16 v[10:13], v[168:171], v[192:195], v[6:9]
	v_mfma_f32_16x16x32_bf16 v[6:9], v[164:167], v[222:225], v[54:57]
	v_mfma_f32_16x16x32_bf16 v[54:57], v[168:171], v[226:229], v[6:9]
	v_mfma_f32_16x16x32_bf16 v[6:9], v[172:175], v[222:225], v[46:49]
	v_mfma_f32_16x16x32_bf16 v[46:49], v[176:179], v[226:229], v[6:9]
	v_mfma_f32_16x16x32_bf16 v[6:9], v[164:167], v[230:233], v[42:45]
	v_mfma_f32_16x16x32_bf16 v[30:33], v[138:141], v[180:183], v[30:33]
	v_mfma_f32_16x16x32_bf16 v[22:25], v[138:141], v[188:191], v[22:25]
	v_mfma_f32_16x16x32_bf16 v[66:69], v[138:141], v[222:225], v[66:69]
	v_mfma_f32_16x16x32_bf16 v[2:5], v[172:175], v[188:191], v[2:5]
	v_mfma_f32_16x16x32_bf16 v[42:45], v[168:171], v[234:237], v[6:9]
	v_mfma_f32_16x16x32_bf16 v[6:9], v[172:175], v[230:233], v[38:41]
	v_mfma_f32_16x16x32_bf16 v[34:37], v[62:65], v[184:187], v[34:37]
	v_mfma_f32_16x16x32_bf16 v[30:33], v[142:145], v[184:187], v[30:33]
	v_mfma_f32_16x16x32_bf16 v[26:29], v[62:65], v[192:195], v[26:29]
	v_mfma_f32_16x16x32_bf16 v[22:25], v[142:145], v[192:195], v[22:25]
	v_mfma_f32_16x16x32_bf16 v[70:73], v[62:65], v[226:229], v[70:73]
	v_mfma_f32_16x16x32_bf16 v[66:69], v[142:145], v[226:229], v[66:69]
	v_mfma_f32_16x16x32_bf16 v[2:5], v[176:179], v[192:195], v[2:5]
	v_mfma_f32_16x16x32_bf16 v[38:41], v[176:179], v[234:237], v[6:9]
	s_setprio 0
	s_barrier
	s_add_i32 s83, s83, 2
	s_add_u32 s62, s62, 0x100
	s_addc_u32 s63, s63, 0
	s_cmp_gt_u32 s83, 61
	s_mov_b64 s[12:13], s[14:15]
	s_cbranch_scc0 .LBB0_933
	s_and_b64 vcc, exec, s[38:39]
	s_cbranch_vccz .LBB0_936
	s_barrier

; #define PG8_STAGE(bufoff, gbase, voff) do { const char* _gb = (const char*)(gbase); asm volatile("" : "+s"(_gb)); _Pragma("unroll") for (int _i = 0; _i < 2; ++_i) { asm volatile("" : "+v"((voff)[_i])); \
;         __builtin_amdgcn_global_load_lds((const unsigned*)(_gb + (voff)[_i]), (PG8_LAS unsigned*)(lds + (bufoff) + ldsw + _i * 8192), 16, 0, 0); } } while (0)
; #define PG8_LDA(dst, b, h) do { _Pragma("unroll") for (int m = 0; m < 4; ++m) _Pragma("unroll") for (int k = 0; k < 2; ++k) dst[m][k] = *(const PG8_LAS bf16x8*)(lds + PG8_SA(b, h) + aoff + m * 2048 + k * 1024); } while (0)
; #define PG8_LDB(dst, b, h) do { _Pragma("unroll") for (int n = 0; n < 2; ++n) _Pragma("unroll") for (int k = 0; k < 2; ++k) dst[n][k] = *(const PG8_LAS bf16x8*)(lds + PG8_SB(b, h) + boff + n * 2048 + k * 1024); } while (0)
; #define PG8_WAIT_V(n) asm volatile("s_waitcnt vmcnt(" #n ")" ::: "memory")
; #define PG8_WAIT_L(n) asm volatile("s_waitcnt lgkmcnt(" #n ")" ::: "memory")
; #define PG8_BAR __builtin_amdgcn_s_barrier()
; #define PG8_SCHED __builtin_amdgcn_sched_barrier(0)
; #define PG8_STAGE(bufoff, gbase, voff) do { const char* _gb = (const char*)(gbase); asm volatile("" : "+s"(_gb)); _Pragma("unroll") for (int _i = 0; _i < 2; ++_i) { asm volatile("" : "+v"((voff)[_i])); \
;         __builtin_amdgcn_global_load_lds((const unsigned*)(_gb + (voff)[_i]), (PG8_LAS unsigned*)(lds + (bufoff) + ldsw + _i * 8192), 16, 0, 0); } } while (0)
; #define PG8_LDA(dst, b, h) do { _Pragma("unroll") for (int m = 0; m < 4; ++m) _Pragma("unroll") for (int k = 0; k < 2; ++k) dst[m][k] = *(const PG8_LAS bf16x8*)(lds + PG8_SA(b, h) + aoff + m * 2048 + k * 1024); } while (0)
; #define PG8_WAIT_V(n) asm volatile("s_waitcnt vmcnt(" #n ")" ::: "memory")
; template <class Epi, class Sched, bool ALIGN_EPI = false, bool SP2 = false>
; __device__ __forceinline__ void gemm_phase(PG8_LAS unsigned char* lds, const Gemm g, const Sched& S, const Epi& E) {
;     ...
;             PG8_LDB(B0, 0, 0); PG8_LDB(B1, 0, 1); PG8_SCHED; PG8_LDA(At, 0, 0); PG8_STAGE(PG8_SA(1, 1), a1 + hstep, voffA);
;             PG8_WAIT_V(8); PG8_WAIT_L(0); PG8_BAR; PG8_MMA2(0); PG8_BAR; PG8_SCHED;
;             PG8_LDA(At, 0, 1); PG8_STAGE(PG8_SB(0, 0), b2, voffB); PG8_STAGE(PG8_SB(0, 1), b2 + hstep, voffB); PG8_STAGE(PG8_SA(0, 0), a2, voffA);
;             PG8_WAIT_V(8); PG8_WAIT_L(0); PG8_BAR; PG8_MMA2(1); PG8_BAR; PG8_SCHED;
.LBB0_1125:
	ds_read_b128 v[130:133], v162
	ds_read_b128 v[134:137], v162 offset:1024
	ds_read_b128 v[138:141], v162 offset:2048
	ds_read_b128 v[142:145], v162 offset:3072
	ds_read_b128 v[150:153], v163
	ds_read_b128 v[166:169], v163 offset:1024
	ds_read_b128 v[170:173], v163 offset:2048
	ds_read_b128 v[174:177], v163 offset:3072
	s_add_u32 s20, s16, 0x100
	s_addc_u32 s21, s17, 0
	s_cmpk_eq_i32 s53, 0xbc
	s_cselect_b32 s26, s6, s20
	s_cselect_b32 s27, s7, s21
	s_cselect_b32 s24, s18, s51
	s_cselect_b32 s25, s19, s52
	s_add_u32 s2, s26, 0x80
	s_addc_u32 s3, s27, 0
	s_add_u32 s16, s16, 0x300080
	s_addc_u32 s17, s17, 0
	s_add_i32 m0, s34, 0xc000
	ds_read_b128 v[178:181], v164
	ds_read_b128 v[182:185], v164 offset:1024
	ds_read_b128 v[186:189], v164 offset:2048
	ds_read_b128 v[190:193], v164 offset:3072
	ds_read_b128 v[194:197], v164 offset:4096
	ds_read_b128 v[198:201], v164 offset:5120
	ds_read_b128 v[202:205], v164 offset:6144
	ds_read_b128 v[206:209], v164 offset:7168
	s_nop 0
	global_load_lds_dwordx4 v1, s[16:17]
	s_add_i32 m0, s34, 0xe000
	s_nop 0
	global_load_lds_dwordx4 v157, s[16:17]
	s_nop 0
	s_nop 0
	s_setprio 1
	s_waitcnt vmcnt(8) lgkmcnt(0)
	s_barrier
	v_mfma_f32_16x16x32_bf16 v[126:129], v[130:133], v[178:181], v[126:129]
	v_mfma_f32_16x16x32_bf16 v[122:125], v[138:141], v[178:181], v[122:125]
	v_mfma_f32_16x16x32_bf16 v[110:113], v[130:133], v[186:189], v[110:113]
	v_mfma_f32_16x16x32_bf16 v[106:109], v[138:141], v[186:189], v[106:109]
	v_mfma_f32_16x16x32_bf16 v[94:97], v[130:133], v[194:197], v[94:97]
	v_mfma_f32_16x16x32_bf16 v[90:93], v[138:141], v[194:197], v[90:93]
	v_mfma_f32_16x16x32_bf16 v[78:81], v[130:133], v[202:205], v[78:81]
	v_mfma_f32_16x16x32_bf16 v[74:77], v[138:141], v[202:205], v[74:77]
	v_mfma_f32_16x16x32_bf16 v[118:121], v[150:153], v[178:181], v[118:121]
	v_mfma_f32_16x16x32_bf16 v[114:117], v[170:173], v[178:181], v[114:117]
	v_mfma_f32_16x16x32_bf16 v[102:105], v[150:153], v[186:189], v[102:105]
	v_mfma_f32_16x16x32_bf16 v[98:101], v[170:173], v[186:189], v[98:101]
	v_mfma_f32_16x16x32_bf16 v[86:89], v[150:153], v[194:197], v[86:89]
	v_mfma_f32_16x16x32_bf16 v[82:85], v[170:173], v[194:197], v[82:85]
	v_mfma_f32_16x16x32_bf16 v[70:73], v[150:153], v[202:205], v[70:73]
	v_mfma_f32_16x16x32_bf16 v[66:69], v[170:173], v[202:205], v[66:69]
	v_mfma_f32_16x16x32_bf16 v[126:129], v[134:137], v[182:185], v[126:129]
	v_mfma_f32_16x16x32_bf16 v[122:125], v[142:145], v[182:185], v[122:125]
	v_mfma_f32_16x16x32_bf16 v[110:113], v[134:137], v[190:193], v[110:113]
	v_mfma_f32_16x16x32_bf16 v[106:109], v[142:145], v[190:193], v[106:109]
	v_mfma_f32_16x16x32_bf16 v[94:97], v[134:137], v[198:201], v[94:97]
	v_mfma_f32_16x16x32_bf16 v[90:93], v[142:145], v[198:201], v[90:93]
	v_mfma_f32_16x16x32_bf16 v[78:81], v[134:137], v[206:209], v[78:81]
	v_mfma_f32_16x16x32_bf16 v[74:77], v[142:145], v[206:209], v[74:77]
	v_mfma_f32_16x16x32_bf16 v[118:121], v[166:169], v[182:185], v[118:121]
	v_mfma_f32_16x16x32_bf16 v[114:117], v[174:177], v[182:185], v[114:117]
	v_mfma_f32_16x16x32_bf16 v[102:105], v[166:169], v[190:193], v[102:105]
	v_mfma_f32_16x16x32_bf16 v[98:101], v[174:177], v[190:193], v[98:101]
	v_mfma_f32_16x16x32_bf16 v[86:89], v[166:169], v[198:201], v[86:89]
	v_mfma_f32_16x16x32_bf16 v[82:85], v[174:177], v[198:201], v[82:85]
	v_mfma_f32_16x16x32_bf16 v[70:73], v[166:169], v[206:209], v[70:73]
	v_mfma_f32_16x16x32_bf16 v[66:69], v[174:177], v[206:209], v[66:69]
	s_setprio 0
	s_barrier
	s_add_i32 s54, s43, s33
	s_mov_b64 s[16:17], s[24:25]
	s_mov_b32 m0, s54
	ds_read_b128 v[178:181], v164 offset:16384
	ds_read_b128 v[182:185], v164 offset:17408
	ds_read_b128 v[186:189], v164 offset:18432
	ds_read_b128 v[190:193], v164 offset:19456
	ds_read_b128 v[194:197], v164 offset:20480
	ds_read_b128 v[198:201], v164 offset:21504
	ds_read_b128 v[202:205], v164 offset:22528
	ds_read_b128 v[206:209], v164 offset:23552
	s_nop 0
	global_load_lds_dwordx4 v156, s[16:17]
	s_add_i32 m0, s54, 0x2000
	s_nop 0
	global_load_lds_dwordx4 v158, s[16:17]
	s_add_u32 s16, s24, 0x300000
	s_addc_u32 s17, s25, 0
	s_add_i32 s54, s44, s33
	s_mov_b32 m0, s54
	s_nop 0
	global_load_lds_dwordx4 v156, s[16:17]
	s_add_i32 m0, s54, 0x2000
	s_nop 0
	global_load_lds_dwordx4 v158, s[16:17]
	s_mov_b64 s[16:17], s[26:27]
	s_mov_b32 m0, s34
	s_nop 0
	global_load_lds_dwordx4 v1, s[16:17]
	s_mov_b32 m0, s35
	s_nop 0
	global_load_lds_dwordx4 v157, s[16:17]
	s_nop 0
	s_nop 0
	s_setprio 1
	s_waitcnt vmcnt(8) lgkmcnt(0)
	s_barrier
	v_mfma_f32_16x16x32_bf16 v[62:65], v[130:133], v[178:181], v[62:65]
	v_mfma_f32_16x16x32_bf16 v[58:61], v[138:141], v[178:181], v[58:61]
	v_mfma_f32_16x16x32_bf16 v[46:49], v[130:133], v[186:189], v[46:49]
	v_mfma_f32_16x16x32_bf16 v[42:45], v[138:141], v[186:189], v[42:45]
	v_mfma_f32_16x16x32_bf16 v[30:33], v[130:133], v[194:197], v[30:33]
	v_mfma_f32_16x16x32_bf16 v[26:29], v[138:141], v[194:197], v[26:29]
	v_mfma_f32_16x16x32_bf16 v[14:17], v[130:133], v[202:205], v[14:17]
	v_mfma_f32_16x16x32_bf16 v[10:13], v[138:141], v[202:205], v[10:13]
	v_mfma_f32_16x16x32_bf16 v[54:57], v[150:153], v[178:181], v[54:57]
	v_mfma_f32_16x16x32_bf16 v[50:53], v[170:173], v[178:181], v[50:53]
	v_mfma_f32_16x16x32_bf16 v[38:41], v[150:153], v[186:189], v[38:41]
	v_mfma_f32_16x16x32_bf16 v[34:37], v[170:173], v[186:189], v[34:37]
	v_mfma_f32_16x16x32_bf16 v[22:25], v[150:153], v[194:197], v[22:25]
	v_mfma_f32_16x16x32_bf16 v[18:21], v[170:173], v[194:197], v[18:21]
	v_mfma_f32_16x16x32_bf16 v[6:9], v[150:153], v[202:205], v[6:9]
	v_mfma_f32_16x16x32_bf16 v[2:5], v[170:173], v[202:205], v[2:5]
	v_mfma_f32_16x16x32_bf16 v[62:65], v[134:137], v[182:185], v[62:65]
	v_mfma_f32_16x16x32_bf16 v[58:61], v[142:145], v[182:185], v[58:61]
	v_mfma_f32_16x16x32_bf16 v[46:49], v[134:137], v[190:193], v[46:49]
	v_mfma_f32_16x16x32_bf16 v[42:45], v[142:145], v[190:193], v[42:45]
	v_mfma_f32_16x16x32_bf16 v[30:33], v[134:137], v[198:201], v[30:33]
	v_mfma_f32_16x16x32_bf16 v[26:29], v[142:145], v[198:201], v[26:29]
	v_mfma_f32_16x16x32_bf16 v[14:17], v[134:137], v[206:209], v[14:17]
	v_mfma_f32_16x16x32_bf16 v[10:13], v[142:145], v[206:209], v[10:13]
	v_mfma_f32_16x16x32_bf16 v[54:57], v[166:169], v[182:185], v[54:57]
	v_mfma_f32_16x16x32_bf16 v[50:53], v[174:177], v[182:185], v[50:53]
	v_mfma_f32_16x16x32_bf16 v[38:41], v[166:169], v[190:193], v[38:41]
	v_mfma_f32_16x16x32_bf16 v[34:37], v[174:177], v[190:193], v[34:37]
	v_mfma_f32_16x16x32_bf16 v[22:25], v[166:169], v[198:201], v[22:25]
	v_mfma_f32_16x16x32_bf16 v[18:21], v[174:177], v[198:201], v[18:21]
	v_mfma_f32_16x16x32_bf16 v[6:9], v[166:169], v[206:209], v[6:9]
	v_mfma_f32_16x16x32_bf16 v[2:5], v[174:177], v[206:209], v[2:5]
	s_setprio 0
	s_barrier
; #define PG8_STAGE(bufoff, gbase, voff) do { const char* _gb = (const char*)(gbase); asm volatile("" : "+s"(_gb)); _Pragma("unroll") for (int _i = 0; _i < 2; ++_i) { asm volatile("" : "+v"((voff)[_i])); \
;         __builtin_amdgcn_global_load_lds((const unsigned*)(_gb + (voff)[_i]), (PG8_LAS unsigned*)(lds + (bufoff) + ldsw + _i * 8192), 16, 0, 0); } } while (0)
; #define PG8_LDA(dst, b, h) do { _Pragma("unroll") for (int m = 0; m < 4; ++m) _Pragma("unroll") for (int k = 0; k < 2; ++k) dst[m][k] = *(const PG8_LAS bf16x8*)(lds + PG8_SA(b, h) + aoff + m * 2048 + k * 1024); } while (0)
; #define PG8_LDB(dst, b, h) do { _Pragma("unroll") for (int n = 0; n < 2; ++n) _Pragma("unroll") for (int k = 0; k < 2; ++k) dst[n][k] = *(const PG8_LAS bf16x8*)(lds + PG8_SB(b, h) + boff + n * 2048 + k * 1024); } while (0)
; #define PG8_WAIT_V(n) asm volatile("s_waitcnt vmcnt(" #n ")" ::: "memory")
; #define PG8_WAIT_L(n) asm volatile("s_waitcnt lgkmcnt(" #n ")" ::: "memory")
; #define PG8_BAR __builtin_amdgcn_s_barrier()
; #define PG8_SCHED __builtin_amdgcn_sched_barrier(0)
; #define PG8_STAGE(bufoff, gbase, voff) do { const char* _gb = (const char*)(gbase); asm volatile("" : "+s"(_gb)); _Pragma("unroll") for (int _i = 0; _i < 2; ++_i) { asm volatile("" : "+v"((voff)[_i])); \
;         __builtin_amdgcn_global_load_lds((const unsigned*)(_gb + (voff)[_i]), (PG8_LAS unsigned*)(lds + (bufoff) + ldsw + _i * 8192), 16, 0, 0); } } while (0)
; #define PG8_LDA(dst, b, h) do { _Pragma("unroll") for (int m = 0; m < 4; ++m) _Pragma("unroll") for (int k = 0; k < 2; ++k) dst[m][k] = *(const PG8_LAS bf16x8*)(lds + PG8_SA(b, h) + aoff + m * 2048 + k * 1024); } while (0)
; template <class Epi, class Sched, bool ALIGN_EPI = false, bool SP2 = false>
; __device__ __forceinline__ void gemm_phase(PG8_LAS unsigned char* lds, const Gemm g, const Sched& S, const Epi& E) {
;     ...
;             PG8_LDB(B0, 1, 0); PG8_LDB(B1, 1, 1); PG8_SCHED; PG8_LDA(At, 1, 0); PG8_STAGE(PG8_SA(0, 1), a2 + hstep, voffA);
;             PG8_WAIT_V(8); PG8_WAIT_L(0); PG8_BAR; PG8_MMA2(0); PG8_BAR; PG8_SCHED;
;             PG8_LDA(At, 1, 1); PG8_STAGE(PG8_SB(1, 0), b3, voffB); PG8_STAGE(PG8_SB(1, 1), b3 + hstep, voffB); PG8_STAGE(PG8_SA(1, 0), a3, voffA);
;             PG8_WAIT_V(8); PG8_WAIT_L(0); PG8_BAR; PG8_MMA2(1); PG8_BAR; PG8_SCHED;
;     ...
;         if constexpr (ALIGN_EPI) { if (wr == 0) PG8_BAR; }
	s_add_i32 s54, 0, 0x18000
	s_add_i32 s55, 0, 0x1c000
	v_add_u32_e32 v142, s54, v160
	v_add_u32_e32 v154, s55, v160
	ds_read_b128 v[130:133], v142
	ds_read_b128 v[134:137], v142 offset:1024
	ds_read_b128 v[138:141], v142 offset:2048
	ds_read_b128 v[142:145], v142 offset:3072
	ds_read_b128 v[150:153], v154
	ds_read_b128 v[166:169], v154 offset:1024
	ds_read_b128 v[170:173], v154 offset:2048
	ds_read_b128 v[174:177], v154 offset:3072
	s_add_u32 s16, s26, 0x300000
	s_addc_u32 s17, s27, 0
	s_mov_b32 m0, s36
	ds_read_b128 v[178:181], v164 offset:32768
	ds_read_b128 v[182:185], v164 offset:33792
	ds_read_b128 v[186:189], v164 offset:34816
	ds_read_b128 v[190:193], v164 offset:35840
	ds_read_b128 v[194:197], v164 offset:36864
	ds_read_b128 v[198:201], v164 offset:37888
	ds_read_b128 v[202:205], v164 offset:38912
	ds_read_b128 v[206:209], v164 offset:39936
	s_nop 0
	global_load_lds_dwordx4 v1, s[16:17]
	s_mov_b32 m0, s37
	s_nop 0
	global_load_lds_dwordx4 v157, s[16:17]
	s_nop 0
	s_nop 0
	s_setprio 1
	s_waitcnt vmcnt(8) lgkmcnt(0)
	s_barrier
	v_mfma_f32_16x16x32_bf16 v[126:129], v[130:133], v[178:181], v[126:129]
	v_mfma_f32_16x16x32_bf16 v[122:125], v[138:141], v[178:181], v[122:125]
	v_mfma_f32_16x16x32_bf16 v[110:113], v[130:133], v[186:189], v[110:113]
	v_mfma_f32_16x16x32_bf16 v[106:109], v[138:141], v[186:189], v[106:109]
	v_mfma_f32_16x16x32_bf16 v[94:97], v[130:133], v[194:197], v[94:97]
	v_mfma_f32_16x16x32_bf16 v[90:93], v[138:141], v[194:197], v[90:93]
	v_mfma_f32_16x16x32_bf16 v[78:81], v[130:133], v[202:205], v[78:81]
	v_mfma_f32_16x16x32_bf16 v[74:77], v[138:141], v[202:205], v[74:77]
	v_mfma_f32_16x16x32_bf16 v[118:121], v[150:153], v[178:181], v[118:121]
	v_mfma_f32_16x16x32_bf16 v[114:117], v[170:173], v[178:181], v[114:117]
	v_mfma_f32_16x16x32_bf16 v[102:105], v[150:153], v[186:189], v[102:105]
	v_mfma_f32_16x16x32_bf16 v[98:101], v[170:173], v[186:189], v[98:101]
	v_mfma_f32_16x16x32_bf16 v[86:89], v[150:153], v[194:197], v[86:89]
	v_mfma_f32_16x16x32_bf16 v[82:85], v[170:173], v[194:197], v[82:85]
	v_mfma_f32_16x16x32_bf16 v[70:73], v[150:153], v[202:205], v[70:73]
	v_mfma_f32_16x16x32_bf16 v[66:69], v[170:173], v[202:205], v[66:69]
	v_mfma_f32_16x16x32_bf16 v[126:129], v[134:137], v[182:185], v[126:129]
	v_mfma_f32_16x16x32_bf16 v[122:125], v[142:145], v[182:185], v[122:125]
	v_mfma_f32_16x16x32_bf16 v[110:113], v[134:137], v[190:193], v[110:113]
	v_mfma_f32_16x16x32_bf16 v[106:109], v[142:145], v[190:193], v[106:109]
	v_mfma_f32_16x16x32_bf16 v[94:97], v[134:137], v[198:201], v[94:97]
	v_mfma_f32_16x16x32_bf16 v[90:93], v[142:145], v[198:201], v[90:93]
	v_mfma_f32_16x16x32_bf16 v[78:81], v[134:137], v[206:209], v[78:81]
	v_mfma_f32_16x16x32_bf16 v[74:77], v[142:145], v[206:209], v[74:77]
	v_mfma_f32_16x16x32_bf16 v[118:121], v[166:169], v[182:185], v[118:121]
	v_mfma_f32_16x16x32_bf16 v[114:117], v[174:177], v[182:185], v[114:117]
	v_mfma_f32_16x16x32_bf16 v[102:105], v[166:169], v[190:193], v[102:105]
	v_mfma_f32_16x16x32_bf16 v[98:101], v[174:177], v[190:193], v[98:101]
	v_mfma_f32_16x16x32_bf16 v[86:89], v[166:169], v[198:201], v[86:89]
	v_mfma_f32_16x16x32_bf16 v[82:85], v[174:177], v[198:201], v[82:85]
	v_mfma_f32_16x16x32_bf16 v[70:73], v[166:169], v[206:209], v[70:73]
	v_mfma_f32_16x16x32_bf16 v[66:69], v[174:177], v[206:209], v[66:69]
	s_setprio 0
	s_barrier
	s_add_u32 s16, s24, 0x80
	s_addc_u32 s17, s25, 0
	s_add_i32 s26, s54, s33
	s_mov_b32 m0, s26
	ds_read_b128 v[178:181], v164 offset:49152
	ds_read_b128 v[182:185], v164 offset:50176
	ds_read_b128 v[186:189], v164 offset:51200
	ds_read_b128 v[190:193], v164 offset:52224
	ds_read_b128 v[194:197], v164 offset:53248
	ds_read_b128 v[198:201], v164 offset:54272
	ds_read_b128 v[202:205], v164 offset:55296
	ds_read_b128 v[206:209], v164 offset:56320
	s_nop 0
	global_load_lds_dwordx4 v156, s[16:17]
	s_add_i32 m0, s26, 0x2000
	s_nop 0
	global_load_lds_dwordx4 v158, s[16:17]
	s_add_u32 s16, s24, 0x300080
	s_addc_u32 s17, s25, 0
	s_add_i32 s24, s55, s33
	s_mov_b32 m0, s24
	s_nop 0
	global_load_lds_dwordx4 v156, s[16:17]
	s_add_i32 m0, s24, 0x2000
	s_nop 0
	global_load_lds_dwordx4 v158, s[16:17]
	s_mov_b32 m0, s39
	s_nop 0
	global_load_lds_dwordx4 v1, s[2:3]
	s_mov_b32 m0, s40
	s_nop 0
	global_load_lds_dwordx4 v157, s[2:3]
	s_nop 0
	s_nop 0
	s_setprio 1
	s_waitcnt vmcnt(8) lgkmcnt(0)
	s_barrier
	v_mfma_f32_16x16x32_bf16 v[62:65], v[130:133], v[178:181], v[62:65]
	v_mfma_f32_16x16x32_bf16 v[58:61], v[138:141], v[178:181], v[58:61]
	v_mfma_f32_16x16x32_bf16 v[46:49], v[130:133], v[186:189], v[46:49]
	v_mfma_f32_16x16x32_bf16 v[42:45], v[138:141], v[186:189], v[42:45]
	v_mfma_f32_16x16x32_bf16 v[30:33], v[130:133], v[194:197], v[30:33]
	v_mfma_f32_16x16x32_bf16 v[26:29], v[138:141], v[194:197], v[26:29]
	v_mfma_f32_16x16x32_bf16 v[14:17], v[130:133], v[202:205], v[14:17]
	v_mfma_f32_16x16x32_bf16 v[10:13], v[138:141], v[202:205], v[10:13]
	v_mfma_f32_16x16x32_bf16 v[54:57], v[150:153], v[178:181], v[54:57]
	v_mfma_f32_16x16x32_bf16 v[50:53], v[170:173], v[178:181], v[50:53]
	v_mfma_f32_16x16x32_bf16 v[38:41], v[150:153], v[186:189], v[38:41]
	v_mfma_f32_16x16x32_bf16 v[34:37], v[170:173], v[186:189], v[34:37]
	v_mfma_f32_16x16x32_bf16 v[22:25], v[150:153], v[194:197], v[22:25]
	v_mfma_f32_16x16x32_bf16 v[18:21], v[170:173], v[194:197], v[18:21]
	v_mfma_f32_16x16x32_bf16 v[6:9], v[150:153], v[202:205], v[6:9]
	v_mfma_f32_16x16x32_bf16 v[2:5], v[170:173], v[202:205], v[2:5]
	v_mfma_f32_16x16x32_bf16 v[62:65], v[134:137], v[182:185], v[62:65]
	v_mfma_f32_16x16x32_bf16 v[58:61], v[142:145], v[182:185], v[58:61]
	v_mfma_f32_16x16x32_bf16 v[46:49], v[134:137], v[190:193], v[46:49]
	v_mfma_f32_16x16x32_bf16 v[42:45], v[142:145], v[190:193], v[42:45]
	v_mfma_f32_16x16x32_bf16 v[30:33], v[134:137], v[198:201], v[30:33]
	v_mfma_f32_16x16x32_bf16 v[26:29], v[142:145], v[198:201], v[26:29]
	v_mfma_f32_16x16x32_bf16 v[14:17], v[134:137], v[206:209], v[14:17]
	v_mfma_f32_16x16x32_bf16 v[10:13], v[142:145], v[206:209], v[10:13]
	v_mfma_f32_16x16x32_bf16 v[54:57], v[166:169], v[182:185], v[54:57]
	v_mfma_f32_16x16x32_bf16 v[50:53], v[174:177], v[182:185], v[50:53]
	v_mfma_f32_16x16x32_bf16 v[38:41], v[166:169], v[190:193], v[38:41]
	v_mfma_f32_16x16x32_bf16 v[34:37], v[174:177], v[190:193], v[34:37]
	v_mfma_f32_16x16x32_bf16 v[22:25], v[166:169], v[198:201], v[22:25]
	v_mfma_f32_16x16x32_bf16 v[18:21], v[174:177], v[198:201], v[18:21]
	v_mfma_f32_16x16x32_bf16 v[6:9], v[166:169], v[206:209], v[6:9]
	v_mfma_f32_16x16x32_bf16 v[2:5], v[174:177], v[206:209], v[2:5]
	s_setprio 0
	s_barrier
	s_add_i32 s53, s53, 2
	s_add_u32 s51, s51, 0x100
	s_addc_u32 s52, s52, 0
	s_cmpk_gt_u32 s53, 0xbd
	s_mov_b64 s[16:17], s[20:21]
	s_cbranch_scc0 .LBB0_1125
	s_and_b64 vcc, exec, s[14:15]
	s_cbranch_vccz .LBB0_1128
	s_barrier

; #define PG8_STAGE(bufoff, gbase, voff) do { const char* _gb = (const char*)(gbase); asm volatile("" : "+s"(_gb)); _Pragma("unroll") for (int _i = 0; _i < 2; ++_i) { asm volatile("" : "+v"((voff)[_i])); \
;         __builtin_amdgcn_global_load_lds((const unsigned*)(_gb + (voff)[_i]), (PG8_LAS unsigned*)(lds + (bufoff) + ldsw + _i * 8192), 16, 0, 0); } } while (0)
; #define PG8_LDA(dst, b, h) do { _Pragma("unroll") for (int m = 0; m < 4; ++m) _Pragma("unroll") for (int k = 0; k < 2; ++k) dst[m][k] = *(const PG8_LAS bf16x8*)(lds + PG8_SA(b, h) + aoff + m * 2048 + k * 1024); } while (0)
; #define PG8_LDB(dst, b, h) do { _Pragma("unroll") for (int n = 0; n < 2; ++n) _Pragma("unroll") for (int k = 0; k < 2; ++k) dst[n][k] = *(const PG8_LAS bf16x8*)(lds + PG8_SB(b, h) + boff + n * 2048 + k * 1024); } while (0)
; #define PG8_WAIT_V(n) asm volatile("s_waitcnt vmcnt(" #n ")" ::: "memory")
; #define PG8_WAIT_L(n) asm volatile("s_waitcnt lgkmcnt(" #n ")" ::: "memory")
; #define PG8_BAR __builtin_amdgcn_s_barrier()
; #define PG8_SCHED __builtin_amdgcn_sched_barrier(0)
; #define PG8_STAGE(bufoff, gbase, voff) do { const char* _gb = (const char*)(gbase); asm volatile("" : "+s"(_gb)); _Pragma("unroll") for (int _i = 0; _i < 2; ++_i) { asm volatile("" : "+v"((voff)[_i])); \
;         __builtin_amdgcn_global_load_lds((const unsigned*)(_gb + (voff)[_i]), (PG8_LAS unsigned*)(lds + (bufoff) + ldsw + _i * 8192), 16, 0, 0); } } while (0)
; #define PG8_LDA(dst, b, h) do { _Pragma("unroll") for (int m = 0; m < 4; ++m) _Pragma("unroll") for (int k = 0; k < 2; ++k) dst[m][k] = *(const PG8_LAS bf16x8*)(lds + PG8_SA(b, h) + aoff + m * 2048 + k * 1024); } while (0)
; #define PG8_WAIT_V(n) asm volatile("s_waitcnt vmcnt(" #n ")" ::: "memory")
; template <class Epi, class Sched, bool ALIGN_EPI = false, bool SP2 = false>
; __device__ __forceinline__ void gemm_phase(PG8_LAS unsigned char* lds, const Gemm g, const Sched& S, const Epi& E) {
;     ...
;             PG8_LDB(B0, 0, 0); PG8_LDB(B1, 0, 1); PG8_SCHED; PG8_LDA(At, 0, 0); PG8_STAGE(PG8_SA(1, 1), a1 + hstep, voffA);
;             PG8_WAIT_V(8); PG8_WAIT_L(0); PG8_BAR; PG8_MMA2(0); PG8_BAR; PG8_SCHED;
;             PG8_LDA(At, 0, 1); PG8_STAGE(PG8_SB(0, 0), b2, voffB); PG8_STAGE(PG8_SB(0, 1), b2 + hstep, voffB); PG8_STAGE(PG8_SA(0, 0), a2, voffA);
;             PG8_WAIT_V(8); PG8_WAIT_L(0); PG8_BAR; PG8_MMA2(1); PG8_BAR; PG8_SCHED;
.LBB0_1217:
	ds_read_b128 v[128:131], v175
	ds_read_b128 v[132:135], v175 offset:1024
	ds_read_b128 v[136:139], v175 offset:2048
	ds_read_b128 v[140:143], v175 offset:3072
	ds_read_b128 v[152:155], v176
	ds_read_b128 v[156:159], v176 offset:1024
	ds_read_b128 v[160:163], v176 offset:2048
	ds_read_b128 v[184:187], v176 offset:3072
	s_add_u32 s28, s6, 0x100
	s_addc_u32 s29, s7, 0
	s_cmpk_eq_i32 s58, 0xbc
	s_cselect_b32 s36, s57, s28
	s_cselect_b32 s37, s56, s29
	s_cselect_b32 s34, s8, s4
	s_cselect_b32 s35, s9, s5
	s_add_u32 s30, s36, 0x80
	s_addc_u32 s31, s37, 0
	s_add_u32 s6, s6, 0x300080
	s_addc_u32 s7, s7, 0
	s_add_i32 m0, s41, 0xc000
	ds_read_b128 v[188:191], v177
	ds_read_b128 v[192:195], v177 offset:1024
	ds_read_b128 v[196:199], v177 offset:2048
	ds_read_b128 v[200:203], v177 offset:3072
	ds_read_b128 v[204:207], v177 offset:4096
	ds_read_b128 v[208:211], v177 offset:5120
	ds_read_b128 v[212:215], v177 offset:6144
	ds_read_b128 v[216:219], v177 offset:7168
	s_nop 0
	global_load_lds_dwordx4 v167, s[6:7]
	s_add_i32 m0, s41, 0xe000
	s_nop 0
	global_load_lds_dwordx4 v171, s[6:7]
	s_nop 0
	s_nop 0
	s_setprio 1
	s_waitcnt vmcnt(8) lgkmcnt(0)
	s_barrier
	v_mfma_f32_16x16x32_bf16 v[124:127], v[128:131], v[188:191], v[124:127]
	v_mfma_f32_16x16x32_bf16 v[120:123], v[136:139], v[188:191], v[120:123]
	v_mfma_f32_16x16x32_bf16 v[108:111], v[128:131], v[196:199], v[108:111]
	v_mfma_f32_16x16x32_bf16 v[104:107], v[136:139], v[196:199], v[104:107]
	v_mfma_f32_16x16x32_bf16 v[92:95], v[128:131], v[204:207], v[92:95]
	v_mfma_f32_16x16x32_bf16 v[88:91], v[136:139], v[204:207], v[88:91]
	v_mfma_f32_16x16x32_bf16 v[76:79], v[128:131], v[212:215], v[76:79]
	v_mfma_f32_16x16x32_bf16 v[72:75], v[136:139], v[212:215], v[72:75]
	v_mfma_f32_16x16x32_bf16 v[116:119], v[152:155], v[188:191], v[116:119]
	v_mfma_f32_16x16x32_bf16 v[112:115], v[160:163], v[188:191], v[112:115]
	v_mfma_f32_16x16x32_bf16 v[100:103], v[152:155], v[196:199], v[100:103]
	v_mfma_f32_16x16x32_bf16 v[96:99], v[160:163], v[196:199], v[96:99]
	v_mfma_f32_16x16x32_bf16 v[84:87], v[152:155], v[204:207], v[84:87]
	v_mfma_f32_16x16x32_bf16 v[80:83], v[160:163], v[204:207], v[80:83]
	v_mfma_f32_16x16x32_bf16 v[68:71], v[152:155], v[212:215], v[68:71]
	v_mfma_f32_16x16x32_bf16 v[64:67], v[160:163], v[212:215], v[64:67]
	v_mfma_f32_16x16x32_bf16 v[124:127], v[132:135], v[192:195], v[124:127]
	v_mfma_f32_16x16x32_bf16 v[120:123], v[140:143], v[192:195], v[120:123]
	v_mfma_f32_16x16x32_bf16 v[108:111], v[132:135], v[200:203], v[108:111]
	v_mfma_f32_16x16x32_bf16 v[104:107], v[140:143], v[200:203], v[104:107]
	v_mfma_f32_16x16x32_bf16 v[92:95], v[132:135], v[208:211], v[92:95]
	v_mfma_f32_16x16x32_bf16 v[88:91], v[140:143], v[208:211], v[88:91]
	v_mfma_f32_16x16x32_bf16 v[76:79], v[132:135], v[216:219], v[76:79]
	v_mfma_f32_16x16x32_bf16 v[72:75], v[140:143], v[216:219], v[72:75]
	v_mfma_f32_16x16x32_bf16 v[116:119], v[156:159], v[192:195], v[116:119]
	v_mfma_f32_16x16x32_bf16 v[112:115], v[184:187], v[192:195], v[112:115]
	v_mfma_f32_16x16x32_bf16 v[100:103], v[156:159], v[200:203], v[100:103]
	v_mfma_f32_16x16x32_bf16 v[96:99], v[184:187], v[200:203], v[96:99]
	v_mfma_f32_16x16x32_bf16 v[84:87], v[156:159], v[208:211], v[84:87]
	v_mfma_f32_16x16x32_bf16 v[80:83], v[184:187], v[208:211], v[80:83]
	v_mfma_f32_16x16x32_bf16 v[68:71], v[156:159], v[216:219], v[68:71]
	v_mfma_f32_16x16x32_bf16 v[64:67], v[184:187], v[216:219], v[64:67]
	s_setprio 0
	s_barrier
	s_add_i32 s59, s49, s39
	s_mov_b64 s[6:7], s[34:35]
	s_mov_b32 m0, s59
	ds_read_b128 v[188:191], v177 offset:16384
	ds_read_b128 v[192:195], v177 offset:17408
	ds_read_b128 v[196:199], v177 offset:18432
	ds_read_b128 v[200:203], v177 offset:19456
	ds_read_b128 v[204:207], v177 offset:20480
	ds_read_b128 v[208:211], v177 offset:21504
	ds_read_b128 v[212:215], v177 offset:22528
	ds_read_b128 v[216:219], v177 offset:23552
	s_nop 0
	global_load_lds_dwordx4 v169, s[6:7]
	s_add_i32 m0, s59, 0x2000
	s_nop 0
	global_load_lds_dwordx4 v172, s[6:7]
	s_add_u32 s6, s34, 0x300000
	s_addc_u32 s7, s35, 0
	s_add_i32 s59, s50, s39
	s_mov_b32 m0, s59
	s_nop 0
	global_load_lds_dwordx4 v169, s[6:7]
	s_add_i32 m0, s59, 0x2000
	s_nop 0
	global_load_lds_dwordx4 v172, s[6:7]
	s_mov_b64 s[6:7], s[36:37]
	s_mov_b32 m0, s41
	s_nop 0
	global_load_lds_dwordx4 v167, s[6:7]
	s_mov_b32 m0, s42
	s_nop 0
	global_load_lds_dwordx4 v171, s[6:7]
	s_nop 0
	s_nop 0
	s_setprio 1
	s_waitcnt vmcnt(8) lgkmcnt(0)
	s_barrier
	v_mfma_f32_16x16x32_bf16 v[60:63], v[128:131], v[188:191], v[60:63]
	v_mfma_f32_16x16x32_bf16 v[56:59], v[136:139], v[188:191], v[56:59]
	v_mfma_f32_16x16x32_bf16 v[44:47], v[128:131], v[196:199], v[44:47]
	v_mfma_f32_16x16x32_bf16 v[40:43], v[136:139], v[196:199], v[40:43]
	v_mfma_f32_16x16x32_bf16 v[28:31], v[128:131], v[204:207], v[28:31]
	v_mfma_f32_16x16x32_bf16 v[24:27], v[136:139], v[204:207], v[24:27]
	v_mfma_f32_16x16x32_bf16 v[12:15], v[128:131], v[212:215], v[12:15]
	v_mfma_f32_16x16x32_bf16 v[8:11], v[136:139], v[212:215], v[8:11]
	v_mfma_f32_16x16x32_bf16 v[52:55], v[152:155], v[188:191], v[52:55]
	v_mfma_f32_16x16x32_bf16 v[48:51], v[160:163], v[188:191], v[48:51]
	v_mfma_f32_16x16x32_bf16 v[36:39], v[152:155], v[196:199], v[36:39]
	v_mfma_f32_16x16x32_bf16 v[32:35], v[160:163], v[196:199], v[32:35]
	v_mfma_f32_16x16x32_bf16 v[20:23], v[152:155], v[204:207], v[20:23]
	v_mfma_f32_16x16x32_bf16 v[16:19], v[160:163], v[204:207], v[16:19]
	v_mfma_f32_16x16x32_bf16 v[4:7], v[152:155], v[212:215], v[4:7]
	v_mfma_f32_16x16x32_bf16 v[0:3], v[160:163], v[212:215], v[0:3]
	v_mfma_f32_16x16x32_bf16 v[60:63], v[132:135], v[192:195], v[60:63]
	v_mfma_f32_16x16x32_bf16 v[56:59], v[140:143], v[192:195], v[56:59]
	v_mfma_f32_16x16x32_bf16 v[44:47], v[132:135], v[200:203], v[44:47]
	v_mfma_f32_16x16x32_bf16 v[40:43], v[140:143], v[200:203], v[40:43]
	v_mfma_f32_16x16x32_bf16 v[28:31], v[132:135], v[208:211], v[28:31]
	v_mfma_f32_16x16x32_bf16 v[24:27], v[140:143], v[208:211], v[24:27]
	v_mfma_f32_16x16x32_bf16 v[12:15], v[132:135], v[216:219], v[12:15]
	v_mfma_f32_16x16x32_bf16 v[8:11], v[140:143], v[216:219], v[8:11]
	v_mfma_f32_16x16x32_bf16 v[52:55], v[156:159], v[192:195], v[52:55]
	v_mfma_f32_16x16x32_bf16 v[48:51], v[184:187], v[192:195], v[48:51]
	v_mfma_f32_16x16x32_bf16 v[36:39], v[156:159], v[200:203], v[36:39]
	v_mfma_f32_16x16x32_bf16 v[32:35], v[184:187], v[200:203], v[32:35]
	v_mfma_f32_16x16x32_bf16 v[20:23], v[156:159], v[208:211], v[20:23]
	v_mfma_f32_16x16x32_bf16 v[16:19], v[184:187], v[208:211], v[16:19]
	v_mfma_f32_16x16x32_bf16 v[4:7], v[156:159], v[216:219], v[4:7]
	v_mfma_f32_16x16x32_bf16 v[0:3], v[184:187], v[216:219], v[0:3]
	s_setprio 0
	s_barrier
; #define PG8_STAGE(bufoff, gbase, voff) do { const char* _gb = (const char*)(gbase); asm volatile("" : "+s"(_gb)); _Pragma("unroll") for (int _i = 0; _i < 2; ++_i) { asm volatile("" : "+v"((voff)[_i])); \
;         __builtin_amdgcn_global_load_lds((const unsigned*)(_gb + (voff)[_i]), (PG8_LAS unsigned*)(lds + (bufoff) + ldsw + _i * 8192), 16, 0, 0); } } while (0)
; #define PG8_LDA(dst, b, h) do { _Pragma("unroll") for (int m = 0; m < 4; ++m) _Pragma("unroll") for (int k = 0; k < 2; ++k) dst[m][k] = *(const PG8_LAS bf16x8*)(lds + PG8_SA(b, h) + aoff + m * 2048 + k * 1024); } while (0)
; #define PG8_LDB(dst, b, h) do { _Pragma("unroll") for (int n = 0; n < 2; ++n) _Pragma("unroll") for (int k = 0; k < 2; ++k) dst[n][k] = *(const PG8_LAS bf16x8*)(lds + PG8_SB(b, h) + boff + n * 2048 + k * 1024); } while (0)
; #define PG8_WAIT_V(n) asm volatile("s_waitcnt vmcnt(" #n ")" ::: "memory")
; #define PG8_WAIT_L(n) asm volatile("s_waitcnt lgkmcnt(" #n ")" ::: "memory")
; #define PG8_BAR __builtin_amdgcn_s_barrier()
; #define PG8_SCHED __builtin_amdgcn_sched_barrier(0)
; #define PG8_STAGE(bufoff, gbase, voff) do { const char* _gb = (const char*)(gbase); asm volatile("" : "+s"(_gb)); _Pragma("unroll") for (int _i = 0; _i < 2; ++_i) { asm volatile("" : "+v"((voff)[_i])); \
;         __builtin_amdgcn_global_load_lds((const unsigned*)(_gb + (voff)[_i]), (PG8_LAS unsigned*)(lds + (bufoff) + ldsw + _i * 8192), 16, 0, 0); } } while (0)
; #define PG8_LDA(dst, b, h) do { _Pragma("unroll") for (int m = 0; m < 4; ++m) _Pragma("unroll") for (int k = 0; k < 2; ++k) dst[m][k] = *(const PG8_LAS bf16x8*)(lds + PG8_SA(b, h) + aoff + m * 2048 + k * 1024); } while (0)
; template <class Epi, class Sched, bool ALIGN_EPI = false, bool SP2 = false>
; __device__ __forceinline__ void gemm_phase(PG8_LAS unsigned char* lds, const Gemm g, const Sched& S, const Epi& E) {
;     ...
;             PG8_LDB(B0, 1, 0); PG8_LDB(B1, 1, 1); PG8_SCHED; PG8_LDA(At, 1, 0); PG8_STAGE(PG8_SA(0, 1), a2 + hstep, voffA);
;             PG8_WAIT_V(8); PG8_WAIT_L(0); PG8_BAR; PG8_MMA2(0); PG8_BAR; PG8_SCHED;
;             PG8_LDA(At, 1, 1); PG8_STAGE(PG8_SB(1, 0), b3, voffB); PG8_STAGE(PG8_SB(1, 1), b3 + hstep, voffB); PG8_STAGE(PG8_SA(1, 0), a3, voffA);
;             PG8_WAIT_V(8); PG8_WAIT_L(0); PG8_BAR; PG8_MMA2(1); PG8_BAR; PG8_SCHED;
;     ...
;         if constexpr (ALIGN_EPI) { if (wr == 0) PG8_BAR; }
	s_add_i32 s59, 0, 0x18000
	s_add_i32 s60, 0, 0x1c000
	v_add_u32_e32 v140, s59, v174
	v_add_u32_e32 v164, s60, v174
	ds_read_b128 v[128:131], v140
	ds_read_b128 v[132:135], v140 offset:1024
	ds_read_b128 v[136:139], v140 offset:2048
	ds_read_b128 v[140:143], v140 offset:3072
	ds_read_b128 v[152:155], v164
	ds_read_b128 v[156:159], v164 offset:1024
	ds_read_b128 v[160:163], v164 offset:2048
	ds_read_b128 v[184:187], v164 offset:3072
	s_add_u32 s6, s36, 0x300000
	s_addc_u32 s7, s37, 0
	s_mov_b32 m0, s43
	ds_read_b128 v[188:191], v177 offset:32768
	ds_read_b128 v[192:195], v177 offset:33792
	ds_read_b128 v[196:199], v177 offset:34816
	ds_read_b128 v[200:203], v177 offset:35840
	ds_read_b128 v[204:207], v177 offset:36864
	ds_read_b128 v[208:211], v177 offset:37888
	ds_read_b128 v[212:215], v177 offset:38912
	ds_read_b128 v[216:219], v177 offset:39936
	s_nop 0
	global_load_lds_dwordx4 v167, s[6:7]
	s_mov_b32 m0, s44
	s_nop 0
	global_load_lds_dwordx4 v171, s[6:7]
	s_nop 0
	s_nop 0
	s_setprio 1
	s_waitcnt vmcnt(8) lgkmcnt(0)
	s_barrier
	v_mfma_f32_16x16x32_bf16 v[124:127], v[128:131], v[188:191], v[124:127]
	v_mfma_f32_16x16x32_bf16 v[120:123], v[136:139], v[188:191], v[120:123]
	v_mfma_f32_16x16x32_bf16 v[108:111], v[128:131], v[196:199], v[108:111]
	v_mfma_f32_16x16x32_bf16 v[104:107], v[136:139], v[196:199], v[104:107]
	v_mfma_f32_16x16x32_bf16 v[92:95], v[128:131], v[204:207], v[92:95]
	v_mfma_f32_16x16x32_bf16 v[88:91], v[136:139], v[204:207], v[88:91]
	v_mfma_f32_16x16x32_bf16 v[76:79], v[128:131], v[212:215], v[76:79]
	v_mfma_f32_16x16x32_bf16 v[72:75], v[136:139], v[212:215], v[72:75]
	v_mfma_f32_16x16x32_bf16 v[116:119], v[152:155], v[188:191], v[116:119]
	v_mfma_f32_16x16x32_bf16 v[112:115], v[160:163], v[188:191], v[112:115]
	v_mfma_f32_16x16x32_bf16 v[100:103], v[152:155], v[196:199], v[100:103]
	v_mfma_f32_16x16x32_bf16 v[96:99], v[160:163], v[196:199], v[96:99]
	v_mfma_f32_16x16x32_bf16 v[84:87], v[152:155], v[204:207], v[84:87]
	v_mfma_f32_16x16x32_bf16 v[80:83], v[160:163], v[204:207], v[80:83]
	v_mfma_f32_16x16x32_bf16 v[68:71], v[152:155], v[212:215], v[68:71]
	v_mfma_f32_16x16x32_bf16 v[64:67], v[160:163], v[212:215], v[64:67]
	v_mfma_f32_16x16x32_bf16 v[124:127], v[132:135], v[192:195], v[124:127]
	v_mfma_f32_16x16x32_bf16 v[120:123], v[140:143], v[192:195], v[120:123]
	v_mfma_f32_16x16x32_bf16 v[108:111], v[132:135], v[200:203], v[108:111]
	v_mfma_f32_16x16x32_bf16 v[104:107], v[140:143], v[200:203], v[104:107]
	v_mfma_f32_16x16x32_bf16 v[92:95], v[132:135], v[208:211], v[92:95]
	v_mfma_f32_16x16x32_bf16 v[88:91], v[140:143], v[208:211], v[88:91]
	v_mfma_f32_16x16x32_bf16 v[76:79], v[132:135], v[216:219], v[76:79]
	v_mfma_f32_16x16x32_bf16 v[72:75], v[140:143], v[216:219], v[72:75]
	v_mfma_f32_16x16x32_bf16 v[116:119], v[156:159], v[192:195], v[116:119]
	v_mfma_f32_16x16x32_bf16 v[112:115], v[184:187], v[192:195], v[112:115]
	v_mfma_f32_16x16x32_bf16 v[100:103], v[156:159], v[200:203], v[100:103]
	v_mfma_f32_16x16x32_bf16 v[96:99], v[184:187], v[200:203], v[96:99]
	v_mfma_f32_16x16x32_bf16 v[84:87], v[156:159], v[208:211], v[84:87]
	v_mfma_f32_16x16x32_bf16 v[80:83], v[184:187], v[208:211], v[80:83]
	v_mfma_f32_16x16x32_bf16 v[68:71], v[156:159], v[216:219], v[68:71]
	v_mfma_f32_16x16x32_bf16 v[64:67], v[184:187], v[216:219], v[64:67]
	s_setprio 0
	s_barrier
	s_add_u32 s6, s34, 0x80
	s_addc_u32 s7, s35, 0
	s_add_i32 s36, s59, s39
	s_mov_b32 m0, s36
	ds_read_b128 v[188:191], v177 offset:49152
	ds_read_b128 v[192:195], v177 offset:50176
	ds_read_b128 v[196:199], v177 offset:51200
	ds_read_b128 v[200:203], v177 offset:52224
	ds_read_b128 v[204:207], v177 offset:53248
	ds_read_b128 v[208:211], v177 offset:54272
	ds_read_b128 v[212:215], v177 offset:55296
	ds_read_b128 v[216:219], v177 offset:56320
	s_nop 0
	global_load_lds_dwordx4 v169, s[6:7]
	s_add_i32 m0, s36, 0x2000
	s_nop 0
	global_load_lds_dwordx4 v172, s[6:7]
	s_add_u32 s6, s34, 0x300080
	s_addc_u32 s7, s35, 0
	s_add_i32 s34, s60, s39
	s_mov_b32 m0, s34
	s_nop 0
	global_load_lds_dwordx4 v169, s[6:7]
	s_add_i32 m0, s34, 0x2000
	s_nop 0
	global_load_lds_dwordx4 v172, s[6:7]
	s_mov_b32 m0, s47
	s_nop 0
	global_load_lds_dwordx4 v167, s[30:31]
	s_mov_b32 m0, s48
	s_nop 0
	global_load_lds_dwordx4 v171, s[30:31]
	s_nop 0
	s_nop 0
	s_setprio 1
	s_waitcnt vmcnt(8) lgkmcnt(0)
	s_barrier
	v_mfma_f32_16x16x32_bf16 v[60:63], v[128:131], v[188:191], v[60:63]
	v_mfma_f32_16x16x32_bf16 v[56:59], v[136:139], v[188:191], v[56:59]
	v_mfma_f32_16x16x32_bf16 v[44:47], v[128:131], v[196:199], v[44:47]
	v_mfma_f32_16x16x32_bf16 v[40:43], v[136:139], v[196:199], v[40:43]
	v_mfma_f32_16x16x32_bf16 v[28:31], v[128:131], v[204:207], v[28:31]
	v_mfma_f32_16x16x32_bf16 v[24:27], v[136:139], v[204:207], v[24:27]
	v_mfma_f32_16x16x32_bf16 v[12:15], v[128:131], v[212:215], v[12:15]
	v_mfma_f32_16x16x32_bf16 v[8:11], v[136:139], v[212:215], v[8:11]
	v_mfma_f32_16x16x32_bf16 v[52:55], v[152:155], v[188:191], v[52:55]
	v_mfma_f32_16x16x32_bf16 v[48:51], v[160:163], v[188:191], v[48:51]
	v_mfma_f32_16x16x32_bf16 v[36:39], v[152:155], v[196:199], v[36:39]
	v_mfma_f32_16x16x32_bf16 v[32:35], v[160:163], v[196:199], v[32:35]
	v_mfma_f32_16x16x32_bf16 v[20:23], v[152:155], v[204:207], v[20:23]
	v_mfma_f32_16x16x32_bf16 v[16:19], v[160:163], v[204:207], v[16:19]
	v_mfma_f32_16x16x32_bf16 v[4:7], v[152:155], v[212:215], v[4:7]
	v_mfma_f32_16x16x32_bf16 v[0:3], v[160:163], v[212:215], v[0:3]
	v_mfma_f32_16x16x32_bf16 v[60:63], v[132:135], v[192:195], v[60:63]
	v_mfma_f32_16x16x32_bf16 v[56:59], v[140:143], v[192:195], v[56:59]
	v_mfma_f32_16x16x32_bf16 v[44:47], v[132:135], v[200:203], v[44:47]
	v_mfma_f32_16x16x32_bf16 v[40:43], v[140:143], v[200:203], v[40:43]
	v_mfma_f32_16x16x32_bf16 v[28:31], v[132:135], v[208:211], v[28:31]
	v_mfma_f32_16x16x32_bf16 v[24:27], v[140:143], v[208:211], v[24:27]
	v_mfma_f32_16x16x32_bf16 v[12:15], v[132:135], v[216:219], v[12:15]
	v_mfma_f32_16x16x32_bf16 v[8:11], v[140:143], v[216:219], v[8:11]
	v_mfma_f32_16x16x32_bf16 v[52:55], v[156:159], v[192:195], v[52:55]
	v_mfma_f32_16x16x32_bf16 v[48:51], v[184:187], v[192:195], v[48:51]
	v_mfma_f32_16x16x32_bf16 v[36:39], v[156:159], v[200:203], v[36:39]
	v_mfma_f32_16x16x32_bf16 v[32:35], v[184:187], v[200:203], v[32:35]
	v_mfma_f32_16x16x32_bf16 v[20:23], v[156:159], v[208:211], v[20:23]
	v_mfma_f32_16x16x32_bf16 v[16:19], v[184:187], v[208:211], v[16:19]
	v_mfma_f32_16x16x32_bf16 v[4:7], v[156:159], v[216:219], v[4:7]
	v_mfma_f32_16x16x32_bf16 v[0:3], v[184:187], v[216:219], v[0:3]
	s_setprio 0
	s_barrier
	s_add_i32 s58, s58, 2
	s_add_u32 s4, s4, 0x100
	s_addc_u32 s5, s5, 0
	s_cmpk_gt_u32 s58, 0xbd
	s_mov_b64 s[6:7], s[28:29]
	s_cbranch_scc0 .LBB0_1217
	s_and_b64 vcc, exec, s[18:19]
	s_cbranch_vccz .LBB0_1220
	s_barrier
